# RES epilogues: loads of rounds 1 and 2 issued with round 0 (38 loads into dead/unused registers), two store-bound waits less per tile
# baseline (speedup 1.0000x reference)
.LBB0_707:
	s_add_i32 s58, s64, 0xffffe000
	s_lshr_b32 s58, s58, 12
	s_mulk_i32 s58, 0x1800
	s_addk_i32 s58, 0x1800
	s_cmp_gt_i32 s6, 63
	s_cselect_b32 s6, s58, 0
	s_lshl_b64 s[58:59], s[6:7], 2
	v_mov_b32_e32 v70, s68
	s_add_u32 s6, s14, s58
	ds_read_b64 v[70:71], v70
	s_addc_u32 s63, s15, s59
	s_lshl_b32 s58, s69, 14
	s_add_i32 s58, s58, 0x20000
	s_ashr_i32 s59, s58, 31
	s_lshl_b64 s[58:59], s[58:59], 2
	s_add_u32 s58, s10, s58
	s_waitcnt lgkmcnt(0)
	v_readfirstlane_b32 s70, v70
	s_addc_u32 s59, s11, s59
	v_add_u32_e32 v70, s64, v141
	s_add_u32 s60, s6, 0x5ba2000
	v_lshlrev_b32_e32 v190, 10, v70
	s_addc_u32 s61, s63, 0
	v_or_b32_e32 v102, s66, v140
	v_or_b32_e32 v188, 0x400, v190
	v_or_b32_e32 v187, 0x4400, v190
	v_or_b32_e32 v191, 0x4c00, v190
	v_or_b32_e32 v195, 0x6c00, v190
	v_readfirstlane_b32 s71, v71
	s_add_u32 s62, s6, 0x5ba4000
	v_ashrrev_i32_e32 v103, 31, v102
	v_add_u32_e32 v134, v190, v102
	v_add_u32_e32 v136, v188, v102
	v_or_b32_e32 v186, 0x800, v190
	v_or_b32_e32 v185, 0xc00, v190
	v_or_b32_e32 v183, 0x2000, v190
	v_or_b32_e32 v181, 0x2400, v190
	v_or_b32_e32 v71, 0x2800, v190
	v_or_b32_e32 v182, 0x2c00, v190
	v_or_b32_e32 v184, 0x4000, v190
	v_add_u32_e32 v114, v187, v102
	v_or_b32_e32 v189, 0x4800, v190
	v_add_u32_e32 v120, v191, v102
	v_or_b32_e32 v192, 0x6000, v190
	v_or_b32_e32 v193, 0x6400, v190
	v_or_b32_e32 v194, 0x6800, v190
	v_add_u32_e32 v130, v195, v102
	s_addc_u32 s63, s63, 0
	v_lshlrev_b64 v[72:73], 2, v[102:103]
	v_ashrrev_i32_e32 v137, 31, v136
	v_add_u32_e32 v138, v186, v102
	v_add_u32_e32 v132, v185, v102
	v_add_u32_e32 v124, v183, v102
	v_add_u32_e32 v116, v181, v102
	v_add_u32_e32 v108, v71, v102
	v_add_u32_e32 v110, v182, v102
	v_add_u32_e32 v112, v184, v102
	v_ashrrev_i32_e32 v115, 31, v114
	v_add_u32_e32 v118, v189, v102
	v_ashrrev_i32_e32 v121, 31, v120
	v_add_u32_e32 v122, v192, v102
	v_add_u32_e32 v126, v193, v102
	v_add_u32_e32 v128, v194, v102
	v_ashrrev_i32_e32 v131, 31, v130
	v_ashrrev_i32_e32 v135, 31, v134
	v_lshl_add_u64 v[74:75], s[60:61], 0, v[72:73]
	v_lshl_add_u64 v[104:105], s[70:71], 0, v[72:73]
	v_lshl_add_u64 v[72:73], s[62:63], 0, v[72:73]
	v_lshl_add_u64 v[88:89], v[136:137], 2, s[12:13]
	v_ashrrev_i32_e32 v139, 31, v138
	v_ashrrev_i32_e32 v133, 31, v132
	v_ashrrev_i32_e32 v125, 31, v124
	v_ashrrev_i32_e32 v117, 31, v116
	v_ashrrev_i32_e32 v109, 31, v108
	v_ashrrev_i32_e32 v111, 31, v110
	v_ashrrev_i32_e32 v113, 31, v112
	v_lshl_add_u64 v[86:87], v[114:115], 2, s[12:13]
	v_ashrrev_i32_e32 v119, 31, v118
	v_lshl_add_u64 v[92:93], v[120:121], 2, s[12:13]
	v_ashrrev_i32_e32 v123, 31, v122
	v_ashrrev_i32_e32 v127, 31, v126
	v_ashrrev_i32_e32 v129, 31, v128
	v_lshl_add_u64 v[100:101], v[130:131], 2, s[12:13]
	v_lshl_add_u64 v[106:107], v[134:135], 2, s[12:13]
	global_load_dword v196, v[74:75], off
	global_load_dword v206, v[74:75], off offset:128
	global_load_dword v225, v[74:75], off offset:256
	global_load_dword v198, v[72:73], off
	global_load_dword v207, v[72:73], off offset:128
	global_load_dword v226, v[72:73], off offset:256
	global_load_dword v197, v[104:105], off
	v_lshl_add_u64 v[84:85], v[138:139], 2, s[12:13]
	v_lshl_add_u64 v[82:83], v[132:133], 2, s[12:13]
	v_lshl_add_u64 v[78:79], v[124:125], 2, s[12:13]
	v_lshl_add_u64 v[72:73], v[116:117], 2, s[12:13]
	v_lshl_add_u64 v[74:75], v[108:109], 2, s[12:13]
	v_lshl_add_u64 v[76:77], v[110:111], 2, s[12:13]
	v_lshl_add_u64 v[80:81], v[112:113], 2, s[12:13]
	global_load_dword v180, v[88:89], off
	global_load_dword v179, v[84:85], off
	global_load_dword v178, v[82:83], off
	global_load_dword v177, v[78:79], off
	global_load_dword v176, v[72:73], off
	global_load_dword v175, v[74:75], off
	global_load_dword v174, v[76:77], off
	global_load_dword v173, v[80:81], off
	v_lshl_add_u64 v[90:91], v[118:119], 2, s[12:13]
	global_load_dword v172, v[86:87], off
	global_load_dword v170, v[90:91], off
	v_lshl_add_u64 v[94:95], v[122:123], 2, s[12:13]
	v_lshl_add_u64 v[96:97], v[126:127], 2, s[12:13]
	v_lshl_add_u64 v[98:99], v[128:129], 2, s[12:13]
	global_load_dword v171, v[92:93], off
	global_load_dword v169, v[94:95], off
	global_load_dword v168, v[96:97], off
	global_load_dword v167, v[98:99], off
	global_load_dword v103, v[100:101], off
	global_load_dword v202, v[106:107], off
	v_lshl_add_u64 v[108:109], v[108:109], 1, s[8:9]
	global_load_dword v205, v[106:107], off offset:128
	global_load_dword v208, v[104:105], off offset:128
	global_load_dword v209, v[84:85], off offset:128
	global_load_dword v210, v[78:79], off offset:128
	global_load_dword v211, v[72:73], off offset:128
	global_load_dword v212, v[74:75], off offset:128
	global_load_dword v213, v[80:81], off offset:128
	global_load_dword v214, v[76:77], off offset:128
	global_load_dword v215, v[86:87], off offset:128
	global_load_dword v216, v[82:83], off offset:128
	global_load_dword v217, v[90:91], off offset:128
	global_load_dword v218, v[92:93], off offset:128
	global_load_dword v219, v[94:95], off offset:128
	global_load_dword v220, v[96:97], off offset:128
	global_load_dword v221, v[98:99], off offset:128
	global_load_dword v222, v[100:101], off offset:128
	global_load_dword v223, v[88:89], off offset:128
	global_load_dword v224, v[88:89], off offset:256
	global_load_dword v227, v[104:105], off offset:256
	global_load_dword v229, v[106:107], off offset:256
	global_load_dword v230, v[84:85], off offset:256
	global_load_dword v231, v[78:79], off offset:256
	global_load_dword v232, v[86:87], off offset:256
	global_load_dword v233, v[82:83], off offset:256
	global_load_dword v234, v[72:73], off offset:256
	global_load_dword v235, v[74:75], off offset:256
	global_load_dword v236, v[80:81], off offset:256
	global_load_dword v237, v[76:77], off offset:256
	global_load_dword v238, v[90:91], off offset:256
	global_load_dword v239, v[92:93], off offset:256
	global_load_dword v240, v[94:95], off offset:256
	global_load_dword v241, v[96:97], off offset:256
	global_load_dword v242, v[98:99], off offset:256
	global_load_dword v243, v[100:101], off offset:256
	s_waitcnt vmcnt(0)
	v_add_f32_e32 v198, 1.0, v198
	v_mul_f32_e32 v197, v197, v198
	v_fmac_f32_e32 v180, v49, v196
	v_fmac_f32_e32 v179, v50, v196
	v_fmac_f32_e32 v178, v51, v196
	v_fmac_f32_e32 v177, v52, v196
	v_fmac_f32_e32 v176, v53, v196
	v_fmac_f32_e32 v175, v54, v196
	v_fmac_f32_e32 v174, v55, v196
	v_fmac_f32_e32 v173, v56, v196
	v_fmac_f32_e32 v172, v57, v196
	v_fmac_f32_e32 v170, v58, v196
	v_fmac_f32_e32 v171, v59, v196
	v_fmac_f32_e32 v169, v60, v196
	v_fmac_f32_e32 v168, v61, v196
	v_fmac_f32_e32 v167, v62, v196
	v_fmac_f32_e32 v103, v63, v196
	v_fmac_f32_e32 v202, v48, v196
	v_or_b32_e32 v48, 32, v102
	v_ashrrev_i32_e32 v49, 31, v48
	v_lshlrev_b64 v[50:51], 2, v[48:49]
	global_store_dword v[88:89], v180, off sc1
	global_store_dword v[84:85], v179, off sc1
	global_store_dword v[82:83], v178, off sc1
	global_store_dword v[78:79], v177, off sc1
	global_store_dword v[72:73], v176, off sc1
	global_store_dword v[74:75], v175, off sc1
	global_store_dword v[76:77], v174, off sc1
	global_store_dword v[80:81], v173, off sc1
	global_store_dword v[86:87], v172, off sc1
	global_store_dword v[90:91], v170, off sc1
	global_store_dword v[92:93], v171, off sc1
	global_store_dword v[94:95], v169, off sc1
	global_store_dword v[96:97], v168, off sc1
	global_store_dword v[98:99], v167, off sc1
	global_store_dword v[100:101], v103, off sc1
	global_store_dword v[106:107], v202, off sc1
	v_mul_f32_e32 v54, v197, v202
	v_lshl_add_u64 v[52:53], s[60:61], 0, v[50:51]
	v_lshl_add_u64 v[50:51], s[62:63], 0, v[50:51]
	v_mov_b32_e32 v198, v205
	v_mov_b32_e32 v196, v206
	v_mov_b32_e32 v203, v207
	v_mov_b32_e32 v204, v208
	v_cvt_pk_bf16_f32 v49, v54, s0
	v_lshl_add_u64 v[50:51], v[134:135], 1, s[8:9]
	global_store_short v[50:51], v49, off sc1
	v_mul_f32_e32 v49, v197, v180
	v_cvt_pk_bf16_f32 v49, v49, s0
	v_lshl_add_u64 v[50:51], v[136:137], 1, s[8:9]
	global_store_short v[50:51], v49, off sc1
	v_mul_f32_e32 v49, v197, v179
	v_cvt_pk_bf16_f32 v49, v49, s0
	v_lshl_add_u64 v[50:51], v[138:139], 1, s[8:9]
	global_store_short v[50:51], v49, off sc1
	v_mul_f32_e32 v49, v197, v178
	v_cvt_pk_bf16_f32 v49, v49, s0
	v_lshl_add_u64 v[50:51], v[132:133], 1, s[8:9]
	global_store_short v[50:51], v49, off sc1
	v_mul_f32_e32 v49, v197, v177
	v_cvt_pk_bf16_f32 v49, v49, s0
	v_lshl_add_u64 v[50:51], v[124:125], 1, s[8:9]
	global_store_short v[50:51], v49, off sc1
	v_mul_f32_e32 v49, v197, v176
	v_cvt_pk_bf16_f32 v49, v49, s0
	v_lshl_add_u64 v[50:51], v[116:117], 1, s[8:9]
	global_store_short v[50:51], v49, off sc1
	v_mul_f32_e32 v49, v197, v175
	v_mov_b32_e32 v62, v209
	v_mov_b32_e32 v60, v210
	v_mov_b32_e32 v59, v211
	v_mov_b32_e32 v58, v212
	v_mov_b32_e32 v56, v213
	v_mov_b32_e32 v57, v214
	v_mov_b32_e32 v55, v215
	v_mov_b32_e32 v61, v216
	v_mov_b32_e32 v54, v217
	v_mov_b32_e32 v53, v218
	v_mov_b32_e32 v52, v219
	v_mov_b32_e32 v51, v220
	v_mov_b32_e32 v50, v221
	v_cvt_pk_bf16_f32 v63, v49, s0
	v_mov_b32_e32 v49, v222
	v_fmac_f32_e32 v198, v32, v196
	global_store_short v[108:109], v63, off sc1
	v_mov_b32_e32 v63, v223
	v_mul_f32_e32 v108, v197, v174
	v_cvt_pk_bf16_f32 v116, v108, s0
	v_lshl_add_u64 v[108:109], v[110:111], 1, s[8:9]
	global_store_short v[108:109], v116, off sc1
	v_mul_f32_e32 v108, v197, v173
	v_cvt_pk_bf16_f32 v110, v108, s0
	v_lshl_add_u64 v[108:109], v[112:113], 1, s[8:9]
	global_store_short v[108:109], v110, off sc1
	v_mul_f32_e32 v108, v197, v172
	v_cvt_pk_bf16_f32 v110, v108, s0
	v_lshl_add_u64 v[108:109], v[114:115], 1, s[8:9]
	global_store_short v[108:109], v110, off sc1
	v_mul_f32_e32 v108, v197, v170
	v_cvt_pk_bf16_f32 v110, v108, s0
	v_lshl_add_u64 v[108:109], v[118:119], 1, s[8:9]
	global_store_short v[108:109], v110, off sc1
	v_mul_f32_e32 v108, v197, v171
	v_cvt_pk_bf16_f32 v110, v108, s0
	v_lshl_add_u64 v[108:109], v[120:121], 1, s[8:9]
	global_store_short v[108:109], v110, off sc1
	v_mul_f32_e32 v108, v197, v169
	v_cvt_pk_bf16_f32 v110, v108, s0
	v_lshl_add_u64 v[108:109], v[122:123], 1, s[8:9]
	global_store_short v[108:109], v110, off sc1
	v_mul_f32_e32 v108, v197, v168
	v_cvt_pk_bf16_f32 v110, v108, s0
	v_lshl_add_u64 v[108:109], v[126:127], 1, s[8:9]
	global_store_short v[108:109], v110, off sc1
	v_mul_f32_e32 v108, v197, v167
	v_cvt_pk_bf16_f32 v110, v108, s0
	v_lshl_add_u64 v[108:109], v[128:129], 1, s[8:9]
	global_store_short v[108:109], v110, off sc1
	v_mul_f32_e32 v108, v197, v103
	v_cvt_pk_bf16_f32 v110, v108, s0
	v_lshl_add_u64 v[108:109], v[130:131], 1, s[8:9]
	global_store_short v[108:109], v110, off sc1
	v_add_f32_e32 v108, 1.0, v203
	v_mul_f32_e32 v112, v204, v108
	v_add_u32_e32 v108, v190, v48
	v_fmac_f32_e32 v62, v34, v196
	v_fmac_f32_e32 v61, v35, v196
	v_fmac_f32_e32 v60, v36, v196
	v_fmac_f32_e32 v59, v37, v196
	v_fmac_f32_e32 v58, v38, v196
	v_fmac_f32_e32 v57, v39, v196
	v_fmac_f32_e32 v56, v40, v196
	v_fmac_f32_e32 v55, v41, v196
	v_fmac_f32_e32 v54, v42, v196
	v_fmac_f32_e32 v53, v43, v196
	v_fmac_f32_e32 v52, v44, v196
	v_fmac_f32_e32 v51, v45, v196
	v_fmac_f32_e32 v50, v46, v196
	v_fmac_f32_e32 v49, v47, v196
	v_ashrrev_i32_e32 v109, 31, v108
	global_store_dword v[106:107], v198, off offset:128 sc1
	v_mul_f32_e32 v32, v112, v198
	global_store_dword v[84:85], v62, off offset:128 sc1
	global_store_dword v[82:83], v61, off offset:128 sc1
	global_store_dword v[78:79], v60, off offset:128 sc1
	global_store_dword v[72:73], v59, off offset:128 sc1
	global_store_dword v[74:75], v58, off offset:128 sc1
	global_store_dword v[76:77], v57, off offset:128 sc1
	global_store_dword v[80:81], v56, off offset:128 sc1
	global_store_dword v[86:87], v55, off offset:128 sc1
	global_store_dword v[90:91], v54, off offset:128 sc1
	global_store_dword v[92:93], v53, off offset:128 sc1
	global_store_dword v[94:95], v52, off offset:128 sc1
	global_store_dword v[96:97], v51, off offset:128 sc1
	global_store_dword v[98:99], v50, off offset:128 sc1
	global_store_dword v[100:101], v49, off offset:128 sc1
	v_cvt_pk_bf16_f32 v32, v32, s0
	v_lshl_add_u64 v[108:109], v[108:109], 1, s[8:9]
	v_add_u32_e32 v110, v188, v48
	v_mov_b32_e32 v45, v224
	v_ashrrev_i32_e32 v111, 31, v110
	global_store_short v[108:109], v32, off sc1
	v_mul_f32_e32 v40, v112, v59
	v_mul_f32_e32 v115, v112, v56
	v_cvt_pk_bf16_f32 v115, v115, s0
	v_fmac_f32_e32 v63, v33, v196
	v_mul_f32_e32 v32, v112, v63
	v_cvt_pk_bf16_f32 v34, v32, s0
	v_lshl_add_u64 v[32:33], v[110:111], 1, s[8:9]
	global_store_short v[32:33], v34, off sc1
	v_add_u32_e32 v32, v186, v48
	v_ashrrev_i32_e32 v33, 31, v32
	v_mul_f32_e32 v34, v112, v62
	v_cvt_pk_bf16_f32 v34, v34, s0
	v_lshl_add_u64 v[32:33], v[32:33], 1, s[8:9]
	global_store_short v[32:33], v34, off sc1
	v_add_u32_e32 v32, v185, v48
	v_ashrrev_i32_e32 v33, 31, v32
	v_mul_f32_e32 v34, v112, v61
	v_cvt_pk_bf16_f32 v34, v34, s0
	v_lshl_add_u64 v[32:33], v[32:33], 1, s[8:9]
	global_store_short v[32:33], v34, off sc1
	v_add_u32_e32 v32, v183, v48
	v_ashrrev_i32_e32 v33, 31, v32
	v_mul_f32_e32 v34, v112, v60
	v_cvt_pk_bf16_f32 v34, v34, s0
	v_lshl_add_u64 v[32:33], v[32:33], 1, s[8:9]
	global_store_short v[32:33], v34, off sc1
	v_or_b32_e32 v32, 64, v102
	v_add_u32_e32 v34, v181, v48
	v_ashrrev_i32_e32 v33, 31, v32
	v_ashrrev_i32_e32 v35, 31, v34
	v_lshlrev_b64 v[36:37], 2, v[32:33]
	global_store_dword v[88:89], v63, off offset:128 sc1
	v_lshl_add_u64 v[38:39], s[60:61], 0, v[36:37]
	v_cvt_pk_bf16_f32 v33, v40, s0
	v_lshl_add_u64 v[34:35], v[34:35], 1, s[8:9]
	v_lshl_add_u64 v[36:37], s[62:63], 0, v[36:37]
	v_mov_b32_e32 v109, v225
	v_mov_b32_e32 v113, v226
	v_mov_b32_e32 v114, v227
	v_mov_b32_e32 v116, v229
	v_mov_b32_e32 v47, v230
	v_mov_b32_e32 v44, v231
	v_mov_b32_e32 v39, v232
	v_mov_b32_e32 v46, v233
	v_mov_b32_e32 v43, v234
	v_mov_b32_e32 v42, v235
	v_mov_b32_e32 v40, v236
	v_mov_b32_e32 v41, v237
	v_mov_b32_e32 v38, v238
	v_mov_b32_e32 v37, v239
	v_mov_b32_e32 v36, v240
	v_add_u32_e32 v110, v184, v48
	global_store_short v[34:35], v33, off sc1
	v_add_u32_e32 v34, v71, v48
	v_ashrrev_i32_e32 v35, 31, v34
	v_mul_f32_e32 v33, v112, v58
	v_cvt_pk_bf16_f32 v33, v33, s0
	v_lshl_add_u64 v[34:35], v[34:35], 1, s[8:9]
	global_store_short v[34:35], v33, off sc1
	v_add_u32_e32 v34, v182, v48
	v_ashrrev_i32_e32 v35, 31, v34
	v_mul_f32_e32 v33, v112, v57
	v_cvt_pk_bf16_f32 v33, v33, s0
	v_lshl_add_u64 v[34:35], v[34:35], 1, s[8:9]
	global_store_short v[34:35], v33, off sc1
	v_mov_b32_e32 v35, v241
	v_ashrrev_i32_e32 v111, 31, v110
	v_mov_b32_e32 v34, v242
	v_mov_b32_e32 v33, v243
	v_lshl_add_u64 v[110:111], v[110:111], 1, s[8:9]
	global_store_short v[110:111], v115, off sc1
	v_add_u32_e32 v110, v187, v48
	v_ashrrev_i32_e32 v111, 31, v110
	v_mul_f32_e32 v115, v112, v55
	v_cvt_pk_bf16_f32 v115, v115, s0
	v_lshl_add_u64 v[110:111], v[110:111], 1, s[8:9]
	global_store_short v[110:111], v115, off sc1
	v_add_u32_e32 v110, v189, v48
	v_ashrrev_i32_e32 v111, 31, v110
	v_mul_f32_e32 v115, v112, v54
	v_cvt_pk_bf16_f32 v115, v115, s0
	v_lshl_add_u64 v[110:111], v[110:111], 1, s[8:9]
	global_store_short v[110:111], v115, off sc1
	v_add_u32_e32 v110, v191, v48
	v_ashrrev_i32_e32 v111, 31, v110
	v_mul_f32_e32 v115, v112, v53
	v_cvt_pk_bf16_f32 v115, v115, s0
	v_lshl_add_u64 v[110:111], v[110:111], 1, s[8:9]
	global_store_short v[110:111], v115, off sc1
	v_add_u32_e32 v110, v192, v48
	v_ashrrev_i32_e32 v111, 31, v110
	v_mul_f32_e32 v115, v112, v52
	v_cvt_pk_bf16_f32 v115, v115, s0
	v_lshl_add_u64 v[110:111], v[110:111], 1, s[8:9]
	global_store_short v[110:111], v115, off sc1
	v_add_u32_e32 v110, v193, v48
	v_ashrrev_i32_e32 v111, 31, v110
	v_mul_f32_e32 v115, v112, v51
	v_cvt_pk_bf16_f32 v115, v115, s0
	v_lshl_add_u64 v[110:111], v[110:111], 1, s[8:9]
	global_store_short v[110:111], v115, off sc1
	v_add_u32_e32 v110, v194, v48
	v_ashrrev_i32_e32 v111, 31, v110
	v_mul_f32_e32 v115, v112, v50
	v_cvt_pk_bf16_f32 v115, v115, s0
	v_lshl_add_u64 v[110:111], v[110:111], 1, s[8:9]
	global_store_short v[110:111], v115, off sc1
	v_add_u32_e32 v110, v195, v48
	v_ashrrev_i32_e32 v111, 31, v110
	v_mul_f32_e32 v48, v112, v49
	v_cvt_pk_bf16_f32 v48, v48, s0
	v_lshl_add_u64 v[110:111], v[110:111], 1, s[8:9]
	global_store_short v[110:111], v48, off sc1
	v_add_u32_e32 v110, v190, v32
	v_ashrrev_i32_e32 v111, 31, v110
	v_mul_f32_e32 v108, v198, v198
	v_fmac_f32_e32 v45, v17, v109
	v_add_f32_e32 v48, 1.0, v113
	v_mul_f32_e32 v48, v114, v48
	v_fmac_f32_e32 v116, v16, v109
	v_mul_f32_e32 v16, v48, v116
	v_fmac_f32_e32 v47, v18, v109
	v_cvt_pk_bf16_f32 v18, v16, s0
	v_lshl_add_u64 v[16:17], v[110:111], 1, s[8:9]
	global_store_short v[16:17], v18, off sc1
	v_add_u32_e32 v16, v188, v32
	v_ashrrev_i32_e32 v17, 31, v16
	v_mul_f32_e32 v18, v48, v45
	v_cvt_pk_bf16_f32 v18, v18, s0
	v_lshl_add_u64 v[16:17], v[16:17], 1, s[8:9]
	global_store_short v[16:17], v18, off sc1
	v_add_u32_e32 v16, v186, v32
	v_ashrrev_i32_e32 v17, 31, v16
	v_mul_f32_e32 v18, v48, v47
	v_cvt_pk_bf16_f32 v18, v18, s0
	v_lshl_add_u64 v[16:17], v[16:17], 1, s[8:9]
	v_fmac_f32_e32 v46, v19, v109
	global_store_short v[16:17], v18, off sc1
	v_add_u32_e32 v16, v185, v32
	v_ashrrev_i32_e32 v17, 31, v16
	v_mul_f32_e32 v18, v48, v46
	v_cvt_pk_bf16_f32 v18, v18, s0
	v_lshl_add_u64 v[16:17], v[16:17], 1, s[8:9]
	global_store_short v[16:17], v18, off sc1
	v_or_b32_e32 v16, 0x60, v102
	v_ashrrev_i32_e32 v17, 31, v16
	v_fmac_f32_e32 v44, v20, v109
	v_fmac_f32_e32 v43, v21, v109
	v_fmac_f32_e32 v42, v22, v109
	v_fmac_f32_e32 v41, v23, v109
	v_fmac_f32_e32 v40, v24, v109
	v_fmac_f32_e32 v39, v25, v109
	v_fmac_f32_e32 v38, v26, v109
	v_fmac_f32_e32 v37, v27, v109
	v_fmac_f32_e32 v36, v28, v109
	v_fmac_f32_e32 v35, v29, v109
	v_fmac_f32_e32 v34, v30, v109
	v_fmac_f32_e32 v33, v31, v109
	v_lshlrev_b64 v[20:21], 2, v[16:17]
	global_store_dword v[88:89], v45, off offset:256 sc1
	global_store_dword v[84:85], v47, off offset:256 sc1
	global_store_dword v[82:83], v46, off offset:256 sc1
	global_store_dword v[78:79], v44, off offset:256 sc1
	global_store_dword v[72:73], v43, off offset:256 sc1
	global_store_dword v[74:75], v42, off offset:256 sc1
	global_store_dword v[76:77], v41, off offset:256 sc1
	global_store_dword v[80:81], v40, off offset:256 sc1
	global_store_dword v[86:87], v39, off offset:256 sc1
	global_store_dword v[90:91], v38, off offset:256 sc1
	global_store_dword v[92:93], v37, off offset:256 sc1
	global_store_dword v[94:95], v36, off offset:256 sc1
	global_store_dword v[96:97], v35, off offset:256 sc1
	global_store_dword v[98:99], v34, off offset:256 sc1
	global_store_dword v[100:101], v33, off offset:256 sc1
	global_store_dword v[106:107], v116, off offset:256 sc1
	v_lshl_add_u64 v[22:23], s[60:61], 0, v[20:21]
	v_lshl_add_u64 v[20:21], s[62:63], 0, v[20:21]
	global_load_dword v29, v[106:107], off offset:384
	global_load_dword v102, v[22:23], off
	global_load_dword v17, v[20:21], off
	s_nop 0
	global_load_dword v20, v[104:105], off offset:384
	v_add_u32_e32 v18, v183, v32
	v_ashrrev_i32_e32 v19, 31, v18
	v_mul_f32_e32 v21, v48, v44
	v_cvt_pk_bf16_f32 v21, v21, s0
	v_lshl_add_u64 v[18:19], v[18:19], 1, s[8:9]
	global_store_short v[18:19], v21, off sc1
	v_add_u32_e32 v18, v181, v32
	v_ashrrev_i32_e32 v19, 31, v18
	v_mul_f32_e32 v21, v48, v43
	v_cvt_pk_bf16_f32 v21, v21, s0
	v_lshl_add_u64 v[18:19], v[18:19], 1, s[8:9]
	global_store_short v[18:19], v21, off sc1
	v_add_u32_e32 v18, v71, v32
	v_ashrrev_i32_e32 v19, 31, v18
	v_mul_f32_e32 v21, v48, v42
	v_cvt_pk_bf16_f32 v21, v21, s0
	v_lshl_add_u64 v[18:19], v[18:19], 1, s[8:9]
	global_store_short v[18:19], v21, off sc1
	v_add_u32_e32 v18, v182, v32
	v_ashrrev_i32_e32 v19, 31, v18
	v_mul_f32_e32 v21, v48, v41
	v_cvt_pk_bf16_f32 v21, v21, s0
	v_lshl_add_u64 v[18:19], v[18:19], 1, s[8:9]
	global_store_short v[18:19], v21, off sc1
	v_add_u32_e32 v18, v184, v32
	v_ashrrev_i32_e32 v19, 31, v18
	v_mul_f32_e32 v21, v48, v40
	v_cvt_pk_bf16_f32 v21, v21, s0
	v_lshl_add_u64 v[18:19], v[18:19], 1, s[8:9]
	global_store_short v[18:19], v21, off sc1
	v_add_u32_e32 v18, v187, v32
	v_ashrrev_i32_e32 v19, 31, v18
	v_mul_f32_e32 v21, v48, v39
	v_cvt_pk_bf16_f32 v21, v21, s0
	v_lshl_add_u64 v[18:19], v[18:19], 1, s[8:9]
	global_store_short v[18:19], v21, off sc1
	v_add_u32_e32 v18, v189, v32
	v_ashrrev_i32_e32 v19, 31, v18
	v_mul_f32_e32 v21, v48, v38
	v_cvt_pk_bf16_f32 v21, v21, s0
	v_lshl_add_u64 v[18:19], v[18:19], 1, s[8:9]
	global_store_short v[18:19], v21, off sc1
	v_add_u32_e32 v18, v191, v32
	v_ashrrev_i32_e32 v19, 31, v18
	v_mul_f32_e32 v21, v48, v37
	v_cvt_pk_bf16_f32 v21, v21, s0
	v_lshl_add_u64 v[18:19], v[18:19], 1, s[8:9]
	global_store_short v[18:19], v21, off sc1
	v_add_u32_e32 v18, v192, v32
	v_ashrrev_i32_e32 v19, 31, v18
	v_mul_f32_e32 v21, v48, v36
	v_cvt_pk_bf16_f32 v21, v21, s0
	v_lshl_add_u64 v[18:19], v[18:19], 1, s[8:9]
	global_load_dword v28, v[88:89], off offset:384
	global_load_dword v27, v[84:85], off offset:384
	global_load_dword v25, v[78:79], off offset:384
	global_load_dword v24, v[72:73], off offset:384
	global_load_dword v23, v[74:75], off offset:384
	v_mul_f32_e32 v30, v48, v33
	global_store_short v[18:19], v21, off sc1
	v_add_u32_e32 v18, v193, v32
	v_ashrrev_i32_e32 v19, 31, v18
	v_mul_f32_e32 v21, v48, v35
	v_cvt_pk_bf16_f32 v21, v21, s0
	v_lshl_add_u64 v[18:19], v[18:19], 1, s[8:9]
	global_store_short v[18:19], v21, off sc1
	v_add_u32_e32 v18, v194, v32
	v_ashrrev_i32_e32 v19, 31, v18
	v_mul_f32_e32 v21, v48, v34
	v_cvt_pk_bf16_f32 v21, v21, s0
	v_lshl_add_u64 v[18:19], v[18:19], 1, s[8:9]
	global_store_short v[18:19], v21, off sc1
	v_add_u32_e32 v18, v195, v32
	global_load_dword v21, v[80:81], off offset:384
	global_load_dword v22, v[76:77], off offset:384
	v_ashrrev_i32_e32 v19, 31, v18
	v_cvt_pk_bf16_f32 v30, v30, s0
	v_lshl_add_u64 v[18:19], v[18:19], 1, s[8:9]
	s_waitcnt vmcnt(19)
	v_add_f32_e32 v17, 1.0, v17
	s_waitcnt vmcnt(18)
	v_mul_f32_e32 v32, v20, v17
	global_load_dword v20, v[86:87], off offset:384
	global_load_dword v26, v[82:83], off offset:384
	v_fmac_f32_e32 v29, v0, v102
	global_store_short v[18:19], v30, off sc1
	v_add_u32_e32 v18, v190, v16
	v_ashrrev_i32_e32 v19, 31, v18
	v_mul_f32_e32 v0, v32, v29
	v_cvt_pk_bf16_f32 v0, v0, s0
	v_lshl_add_u64 v[18:19], v[18:19], 1, s[8:9]
	global_store_short v[18:19], v0, off sc1
	global_load_dword v19, v[90:91], off offset:384
	v_add_u32_e32 v30, v188, v16
	global_load_dword v18, v[92:93], off offset:384
	v_ashrrev_i32_e32 v31, 31, v30
	v_fmac_f32_e32 v108, v202, v202
	v_fmac_f32_e32 v108, v116, v116
	v_fmac_f32_e32 v108, v29, v29
	global_store_dword v[106:107], v29, off offset:384 sc1
	s_waitcnt vmcnt(16)
	v_fmac_f32_e32 v28, v1, v102
	v_mul_f32_e32 v0, v32, v28
	v_cvt_pk_bf16_f32 v17, v0, s0
	v_lshl_add_u64 v[0:1], v[30:31], 1, s[8:9]
	global_store_short v[0:1], v17, off sc1
	v_add_u32_e32 v0, v186, v16
	s_waitcnt vmcnt(16)
	v_fmac_f32_e32 v27, v2, v102
	global_load_dword v17, v[94:95], off offset:384
	v_ashrrev_i32_e32 v1, 31, v0
	v_mul_f32_e32 v2, v32, v27
	v_cvt_pk_bf16_f32 v2, v2, s0
	v_lshl_add_u64 v[0:1], v[0:1], 1, s[8:9]
	global_store_short v[0:1], v2, off sc1
	v_add_u32_e32 v0, v185, v16
	global_load_dword v2, v[96:97], off offset:384
	v_ashrrev_i32_e32 v1, 31, v0
	v_lshl_add_u64 v[0:1], v[0:1], 1, s[8:9]
	v_add_u32_e32 v30, v183, v16
	s_waitcnt vmcnt(18)
	v_fmac_f32_e32 v25, v4, v102
	v_ashrrev_i32_e32 v31, 31, v30
	v_lshl_add_u64 v[30:31], v[30:31], 1, s[8:9]
	s_waitcnt vmcnt(17)
	v_fmac_f32_e32 v24, v5, v102
	s_waitcnt vmcnt(16)
	v_fmac_f32_e32 v23, v6, v102
	s_waitcnt vmcnt(11)
	v_fmac_f32_e32 v22, v7, v102
	v_fmac_f32_e32 v21, v8, v102
	global_store_dword v[88:89], v28, off offset:384 sc1
	global_store_dword v[84:85], v27, off offset:384 sc1
	s_waitcnt vmcnt(12)
	v_fmac_f32_e32 v20, v9, v102
	s_waitcnt vmcnt(11)
	v_fmac_f32_e32 v26, v3, v102
	v_mul_f32_e32 v3, v32, v26
	v_cvt_pk_bf16_f32 v3, v3, s0
	global_store_short v[0:1], v3, off sc1
	global_load_dword v1, v[98:99], off offset:384
	v_mul_f32_e32 v0, v32, v25
	v_cvt_pk_bf16_f32 v0, v0, s0
	global_store_short v[30:31], v0, off sc1
	global_load_dword v0, v[100:101], off offset:384
	v_add_u32_e32 v30, v181, v16
	v_ashrrev_i32_e32 v31, 31, v30
	v_mul_f32_e32 v3, v32, v24
	v_cvt_pk_bf16_f32 v3, v3, s0
	v_lshl_add_u64 v[4:5], v[30:31], 1, s[8:9]
	global_store_short v[4:5], v3, off sc1
	v_add_u32_e32 v4, v71, v16
	v_ashrrev_i32_e32 v5, 31, v4
	v_mul_f32_e32 v3, v32, v23
	v_cvt_pk_bf16_f32 v3, v3, s0
	v_lshl_add_u64 v[4:5], v[4:5], 1, s[8:9]
	global_store_short v[4:5], v3, off sc1
	v_add_u32_e32 v4, v182, v16
	v_ashrrev_i32_e32 v5, 31, v4
	v_mul_f32_e32 v3, v32, v22
	v_cvt_pk_bf16_f32 v3, v3, s0
	v_lshl_add_u64 v[4:5], v[4:5], 1, s[8:9]
	global_store_short v[4:5], v3, off sc1
	v_add_u32_e32 v4, v184, v16
	v_ashrrev_i32_e32 v5, 31, v4
	v_mul_f32_e32 v3, v32, v21
	v_cvt_pk_bf16_f32 v3, v3, s0
	v_lshl_add_u64 v[4:5], v[4:5], 1, s[8:9]
	global_store_short v[4:5], v3, off sc1
	v_add_u32_e32 v4, v187, v16
	v_ashrrev_i32_e32 v5, 31, v4
	v_mul_f32_e32 v3, v32, v20
	v_cvt_pk_bf16_f32 v3, v3, s0
	v_lshl_add_u64 v[4:5], v[4:5], 1, s[8:9]
	global_store_short v[4:5], v3, off sc1
	v_add_u32_e32 v4, v189, v16
	s_waitcnt vmcnt(17)
	v_fmac_f32_e32 v19, v10, v102
	v_ashrrev_i32_e32 v5, 31, v4
	v_mul_f32_e32 v3, v32, v19
	v_cvt_pk_bf16_f32 v3, v3, s0
	v_lshl_add_u64 v[4:5], v[4:5], 1, s[8:9]
	global_store_short v[4:5], v3, off sc1
	v_add_u32_e32 v4, v191, v16
	s_waitcnt vmcnt(17)
	v_fmac_f32_e32 v18, v11, v102
	v_ashrrev_i32_e32 v5, 31, v4
	v_mul_f32_e32 v3, v32, v18
	v_cvt_pk_bf16_f32 v3, v3, s0
	v_lshl_add_u64 v[4:5], v[4:5], 1, s[8:9]
	global_store_short v[4:5], v3, off sc1
	v_add_u32_e32 v4, v192, v16
	v_ashrrev_i32_e32 v5, 31, v4
	v_lshl_add_u64 v[4:5], v[4:5], 1, s[8:9]
	v_add_u32_e32 v10, v195, v16
	v_ashrrev_i32_e32 v11, 31, v10
	v_lshl_add_u64 v[10:11], v[10:11], 1, s[8:9]
	s_waitcnt vmcnt(15)
	v_fmac_f32_e32 v17, v12, v102
	v_mul_f32_e32 v3, v32, v17
	v_cvt_pk_bf16_f32 v3, v3, s0
	global_store_short v[4:5], v3, off sc1
	v_add_u32_e32 v4, v193, v16
	v_ashrrev_i32_e32 v5, 31, v4
	v_lshl_add_u64 v[4:5], v[4:5], 1, s[8:9]
	s_waitcnt vmcnt(14)
	v_fmac_f32_e32 v2, v13, v102
	v_mul_f32_e32 v3, v32, v2
	v_cvt_pk_bf16_f32 v3, v3, s0
	global_store_short v[4:5], v3, off sc1
	v_add_u32_e32 v4, v194, v16
	v_ashrrev_i32_e32 v5, 31, v4
	v_lshl_add_u64 v[4:5], v[4:5], 1, s[8:9]
	v_xor_b32_e32 v13, 16, v166
	v_ashrrev_i32_e32 v71, 31, v70
	global_store_dword v[82:83], v26, off offset:384 sc1
	global_store_dword v[78:79], v25, off offset:384 sc1
	global_store_dword v[72:73], v24, off offset:384 sc1
	global_store_dword v[74:75], v23, off offset:384 sc1
	global_store_dword v[76:77], v22, off offset:384 sc1
	global_store_dword v[80:81], v21, off offset:384 sc1
	global_store_dword v[86:87], v20, off offset:384 sc1
	global_store_dword v[90:91], v19, off offset:384 sc1
	global_store_dword v[92:93], v18, off offset:384 sc1
	s_waitcnt vmcnt(20)
	v_fmac_f32_e32 v1, v14, v102
	v_mul_f32_e32 v3, v32, v1
	v_cvt_pk_bf16_f32 v3, v3, s0
	global_store_short v[4:5], v3, off sc1
	v_and_b32_e32 v4, 64, v166
	v_xor_b32_e32 v3, 1, v166
	v_add_u32_e32 v7, 64, v4
	v_cmp_lt_i32_e32 vcc, v3, v7
	v_xor_b32_e32 v4, 2, v166
	s_waitcnt vmcnt(19)
	v_fmac_f32_e32 v0, v15, v102
	v_cndmask_b32_e32 v3, v166, v3, vcc
	v_lshlrev_b32_e32 v3, 2, v3
	ds_bpermute_b32 v5, v3, v108
	v_cmp_lt_i32_e32 vcc, v4, v7
	v_mul_f32_e32 v12, v32, v0
	v_cvt_pk_bf16_f32 v12, v12, s0
	v_cndmask_b32_e32 v4, v166, v4, vcc
	v_lshlrev_b32_e32 v4, 2, v4
	s_waitcnt lgkmcnt(0)
	v_add_f32_e32 v6, v108, v5
	ds_bpermute_b32 v8, v4, v6
	v_xor_b32_e32 v5, 4, v166
	v_cmp_lt_i32_e32 vcc, v5, v7
	global_store_dword v[94:95], v17, off offset:384 sc1
	global_store_dword v[96:97], v2, off offset:384 sc1
	v_cndmask_b32_e32 v5, v166, v5, vcc
	v_lshlrev_b32_e32 v5, 2, v5
	s_waitcnt lgkmcnt(0)
	v_add_f32_e32 v8, v6, v8
	ds_bpermute_b32 v9, v5, v8
	v_xor_b32_e32 v6, 8, v166
	v_cmp_lt_i32_e32 vcc, v6, v7
	global_store_dword v[98:99], v1, off offset:384 sc1
	global_store_dword v[100:101], v0, off offset:384 sc1
	v_cndmask_b32_e32 v6, v166, v6, vcc
	v_lshlrev_b32_e32 v6, 2, v6
	s_waitcnt lgkmcnt(0)
	v_add_f32_e32 v8, v8, v9
	ds_bpermute_b32 v9, v6, v8
	v_cmp_lt_i32_e32 vcc, v13, v7
	global_store_short v[10:11], v12, off sc1
	s_waitcnt lgkmcnt(0)
	v_add_f32_e32 v8, v8, v9
	v_cndmask_b32_e32 v7, v166, v13, vcc
	v_lshlrev_b32_e32 v7, 2, v7
	ds_bpermute_b32 v9, v7, v8
	s_and_saveexec_b64 s[60:61], s[0:1]
	s_cbranch_execz .LBB0_709
	s_waitcnt lgkmcnt(0)
	v_add_f32_e32 v10, v8, v9
	v_lshl_add_u64 v[8:9], v[70:71], 2, s[58:59]
	global_store_dword v[8:9], v10, off sc1

.LBB0_779:
	s_add_i32 s58, s67, 0xffffe000
	s_lshr_b32 s58, s58, 12
	s_mulk_i32 s58, 0x1800
	s_addk_i32 s58, 0x1800
	s_cmp_gt_i32 s6, 63
	s_cselect_b32 s6, s58, 0
	s_lshl_b64 s[58:59], s[6:7], 2
	s_add_u32 s58, s14, s58
	s_addc_u32 s59, s15, s59
	s_add_u32 s60, s58, 0x5ba5000
	s_addc_u32 s61, s59, 0
	s_addk_i32 s6, 0x4800
	s_lshl_b64 s[58:59], s[6:7], 2
	v_mov_b32_e32 v70, s66
	s_add_u32 s6, s14, s58
	ds_read_b64 v[70:71], v70
	s_addc_u32 s65, s15, s59
	s_lshl_b32 s58, s64, 14
	s_add_i32 s58, s58, 0x40000
	s_ashr_i32 s59, s58, 31
	s_lshl_b64 s[58:59], s[58:59], 2
	s_add_u32 s58, s10, s58
	s_waitcnt lgkmcnt(0)
	v_readfirstlane_b32 s62, v70
	s_addc_u32 s59, s11, s59
	v_or_b32_e32 v102, s68, v138
	v_add_u32_e32 v70, s67, v139
	v_readfirstlane_b32 s63, v71
	s_add_u32 s62, s62, 0x1000
	v_ashrrev_i32_e32 v103, 31, v102
	v_lshlrev_b32_e32 v191, 10, v70
	s_addc_u32 s63, s63, 0
	v_lshlrev_b64 v[72:73], 2, v[102:103]
	v_or_b32_e32 v187, 0x400, v191
	v_or_b32_e32 v186, 0x4400, v191
	v_or_b32_e32 v189, 0x4c00, v191
	v_or_b32_e32 v194, 0x6c00, v191
	s_add_u32 s64, s6, 0x5ba1000
	v_lshl_add_u64 v[74:75], s[60:61], 0, v[72:73]
	v_add_u32_e32 v130, v191, v102
	v_add_u32_e32 v132, v187, v102
	v_or_b32_e32 v185, 0x800, v191
	v_or_b32_e32 v184, 0xc00, v191
	v_or_b32_e32 v182, 0x2000, v191
	v_or_b32_e32 v180, 0x2400, v191
	v_or_b32_e32 v71, 0x2800, v191
	v_or_b32_e32 v181, 0x2c00, v191
	v_or_b32_e32 v183, 0x4000, v191
	v_add_u32_e32 v112, v186, v102
	v_or_b32_e32 v188, 0x4800, v191
	v_add_u32_e32 v116, v189, v102
	v_or_b32_e32 v190, 0x6000, v191
	v_or_b32_e32 v192, 0x6400, v191
	v_or_b32_e32 v193, 0x6800, v191
	v_add_u32_e32 v128, v194, v102
	s_addc_u32 s65, s65, 0
	global_load_dword v195, v[74:75], off
	global_load_dword v205, v[74:75], off offset:128
	global_load_dword v224, v[74:75], off offset:256
	v_lshl_add_u64 v[74:75], s[62:63], 0, v[72:73]
	v_ashrrev_i32_e32 v133, 31, v132
	v_add_u32_e32 v134, v185, v102
	v_add_u32_e32 v136, v184, v102
	v_add_u32_e32 v126, v182, v102
	v_add_u32_e32 v118, v180, v102
	v_add_u32_e32 v110, v71, v102
	v_add_u32_e32 v106, v181, v102
	v_add_u32_e32 v108, v183, v102
	v_ashrrev_i32_e32 v113, 31, v112
	v_add_u32_e32 v114, v188, v102
	v_ashrrev_i32_e32 v117, 31, v116
	v_add_u32_e32 v120, v190, v102
	v_add_u32_e32 v122, v192, v102
	v_add_u32_e32 v124, v193, v102
	v_ashrrev_i32_e32 v129, 31, v128
	v_ashrrev_i32_e32 v131, 31, v130
	v_lshl_add_u64 v[72:73], s[64:65], 0, v[72:73]
	global_load_dword v196, v[74:75], off
	global_load_dword v204, v[74:75], off offset:128
	global_load_dword v223, v[74:75], off offset:256
	global_load_dword v197, v[72:73], off
	global_load_dword v203, v[72:73], off offset:128
	global_load_dword v222, v[72:73], off offset:256
	v_lshl_add_u64 v[88:89], v[132:133], 2, s[12:13]
	v_ashrrev_i32_e32 v135, 31, v134
	v_ashrrev_i32_e32 v137, 31, v136
	v_ashrrev_i32_e32 v127, 31, v126
	v_ashrrev_i32_e32 v119, 31, v118
	v_ashrrev_i32_e32 v111, 31, v110
	v_ashrrev_i32_e32 v107, 31, v106
	v_ashrrev_i32_e32 v109, 31, v108
	v_lshl_add_u64 v[86:87], v[112:113], 2, s[12:13]
	v_ashrrev_i32_e32 v115, 31, v114
	v_lshl_add_u64 v[92:93], v[116:117], 2, s[12:13]
	v_ashrrev_i32_e32 v121, 31, v120
	v_ashrrev_i32_e32 v123, 31, v122
	v_ashrrev_i32_e32 v125, 31, v124
	v_lshl_add_u64 v[100:101], v[128:129], 2, s[12:13]
	v_lshl_add_u64 v[104:105], v[130:131], 2, s[12:13]
	v_lshl_add_u64 v[84:85], v[134:135], 2, s[12:13]
	v_lshl_add_u64 v[82:83], v[136:137], 2, s[12:13]
	v_lshl_add_u64 v[78:79], v[126:127], 2, s[12:13]
	v_lshl_add_u64 v[72:73], v[118:119], 2, s[12:13]
	v_lshl_add_u64 v[74:75], v[110:111], 2, s[12:13]
	v_lshl_add_u64 v[76:77], v[106:107], 2, s[12:13]
	v_lshl_add_u64 v[80:81], v[108:109], 2, s[12:13]
	global_load_dword v179, v[88:89], off
	global_load_dword v178, v[84:85], off
	global_load_dword v177, v[82:83], off
	global_load_dword v176, v[78:79], off
	global_load_dword v175, v[72:73], off
	global_load_dword v174, v[74:75], off
	global_load_dword v173, v[76:77], off
	global_load_dword v172, v[80:81], off
	v_lshl_add_u64 v[90:91], v[114:115], 2, s[12:13]
	global_load_dword v171, v[86:87], off
	global_load_dword v169, v[90:91], off
	v_lshl_add_u64 v[94:95], v[120:121], 2, s[12:13]
	v_lshl_add_u64 v[96:97], v[122:123], 2, s[12:13]
	v_lshl_add_u64 v[98:99], v[124:125], 2, s[12:13]
	global_load_dword v170, v[92:93], off
	global_load_dword v168, v[94:95], off
	global_load_dword v167, v[96:97], off
	global_load_dword v166, v[98:99], off
	global_load_dword v103, v[100:101], off
	global_load_dword v198, v[104:105], off
	v_lshl_add_u64 v[110:111], v[110:111], 1, s[8:9]
	v_lshl_add_u64 v[106:107], v[106:107], 1, s[8:9]
	global_load_dword v202, v[104:105], off offset:128
	global_load_dword v206, v[84:85], off offset:128
	global_load_dword v207, v[78:79], off offset:128
	global_load_dword v208, v[72:73], off offset:128
	global_load_dword v209, v[74:75], off offset:128
	global_load_dword v210, v[80:81], off offset:128
	global_load_dword v211, v[76:77], off offset:128
	global_load_dword v212, v[86:87], off offset:128
	global_load_dword v213, v[82:83], off offset:128
	global_load_dword v214, v[90:91], off offset:128
	global_load_dword v215, v[92:93], off offset:128
	global_load_dword v216, v[94:95], off offset:128
	global_load_dword v217, v[96:97], off offset:128
	global_load_dword v218, v[98:99], off offset:128
	global_load_dword v219, v[100:101], off offset:128
	global_load_dword v220, v[88:89], off offset:128
	global_load_dword v221, v[88:89], off offset:256
	global_load_dword v225, v[90:91], off offset:256
	global_load_dword v226, v[92:93], off offset:256
	global_load_dword v227, v[94:95], off offset:256
	global_load_dword v229, v[104:105], off offset:256
	global_load_dword v230, v[84:85], off offset:256
	global_load_dword v231, v[86:87], off offset:256
	global_load_dword v232, v[82:83], off offset:256
	global_load_dword v233, v[78:79], off offset:256
	global_load_dword v234, v[72:73], off offset:256
	global_load_dword v235, v[74:75], off offset:256
	global_load_dword v236, v[80:81], off offset:256
	global_load_dword v237, v[76:77], off offset:256
	global_load_dword v238, v[96:97], off offset:256
	global_load_dword v239, v[98:99], off offset:256
	global_load_dword v240, v[100:101], off offset:256
	s_waitcnt vmcnt(0)
	v_add_f32_e32 v197, 1.0, v197
	v_mul_f32_e32 v196, v196, v197
	v_fmac_f32_e32 v179, v49, v195
	v_fmac_f32_e32 v178, v50, v195
	v_fmac_f32_e32 v177, v51, v195
	v_fmac_f32_e32 v176, v52, v195
	v_fmac_f32_e32 v175, v53, v195
	v_fmac_f32_e32 v174, v54, v195
	v_fmac_f32_e32 v173, v55, v195
	v_fmac_f32_e32 v172, v56, v195
	v_fmac_f32_e32 v171, v57, v195
	v_fmac_f32_e32 v169, v58, v195
	v_fmac_f32_e32 v170, v59, v195
	v_fmac_f32_e32 v168, v60, v195
	v_fmac_f32_e32 v167, v61, v195
	v_fmac_f32_e32 v166, v62, v195
	v_fmac_f32_e32 v103, v63, v195
	v_fmac_f32_e32 v198, v48, v195
	v_mul_f32_e32 v48, v196, v198
	v_cvt_pk_bf16_f32 v58, v48, s0
	v_or_b32_e32 v48, 32, v102
	v_ashrrev_i32_e32 v49, 31, v48
	v_lshlrev_b64 v[52:53], 2, v[48:49]
	global_store_dword v[88:89], v179, off sc1
	global_store_dword v[84:85], v178, off sc1
	global_store_dword v[82:83], v177, off sc1
	global_store_dword v[78:79], v176, off sc1
	global_store_dword v[72:73], v175, off sc1
	global_store_dword v[74:75], v174, off sc1
	global_store_dword v[76:77], v173, off sc1
	global_store_dword v[80:81], v172, off sc1
	global_store_dword v[86:87], v171, off sc1
	global_store_dword v[90:91], v169, off sc1
	global_store_dword v[92:93], v170, off sc1
	global_store_dword v[94:95], v168, off sc1
	global_store_dword v[96:97], v167, off sc1
	global_store_dword v[98:99], v166, off sc1
	global_store_dword v[100:101], v103, off sc1
	global_store_dword v[104:105], v198, off sc1
	v_lshl_add_u64 v[50:51], v[130:131], 1, s[8:9]
	v_lshl_add_u64 v[56:57], s[64:65], 0, v[52:53]
	v_mov_b32_e32 v197, v202
	v_lshl_add_u64 v[54:55], s[62:63], 0, v[52:53]
	v_mov_b32_e32 v130, v203
	v_mov_b32_e32 v131, v204
	v_mul_f32_e32 v49, v196, v179
	global_store_short v[50:51], v58, off sc1
	v_lshl_add_u64 v[50:51], s[60:61], 0, v[52:53]
	v_mov_b32_e32 v195, v205
	v_lshl_add_u64 v[50:51], v[132:133], 1, s[8:9]
	v_cvt_pk_bf16_f32 v49, v49, s0
	global_store_short v[50:51], v49, off sc1
	v_mul_f32_e32 v49, v196, v178
	v_lshl_add_u64 v[50:51], v[134:135], 1, s[8:9]
	v_cvt_pk_bf16_f32 v49, v49, s0
	global_store_short v[50:51], v49, off sc1
	v_mul_f32_e32 v49, v196, v177
	v_lshl_add_u64 v[50:51], v[136:137], 1, s[8:9]
	v_cvt_pk_bf16_f32 v49, v49, s0
	global_store_short v[50:51], v49, off sc1
	v_mul_f32_e32 v49, v196, v176
	v_lshl_add_u64 v[50:51], v[126:127], 1, s[8:9]
	v_cvt_pk_bf16_f32 v49, v49, s0
	global_store_short v[50:51], v49, off sc1
	v_mul_f32_e32 v49, v196, v175
	v_lshl_add_u64 v[50:51], v[118:119], 1, s[8:9]
	v_cvt_pk_bf16_f32 v49, v49, s0
	v_mov_b32_e32 v62, v206
	v_mov_b32_e32 v60, v207
	v_mov_b32_e32 v59, v208
	v_mov_b32_e32 v58, v209
	v_mov_b32_e32 v56, v210
	v_mov_b32_e32 v57, v211
	v_mov_b32_e32 v55, v212
	v_mov_b32_e32 v61, v213
	v_mov_b32_e32 v54, v214
	v_mov_b32_e32 v53, v215
	v_mov_b32_e32 v52, v216
	v_mul_f32_e32 v63, v196, v174
	global_store_short v[50:51], v49, off sc1
	v_mov_b32_e32 v51, v217
	v_cvt_pk_bf16_f32 v63, v63, s0
	v_mov_b32_e32 v50, v218
	v_mov_b32_e32 v49, v219
	v_fmac_f32_e32 v197, v32, v195
	global_store_short v[110:111], v63, off sc1
	v_mov_b32_e32 v63, v220
	v_mul_f32_e32 v110, v196, v173
	v_cvt_pk_bf16_f32 v110, v110, s0
	global_store_short v[106:107], v110, off sc1
	v_lshl_add_u64 v[106:107], v[108:109], 1, s[8:9]
	v_mul_f32_e32 v108, v196, v172
	v_cvt_pk_bf16_f32 v108, v108, s0
	global_store_short v[106:107], v108, off sc1
	v_mul_f32_e32 v108, v196, v171
	v_lshl_add_u64 v[106:107], v[112:113], 1, s[8:9]
	v_cvt_pk_bf16_f32 v108, v108, s0
	global_store_short v[106:107], v108, off sc1
	v_mul_f32_e32 v108, v196, v169
	v_lshl_add_u64 v[106:107], v[114:115], 1, s[8:9]
	v_cvt_pk_bf16_f32 v108, v108, s0
	global_store_short v[106:107], v108, off sc1
	v_mul_f32_e32 v108, v196, v170
	v_lshl_add_u64 v[106:107], v[116:117], 1, s[8:9]
	v_cvt_pk_bf16_f32 v108, v108, s0
	global_store_short v[106:107], v108, off sc1
	v_mul_f32_e32 v108, v196, v168
	v_lshl_add_u64 v[106:107], v[120:121], 1, s[8:9]
	v_cvt_pk_bf16_f32 v108, v108, s0
	global_store_short v[106:107], v108, off sc1
	v_mul_f32_e32 v108, v196, v167
	v_lshl_add_u64 v[106:107], v[122:123], 1, s[8:9]
	v_cvt_pk_bf16_f32 v108, v108, s0
	global_store_short v[106:107], v108, off sc1
	v_mul_f32_e32 v108, v196, v166
	v_lshl_add_u64 v[106:107], v[124:125], 1, s[8:9]
	v_cvt_pk_bf16_f32 v108, v108, s0
	global_store_short v[106:107], v108, off sc1
	v_mul_f32_e32 v108, v196, v103
	v_lshl_add_u64 v[106:107], v[128:129], 1, s[8:9]
	v_cvt_pk_bf16_f32 v108, v108, s0
	global_store_short v[106:107], v108, off sc1
	v_add_f32_e32 v106, 1.0, v130
	v_mul_f32_e32 v107, v131, v106
	v_add_u32_e32 v108, v191, v48
	v_ashrrev_i32_e32 v109, 31, v108
	v_mul_f32_e32 v32, v107, v197
	v_fmac_f32_e32 v62, v34, v195
	v_fmac_f32_e32 v61, v35, v195
	v_fmac_f32_e32 v60, v36, v195
	v_fmac_f32_e32 v59, v37, v195
	v_fmac_f32_e32 v58, v38, v195
	v_fmac_f32_e32 v57, v39, v195
	v_fmac_f32_e32 v56, v40, v195
	v_fmac_f32_e32 v55, v41, v195
	v_fmac_f32_e32 v54, v42, v195
	v_fmac_f32_e32 v53, v43, v195
	v_fmac_f32_e32 v52, v44, v195
	v_fmac_f32_e32 v51, v45, v195
	v_fmac_f32_e32 v50, v46, v195
	v_fmac_f32_e32 v49, v47, v195
	global_store_dword v[104:105], v197, off offset:128 sc1
	v_lshl_add_u64 v[108:109], v[108:109], 1, s[8:9]
	v_cvt_pk_bf16_f32 v32, v32, s0
	global_store_dword v[84:85], v62, off offset:128 sc1
	global_store_dword v[82:83], v61, off offset:128 sc1
	global_store_dword v[78:79], v60, off offset:128 sc1
	global_store_dword v[72:73], v59, off offset:128 sc1
	global_store_dword v[74:75], v58, off offset:128 sc1
	global_store_dword v[76:77], v57, off offset:128 sc1
	global_store_dword v[80:81], v56, off offset:128 sc1
	global_store_dword v[86:87], v55, off offset:128 sc1
	global_store_dword v[90:91], v54, off offset:128 sc1
	global_store_dword v[92:93], v53, off offset:128 sc1
	global_store_dword v[94:95], v52, off offset:128 sc1
	global_store_dword v[96:97], v51, off offset:128 sc1
	global_store_dword v[98:99], v50, off offset:128 sc1
	global_store_dword v[100:101], v49, off offset:128 sc1
	global_store_short v[108:109], v32, off sc1
	v_add_u32_e32 v108, v187, v48
	v_mov_b32_e32 v45, v221
	v_ashrrev_i32_e32 v109, 31, v108
	v_mul_f32_e32 v113, v107, v56
	v_cvt_pk_bf16_f32 v113, v113, s0
	v_mul_f32_e32 v106, v197, v197
	v_fmac_f32_e32 v106, v198, v198
	v_fmac_f32_e32 v63, v33, v195
	v_mul_f32_e32 v34, v107, v63
	v_lshl_add_u64 v[32:33], v[108:109], 1, s[8:9]
	v_cvt_pk_bf16_f32 v34, v34, s0
	global_store_short v[32:33], v34, off sc1
	v_add_u32_e32 v32, v185, v48
	v_ashrrev_i32_e32 v33, 31, v32
	v_mul_f32_e32 v34, v107, v62
	v_lshl_add_u64 v[32:33], v[32:33], 1, s[8:9]
	v_cvt_pk_bf16_f32 v34, v34, s0
	global_store_short v[32:33], v34, off sc1
	v_add_u32_e32 v32, v184, v48
	v_ashrrev_i32_e32 v33, 31, v32
	v_mul_f32_e32 v34, v107, v61
	v_lshl_add_u64 v[32:33], v[32:33], 1, s[8:9]
	v_cvt_pk_bf16_f32 v34, v34, s0
	global_store_short v[32:33], v34, off sc1
	v_add_u32_e32 v32, v182, v48
	v_ashrrev_i32_e32 v33, 31, v32
	v_mul_f32_e32 v34, v107, v60
	v_lshl_add_u64 v[32:33], v[32:33], 1, s[8:9]
	v_cvt_pk_bf16_f32 v34, v34, s0
	global_store_short v[32:33], v34, off sc1
	v_add_u32_e32 v32, v180, v48
	v_ashrrev_i32_e32 v33, 31, v32
	v_lshl_add_u64 v[34:35], v[32:33], 1, s[8:9]
	v_mul_f32_e32 v32, v107, v59
	v_cvt_pk_bf16_f32 v42, v32, s0
	v_or_b32_e32 v32, 64, v102
	v_ashrrev_i32_e32 v33, 31, v32
	v_lshlrev_b64 v[36:37], 2, v[32:33]
	global_store_dword v[88:89], v63, off offset:128 sc1
	v_lshl_add_u64 v[40:41], s[64:65], 0, v[36:37]
	v_lshl_add_u64 v[38:39], s[62:63], 0, v[36:37]
	v_mov_b32_e32 v110, v222
	v_mov_b32_e32 v111, v223
	v_mul_f32_e32 v33, v107, v58
	global_store_short v[34:35], v42, off sc1
	v_lshl_add_u64 v[34:35], s[60:61], 0, v[36:37]
	v_mov_b32_e32 v112, v224
	v_add_u32_e32 v34, v71, v48
	v_ashrrev_i32_e32 v35, 31, v34
	v_lshl_add_u64 v[34:35], v[34:35], 1, s[8:9]
	v_cvt_pk_bf16_f32 v33, v33, s0
	global_store_short v[34:35], v33, off sc1
	v_add_u32_e32 v34, v181, v48
	v_ashrrev_i32_e32 v35, 31, v34
	v_mul_f32_e32 v33, v107, v57
	v_lshl_add_u64 v[34:35], v[34:35], 1, s[8:9]
	v_cvt_pk_bf16_f32 v33, v33, s0
	v_mov_b32_e32 v38, v225
	v_mov_b32_e32 v37, v226
	v_mov_b32_e32 v36, v227
	v_mov_b32_e32 v114, v229
	v_mov_b32_e32 v47, v230
	v_mov_b32_e32 v39, v231
	v_mov_b32_e32 v46, v232
	v_mov_b32_e32 v44, v233
	v_mov_b32_e32 v43, v234
	v_mov_b32_e32 v42, v235
	v_mov_b32_e32 v40, v236
	v_mov_b32_e32 v41, v237
	v_add_u32_e32 v108, v183, v48
	global_store_short v[34:35], v33, off sc1
	v_mov_b32_e32 v35, v238
	v_ashrrev_i32_e32 v109, 31, v108
	v_mov_b32_e32 v34, v239
	v_mov_b32_e32 v33, v240
	v_lshl_add_u64 v[108:109], v[108:109], 1, s[8:9]
	global_store_short v[108:109], v113, off sc1
	v_add_u32_e32 v108, v186, v48
	v_ashrrev_i32_e32 v109, 31, v108
	v_mul_f32_e32 v113, v107, v55
	v_lshl_add_u64 v[108:109], v[108:109], 1, s[8:9]
	v_cvt_pk_bf16_f32 v113, v113, s0
	global_store_short v[108:109], v113, off sc1
	v_add_u32_e32 v108, v188, v48
	v_ashrrev_i32_e32 v109, 31, v108
	v_mul_f32_e32 v113, v107, v54
	v_lshl_add_u64 v[108:109], v[108:109], 1, s[8:9]
	v_cvt_pk_bf16_f32 v113, v113, s0
	global_store_short v[108:109], v113, off sc1
	v_add_u32_e32 v108, v189, v48
	v_ashrrev_i32_e32 v109, 31, v108
	v_mul_f32_e32 v113, v107, v53
	v_lshl_add_u64 v[108:109], v[108:109], 1, s[8:9]
	v_cvt_pk_bf16_f32 v113, v113, s0
	global_store_short v[108:109], v113, off sc1
	v_add_u32_e32 v108, v190, v48
	v_ashrrev_i32_e32 v109, 31, v108
	v_mul_f32_e32 v113, v107, v52
	v_lshl_add_u64 v[108:109], v[108:109], 1, s[8:9]
	v_cvt_pk_bf16_f32 v113, v113, s0
	global_store_short v[108:109], v113, off sc1
	v_add_u32_e32 v108, v192, v48
	v_ashrrev_i32_e32 v109, 31, v108
	v_mul_f32_e32 v113, v107, v51
	v_lshl_add_u64 v[108:109], v[108:109], 1, s[8:9]
	v_cvt_pk_bf16_f32 v113, v113, s0
	global_store_short v[108:109], v113, off sc1
	v_add_u32_e32 v108, v193, v48
	v_ashrrev_i32_e32 v109, 31, v108
	v_mul_f32_e32 v113, v107, v50
	v_lshl_add_u64 v[108:109], v[108:109], 1, s[8:9]
	v_cvt_pk_bf16_f32 v113, v113, s0
	global_store_short v[108:109], v113, off sc1
	v_add_u32_e32 v108, v194, v48
	v_ashrrev_i32_e32 v109, 31, v108
	v_mul_f32_e32 v48, v107, v49
	v_lshl_add_u64 v[108:109], v[108:109], 1, s[8:9]
	v_cvt_pk_bf16_f32 v48, v48, s0
	global_store_short v[108:109], v48, off sc1
	v_add_u32_e32 v108, v191, v32
	v_ashrrev_i32_e32 v109, 31, v108
	v_add_f32_e32 v48, 1.0, v110
	v_mul_f32_e32 v48, v111, v48
	v_fmac_f32_e32 v45, v17, v112
	global_store_dword v[88:89], v45, off offset:256 sc1
	v_fmac_f32_e32 v38, v26, v112
	v_fmac_f32_e32 v37, v27, v112
	v_fmac_f32_e32 v36, v28, v112
	v_fmac_f32_e32 v114, v16, v112
	v_fmac_f32_e32 v47, v18, v112
	v_mul_f32_e32 v18, v48, v114
	v_lshl_add_u64 v[16:17], v[108:109], 1, s[8:9]
	v_cvt_pk_bf16_f32 v18, v18, s0
	global_store_short v[16:17], v18, off sc1
	v_add_u32_e32 v16, v187, v32
	v_ashrrev_i32_e32 v17, 31, v16
	v_mul_f32_e32 v18, v48, v45
	v_lshl_add_u64 v[16:17], v[16:17], 1, s[8:9]
	v_cvt_pk_bf16_f32 v18, v18, s0
	global_store_short v[16:17], v18, off sc1
	v_add_u32_e32 v16, v185, v32
	v_ashrrev_i32_e32 v17, 31, v16
	v_mul_f32_e32 v18, v48, v47
	v_lshl_add_u64 v[16:17], v[16:17], 1, s[8:9]
	v_cvt_pk_bf16_f32 v18, v18, s0
	v_fmac_f32_e32 v46, v19, v112
	global_store_short v[16:17], v18, off sc1
	v_add_u32_e32 v16, v184, v32
	v_ashrrev_i32_e32 v17, 31, v16
	v_mul_f32_e32 v18, v48, v46
	v_lshl_add_u64 v[16:17], v[16:17], 1, s[8:9]
	v_cvt_pk_bf16_f32 v18, v18, s0
	global_store_short v[16:17], v18, off sc1
	v_add_u32_e32 v16, v182, v32
	v_ashrrev_i32_e32 v17, 31, v16
	v_lshl_add_u64 v[18:19], v[16:17], 1, s[8:9]
	v_or_b32_e32 v16, 0x60, v102
	v_ashrrev_i32_e32 v17, 31, v16
	v_fmac_f32_e32 v44, v20, v112
	v_fmac_f32_e32 v43, v21, v112
	v_fmac_f32_e32 v42, v22, v112
	v_fmac_f32_e32 v41, v23, v112
	v_fmac_f32_e32 v40, v24, v112
	v_fmac_f32_e32 v39, v25, v112
	v_fmac_f32_e32 v35, v29, v112
	v_fmac_f32_e32 v34, v30, v112
	v_fmac_f32_e32 v33, v31, v112
	v_lshlrev_b64 v[20:21], 2, v[16:17]
	global_store_dword v[84:85], v47, off offset:256 sc1
	global_store_dword v[82:83], v46, off offset:256 sc1
	global_store_dword v[78:79], v44, off offset:256 sc1
	global_store_dword v[72:73], v43, off offset:256 sc1
	global_store_dword v[74:75], v42, off offset:256 sc1
	global_store_dword v[76:77], v41, off offset:256 sc1
	global_store_dword v[80:81], v40, off offset:256 sc1
	global_store_dword v[86:87], v39, off offset:256 sc1
	global_store_dword v[90:91], v38, off offset:256 sc1
	global_store_dword v[92:93], v37, off offset:256 sc1
	global_store_dword v[94:95], v36, off offset:256 sc1
	global_store_dword v[96:97], v35, off offset:256 sc1
	global_store_dword v[98:99], v34, off offset:256 sc1
	global_store_dword v[100:101], v33, off offset:256 sc1
	global_store_dword v[104:105], v114, off offset:256 sc1
	v_mul_f32_e32 v26, v48, v44
	v_lshl_add_u64 v[22:23], s[62:63], 0, v[20:21]
	v_lshl_add_u64 v[24:25], s[64:65], 0, v[20:21]
	global_load_dword v29, v[104:105], off offset:384
	global_load_dword v17, v[24:25], off
	global_load_dword v30, v[22:23], off
	v_cvt_pk_bf16_f32 v22, v26, s0
	global_store_short v[18:19], v22, off sc1
	v_lshl_add_u64 v[18:19], s[60:61], 0, v[20:21]
	global_load_dword v102, v[18:19], off
	v_add_u32_e32 v18, v180, v32
	v_ashrrev_i32_e32 v19, 31, v18
	v_mul_f32_e32 v20, v48, v43
	v_lshl_add_u64 v[18:19], v[18:19], 1, s[8:9]
	v_cvt_pk_bf16_f32 v20, v20, s0
	global_store_short v[18:19], v20, off sc1
	v_add_u32_e32 v18, v71, v32
	v_ashrrev_i32_e32 v19, 31, v18
	v_mul_f32_e32 v20, v48, v42
	v_lshl_add_u64 v[18:19], v[18:19], 1, s[8:9]
	v_cvt_pk_bf16_f32 v20, v20, s0
	global_store_short v[18:19], v20, off sc1
	v_add_u32_e32 v18, v181, v32
	v_ashrrev_i32_e32 v19, 31, v18
	v_mul_f32_e32 v20, v48, v41
	v_lshl_add_u64 v[18:19], v[18:19], 1, s[8:9]
	v_cvt_pk_bf16_f32 v20, v20, s0
	global_store_short v[18:19], v20, off sc1
	v_add_u32_e32 v18, v183, v32
	v_ashrrev_i32_e32 v19, 31, v18
	v_mul_f32_e32 v20, v48, v40
	v_lshl_add_u64 v[18:19], v[18:19], 1, s[8:9]
	v_cvt_pk_bf16_f32 v20, v20, s0
	global_store_short v[18:19], v20, off sc1
	v_add_u32_e32 v18, v186, v32
	v_ashrrev_i32_e32 v19, 31, v18
	v_mul_f32_e32 v20, v48, v39
	v_lshl_add_u64 v[18:19], v[18:19], 1, s[8:9]
	v_cvt_pk_bf16_f32 v20, v20, s0
	global_store_short v[18:19], v20, off sc1
	v_add_u32_e32 v18, v188, v32
	v_ashrrev_i32_e32 v19, 31, v18
	v_mul_f32_e32 v20, v48, v38
	v_lshl_add_u64 v[18:19], v[18:19], 1, s[8:9]
	v_cvt_pk_bf16_f32 v20, v20, s0
	global_store_short v[18:19], v20, off sc1
	v_add_u32_e32 v18, v189, v32
	v_ashrrev_i32_e32 v19, 31, v18
	v_mul_f32_e32 v20, v48, v37
	v_lshl_add_u64 v[18:19], v[18:19], 1, s[8:9]
	v_cvt_pk_bf16_f32 v20, v20, s0
	global_store_short v[18:19], v20, off sc1
	v_add_u32_e32 v18, v190, v32
	v_ashrrev_i32_e32 v19, 31, v18
	v_mul_f32_e32 v20, v48, v36
	v_lshl_add_u64 v[18:19], v[18:19], 1, s[8:9]
	v_cvt_pk_bf16_f32 v20, v20, s0
	global_store_short v[18:19], v20, off sc1
	v_add_u32_e32 v18, v192, v32
	v_ashrrev_i32_e32 v19, 31, v18
	v_mul_f32_e32 v20, v48, v35
	v_lshl_add_u64 v[18:19], v[18:19], 1, s[8:9]
	v_cvt_pk_bf16_f32 v20, v20, s0
	global_load_dword v28, v[88:89], off offset:384
	global_load_dword v27, v[84:85], off offset:384
	global_load_dword v25, v[78:79], off offset:384
	global_load_dword v24, v[72:73], off offset:384
	global_load_dword v23, v[74:75], off offset:384
	global_load_dword v21, v[80:81], off offset:384
	global_load_dword v22, v[76:77], off offset:384
	v_fmac_f32_e32 v106, v114, v114
	global_store_short v[18:19], v20, off sc1
	v_add_u32_e32 v18, v193, v32
	v_ashrrev_i32_e32 v19, 31, v18
	v_mul_f32_e32 v20, v48, v34
	v_lshl_add_u64 v[18:19], v[18:19], 1, s[8:9]
	v_cvt_pk_bf16_f32 v20, v20, s0
	global_store_short v[18:19], v20, off sc1
	v_add_u32_e32 v18, v194, v32
	v_ashrrev_i32_e32 v19, 31, v18
	v_mul_f32_e32 v20, v48, v33
	v_lshl_add_u64 v[18:19], v[18:19], 1, s[8:9]
	v_cvt_pk_bf16_f32 v20, v20, s0
	global_store_short v[18:19], v20, off sc1
	global_load_dword v20, v[86:87], off offset:384
	s_waitcnt vmcnt(22)
	v_add_f32_e32 v17, 1.0, v17
	global_load_dword v26, v[82:83], off offset:384
	s_waitcnt vmcnt(22)
	v_mul_f32_e32 v32, v30, v17
	v_add_u32_e32 v18, v191, v16
	s_waitcnt vmcnt(20)
	v_fmac_f32_e32 v29, v0, v102
	v_ashrrev_i32_e32 v19, 31, v18
	v_mul_f32_e32 v0, v32, v29
	v_lshl_add_u64 v[18:19], v[18:19], 1, s[8:9]
	v_cvt_pk_bf16_f32 v0, v0, s0
	global_store_short v[18:19], v0, off sc1
	global_load_dword v19, v[90:91], off offset:384
	v_add_u32_e32 v30, v187, v16
	global_load_dword v18, v[92:93], off offset:384
	v_ashrrev_i32_e32 v31, 31, v30
	v_fmac_f32_e32 v106, v29, v29
	global_store_dword v[104:105], v29, off offset:384 sc1
	s_waitcnt vmcnt(15)
	v_fmac_f32_e32 v28, v1, v102
	v_mul_f32_e32 v17, v32, v28
	v_lshl_add_u64 v[0:1], v[30:31], 1, s[8:9]
	v_cvt_pk_bf16_f32 v17, v17, s0
	global_store_short v[0:1], v17, off sc1
	v_add_u32_e32 v0, v185, v16
	s_waitcnt vmcnt(15)
	v_fmac_f32_e32 v27, v2, v102
	global_load_dword v17, v[94:95], off offset:384
	v_ashrrev_i32_e32 v1, 31, v0
	v_mul_f32_e32 v2, v32, v27
	v_lshl_add_u64 v[0:1], v[0:1], 1, s[8:9]
	v_cvt_pk_bf16_f32 v2, v2, s0
	global_store_short v[0:1], v2, off sc1
	v_add_u32_e32 v0, v184, v16
	global_load_dword v2, v[96:97], off offset:384
	v_ashrrev_i32_e32 v1, 31, v0
	v_lshl_add_u64 v[0:1], v[0:1], 1, s[8:9]
	v_add_u32_e32 v30, v182, v16
	s_waitcnt vmcnt(17)
	v_fmac_f32_e32 v25, v4, v102
	v_ashrrev_i32_e32 v31, 31, v30
	v_lshl_add_u64 v[30:31], v[30:31], 1, s[8:9]
	s_waitcnt vmcnt(16)
	v_fmac_f32_e32 v24, v5, v102
	s_waitcnt vmcnt(15)
	v_fmac_f32_e32 v23, v6, v102
	s_waitcnt vmcnt(8)
	v_fmac_f32_e32 v26, v3, v102
	v_mul_f32_e32 v3, v32, v26
	v_cvt_pk_bf16_f32 v3, v3, s0
	global_store_short v[0:1], v3, off sc1
	global_load_dword v1, v[98:99], off offset:384
	v_mul_f32_e32 v0, v32, v25
	v_cvt_pk_bf16_f32 v0, v0, s0
	global_store_short v[30:31], v0, off sc1
	global_load_dword v0, v[100:101], off offset:384
	v_add_u32_e32 v30, v180, v16
	v_ashrrev_i32_e32 v31, 31, v30
	v_mul_f32_e32 v3, v32, v24
	v_lshl_add_u64 v[4:5], v[30:31], 1, s[8:9]
	v_cvt_pk_bf16_f32 v3, v3, s0
	global_store_short v[4:5], v3, off sc1
	v_add_u32_e32 v4, v71, v16
	v_ashrrev_i32_e32 v5, 31, v4
	v_mul_f32_e32 v3, v32, v23
	v_lshl_add_u64 v[4:5], v[4:5], 1, s[8:9]
	v_cvt_pk_bf16_f32 v3, v3, s0
	global_store_short v[4:5], v3, off sc1
	v_add_u32_e32 v4, v181, v16
	v_fmac_f32_e32 v22, v7, v102
	v_ashrrev_i32_e32 v5, 31, v4
	v_mul_f32_e32 v3, v32, v22
	v_lshl_add_u64 v[4:5], v[4:5], 1, s[8:9]
	v_cvt_pk_bf16_f32 v3, v3, s0
	global_store_short v[4:5], v3, off sc1
	v_add_u32_e32 v4, v183, v16
	v_fmac_f32_e32 v21, v8, v102
	v_ashrrev_i32_e32 v5, 31, v4
	v_mul_f32_e32 v3, v32, v21
	v_lshl_add_u64 v[4:5], v[4:5], 1, s[8:9]
	v_cvt_pk_bf16_f32 v3, v3, s0
	global_store_short v[4:5], v3, off sc1
	v_add_u32_e32 v4, v186, v16
	v_fmac_f32_e32 v20, v9, v102
	v_ashrrev_i32_e32 v5, 31, v4
	v_mul_f32_e32 v3, v32, v20
	v_lshl_add_u64 v[4:5], v[4:5], 1, s[8:9]
	v_cvt_pk_bf16_f32 v3, v3, s0
	global_store_short v[4:5], v3, off sc1
	v_add_u32_e32 v4, v188, v16
	s_waitcnt vmcnt(15)
	v_fmac_f32_e32 v19, v10, v102
	v_ashrrev_i32_e32 v5, 31, v4
	v_mul_f32_e32 v3, v32, v19
	v_lshl_add_u64 v[4:5], v[4:5], 1, s[8:9]
	v_cvt_pk_bf16_f32 v3, v3, s0
	global_store_short v[4:5], v3, off sc1
	v_add_u32_e32 v4, v189, v16
	s_waitcnt vmcnt(15)
	v_fmac_f32_e32 v18, v11, v102
	v_ashrrev_i32_e32 v5, 31, v4
	v_mul_f32_e32 v3, v32, v18
	v_lshl_add_u64 v[4:5], v[4:5], 1, s[8:9]
	v_cvt_pk_bf16_f32 v3, v3, s0
	global_store_short v[4:5], v3, off sc1
	v_add_u32_e32 v4, v190, v16
	v_ashrrev_i32_e32 v5, 31, v4
	v_lshl_add_u64 v[4:5], v[4:5], 1, s[8:9]
	v_ashrrev_i32_e32 v71, 31, v70
	global_store_dword v[88:89], v28, off offset:384 sc1
	global_store_dword v[84:85], v27, off offset:384 sc1
	global_store_dword v[82:83], v26, off offset:384 sc1
	global_store_dword v[78:79], v25, off offset:384 sc1
	s_waitcnt vmcnt(17)
	v_fmac_f32_e32 v17, v12, v102
	v_mul_f32_e32 v3, v32, v17
	v_cvt_pk_bf16_f32 v3, v3, s0
	global_store_short v[4:5], v3, off sc1
	v_add_u32_e32 v4, v192, v16
	v_ashrrev_i32_e32 v5, 31, v4
	v_lshl_add_u64 v[4:5], v[4:5], 1, s[8:9]
	s_waitcnt vmcnt(16)
	v_fmac_f32_e32 v2, v13, v102
	v_mul_f32_e32 v3, v32, v2
	v_cvt_pk_bf16_f32 v3, v3, s0
	global_store_short v[4:5], v3, off sc1
	v_add_u32_e32 v4, v193, v16
	v_ashrrev_i32_e32 v5, 31, v4
	v_lshl_add_u64 v[4:5], v[4:5], 1, s[8:9]
	v_xor_b32_e32 v12, 16, v165
	global_store_dword v[72:73], v24, off offset:384 sc1
	global_store_dword v[74:75], v23, off offset:384 sc1
	global_store_dword v[76:77], v22, off offset:384 sc1
	global_store_dword v[80:81], v21, off offset:384 sc1
	global_store_dword v[86:87], v20, off offset:384 sc1
	s_waitcnt vmcnt(20)
	v_fmac_f32_e32 v1, v14, v102
	v_mul_f32_e32 v3, v32, v1
	v_cvt_pk_bf16_f32 v3, v3, s0
	global_store_short v[4:5], v3, off sc1
	v_add_u32_e32 v4, v194, v16
	v_ashrrev_i32_e32 v5, 31, v4
	v_lshl_add_u64 v[10:11], v[4:5], 1, s[8:9]
	v_and_b32_e32 v4, 64, v165
	v_xor_b32_e32 v3, 1, v165
	v_add_u32_e32 v7, 64, v4
	v_cmp_lt_i32_e32 vcc, v3, v7
	v_xor_b32_e32 v4, 2, v165
	s_waitcnt vmcnt(19)
	v_fmac_f32_e32 v0, v15, v102
	v_cndmask_b32_e32 v3, v165, v3, vcc
	v_lshlrev_b32_e32 v3, 2, v3
	ds_bpermute_b32 v5, v3, v106
	v_cmp_lt_i32_e32 vcc, v4, v7
	global_store_dword v[90:91], v19, off offset:384 sc1
	global_store_dword v[92:93], v18, off offset:384 sc1
	v_cndmask_b32_e32 v4, v165, v4, vcc
	v_lshlrev_b32_e32 v4, 2, v4
	s_waitcnt lgkmcnt(0)
	v_add_f32_e32 v6, v106, v5
	ds_bpermute_b32 v8, v4, v6
	v_xor_b32_e32 v5, 4, v165
	v_cmp_lt_i32_e32 vcc, v5, v7
	global_store_dword v[94:95], v17, off offset:384 sc1
	global_store_dword v[96:97], v2, off offset:384 sc1
	v_cndmask_b32_e32 v5, v165, v5, vcc
	v_lshlrev_b32_e32 v5, 2, v5
	s_waitcnt lgkmcnt(0)
	v_add_f32_e32 v8, v6, v8
	ds_bpermute_b32 v9, v5, v8
	v_xor_b32_e32 v6, 8, v165
	v_cmp_lt_i32_e32 vcc, v6, v7
	global_store_dword v[98:99], v1, off offset:384 sc1
	global_store_dword v[100:101], v0, off offset:384 sc1
	v_cndmask_b32_e32 v6, v165, v6, vcc
	v_lshlrev_b32_e32 v6, 2, v6
	s_waitcnt lgkmcnt(0)
	v_add_f32_e32 v8, v8, v9
	ds_bpermute_b32 v9, v6, v8
	v_cmp_lt_i32_e32 vcc, v12, v7
	s_waitcnt lgkmcnt(0)
	v_add_f32_e32 v8, v8, v9
	v_cndmask_b32_e32 v7, v165, v12, vcc
	v_lshlrev_b32_e32 v7, 2, v7
	ds_bpermute_b32 v9, v7, v8
	v_mul_f32_e32 v12, v32, v0
	v_cvt_pk_bf16_f32 v12, v12, s0
	global_store_short v[10:11], v12, off sc1
	s_and_saveexec_b64 s[60:61], s[0:1]
	s_cbranch_execz .LBB0_781
	s_waitcnt lgkmcnt(0)
	v_add_f32_e32 v10, v8, v9
	v_lshl_add_u64 v[8:9], v[70:71], 2, s[58:59]
	global_store_dword v[8:9], v10, off sc1

.LBB0_1050:
	s_add_i32 s58, s66, 0xffffe000
	s_lshr_b32 s58, s58, 12
	s_mulk_i32 s58, 0x1800
	v_mov_b32_e32 v70, s70
	s_addk_i32 s58, 0x6000
	ds_read_b64 v[70:71], v70
	s_cmp_gt_i32 s6, 63
	s_cselect_b32 s6, s58, 0x4800
	s_lshl_b64 s[58:59], s[6:7], 2
	s_add_u32 s6, s14, s58
	s_addc_u32 s65, s15, s59
	s_waitcnt lgkmcnt(0)
	v_readfirstlane_b32 s58, v70
	v_readfirstlane_b32 s59, v71
	s_add_u32 s60, s58, 0x1000
	s_addc_u32 s61, s59, 0
	s_lshl_b32 s58, s64, 14
	s_add_i32 s58, s58, 0x60000
	s_ashr_i32 s59, s58, 31
	s_lshl_b64 s[58:59], s[58:59], 2
	s_add_u32 s58, s10, s58
	s_addc_u32 s59, s11, s59
	s_add_u32 s62, s6, 0x5ba2000
	v_or_b32_e32 v102, s68, v138
	v_add_u32_e32 v70, s66, v139
	s_addc_u32 s63, s65, 0
	v_lshlrev_b32_e32 v188, 10, v70
	v_ashrrev_i32_e32 v103, 31, v102
	s_add_u32 s64, s6, 0x5ba4000
	v_lshlrev_b64 v[72:73], 2, v[102:103]
	v_or_b32_e32 v186, 0x400, v188
	v_or_b32_e32 v185, 0x4400, v188
	v_or_b32_e32 v189, 0x4c00, v188
	v_or_b32_e32 v193, 0x6c00, v188
	s_addc_u32 s65, s65, 0
	v_lshl_add_u64 v[74:75], s[62:63], 0, v[72:73]
	v_add_u32_e32 v132, v188, v102
	v_add_u32_e32 v134, v186, v102
	v_or_b32_e32 v184, 0x800, v188
	v_or_b32_e32 v183, 0xc00, v188
	v_or_b32_e32 v181, 0x2000, v188
	v_or_b32_e32 v179, 0x2400, v188
	v_or_b32_e32 v71, 0x2800, v188
	v_or_b32_e32 v180, 0x2c00, v188
	v_or_b32_e32 v182, 0x4000, v188
	v_add_u32_e32 v112, v185, v102
	v_or_b32_e32 v187, 0x4800, v188
	v_add_u32_e32 v118, v189, v102
	v_or_b32_e32 v190, 0x6000, v188
	v_or_b32_e32 v191, 0x6400, v188
	v_or_b32_e32 v192, 0x6800, v188
	v_add_u32_e32 v128, v193, v102
	global_load_dword v194, v[74:75], off
	global_load_dword v204, v[74:75], off offset:128
	global_load_dword v223, v[74:75], off offset:256
	v_lshl_add_u64 v[74:75], s[60:61], 0, v[72:73]
	v_lshl_add_u64 v[72:73], s[64:65], 0, v[72:73]
	v_ashrrev_i32_e32 v135, 31, v134
	v_add_u32_e32 v136, v184, v102
	v_add_u32_e32 v130, v183, v102
	v_add_u32_e32 v122, v181, v102
	v_add_u32_e32 v114, v179, v102
	v_add_u32_e32 v106, v71, v102
	v_add_u32_e32 v108, v180, v102
	v_add_u32_e32 v110, v182, v102
	v_ashrrev_i32_e32 v113, 31, v112
	v_add_u32_e32 v116, v187, v102
	v_ashrrev_i32_e32 v119, 31, v118
	v_add_u32_e32 v120, v190, v102
	v_add_u32_e32 v124, v191, v102
	v_add_u32_e32 v126, v192, v102
	v_ashrrev_i32_e32 v129, 31, v128
	v_ashrrev_i32_e32 v133, 31, v132
	global_load_dword v196, v[72:73], off
	global_load_dword v202, v[72:73], off offset:128
	global_load_dword v221, v[72:73], off offset:256
	v_lshl_add_u64 v[88:89], v[134:135], 2, s[12:13]
	v_ashrrev_i32_e32 v137, 31, v136
	v_ashrrev_i32_e32 v131, 31, v130
	v_ashrrev_i32_e32 v123, 31, v122
	v_ashrrev_i32_e32 v115, 31, v114
	v_ashrrev_i32_e32 v107, 31, v106
	v_ashrrev_i32_e32 v109, 31, v108
	v_ashrrev_i32_e32 v111, 31, v110
	v_lshl_add_u64 v[86:87], v[112:113], 2, s[12:13]
	v_ashrrev_i32_e32 v117, 31, v116
	v_lshl_add_u64 v[92:93], v[118:119], 2, s[12:13]
	v_ashrrev_i32_e32 v121, 31, v120
	v_ashrrev_i32_e32 v125, 31, v124
	v_ashrrev_i32_e32 v127, 31, v126
	v_lshl_add_u64 v[100:101], v[128:129], 2, s[12:13]
	v_lshl_add_u64 v[104:105], v[132:133], 2, s[12:13]
	global_load_dword v195, v[74:75], off
	global_load_dword v203, v[74:75], off offset:128
	global_load_dword v222, v[74:75], off offset:256
	v_lshl_add_u64 v[84:85], v[136:137], 2, s[12:13]
	v_lshl_add_u64 v[82:83], v[130:131], 2, s[12:13]
	v_lshl_add_u64 v[78:79], v[122:123], 2, s[12:13]
	v_lshl_add_u64 v[72:73], v[114:115], 2, s[12:13]
	v_lshl_add_u64 v[74:75], v[106:107], 2, s[12:13]
	v_lshl_add_u64 v[76:77], v[108:109], 2, s[12:13]
	v_lshl_add_u64 v[80:81], v[110:111], 2, s[12:13]
	global_load_dword v178, v[88:89], off
	global_load_dword v177, v[84:85], off
	global_load_dword v176, v[82:83], off
	global_load_dword v175, v[78:79], off
	global_load_dword v174, v[72:73], off
	global_load_dword v173, v[74:75], off
	global_load_dword v172, v[76:77], off
	global_load_dword v171, v[80:81], off
	v_lshl_add_u64 v[90:91], v[116:117], 2, s[12:13]
	global_load_dword v170, v[86:87], off
	global_load_dword v168, v[90:91], off
	v_lshl_add_u64 v[94:95], v[120:121], 2, s[12:13]
	v_lshl_add_u64 v[96:97], v[124:125], 2, s[12:13]
	v_lshl_add_u64 v[98:99], v[126:127], 2, s[12:13]
	global_load_dword v169, v[92:93], off
	global_load_dword v167, v[94:95], off
	global_load_dword v166, v[96:97], off
	global_load_dword v165, v[98:99], off
	global_load_dword v103, v[100:101], off
	global_load_dword v197, v[104:105], off
	v_lshl_add_u64 v[106:107], v[106:107], 1, s[8:9]
	global_load_dword v198, v[104:105], off offset:128
	global_load_dword v205, v[84:85], off offset:128
	global_load_dword v206, v[78:79], off offset:128
	global_load_dword v207, v[72:73], off offset:128
	global_load_dword v208, v[74:75], off offset:128
	global_load_dword v209, v[80:81], off offset:128
	global_load_dword v210, v[76:77], off offset:128
	global_load_dword v211, v[86:87], off offset:128
	global_load_dword v212, v[82:83], off offset:128
	global_load_dword v213, v[90:91], off offset:128
	global_load_dword v214, v[92:93], off offset:128
	global_load_dword v215, v[94:95], off offset:128
	global_load_dword v216, v[96:97], off offset:128
	global_load_dword v217, v[98:99], off offset:128
	global_load_dword v218, v[100:101], off offset:128
	global_load_dword v219, v[88:89], off offset:128
	global_load_dword v220, v[88:89], off offset:256
	global_load_dword v224, v[90:91], off offset:256
	global_load_dword v225, v[92:93], off offset:256
	global_load_dword v226, v[94:95], off offset:256
	global_load_dword v227, v[104:105], off offset:256
	global_load_dword v229, v[84:85], off offset:256
	global_load_dword v230, v[86:87], off offset:256
	global_load_dword v231, v[82:83], off offset:256
	global_load_dword v232, v[78:79], off offset:256
	global_load_dword v233, v[72:73], off offset:256
	global_load_dword v234, v[74:75], off offset:256
	global_load_dword v235, v[80:81], off offset:256
	global_load_dword v236, v[76:77], off offset:256
	global_load_dword v237, v[96:97], off offset:256
	global_load_dword v238, v[98:99], off offset:256
	global_load_dword v239, v[100:101], off offset:256
	s_waitcnt vmcnt(0)
	v_add_f32_e32 v196, 1.0, v196
	v_mul_f32_e32 v195, v195, v196
	v_fmac_f32_e32 v178, v49, v194
	v_fmac_f32_e32 v177, v50, v194
	v_fmac_f32_e32 v176, v51, v194
	v_fmac_f32_e32 v175, v52, v194
	v_fmac_f32_e32 v174, v53, v194
	v_fmac_f32_e32 v173, v54, v194
	v_fmac_f32_e32 v172, v55, v194
	v_fmac_f32_e32 v171, v56, v194
	v_fmac_f32_e32 v170, v57, v194
	v_fmac_f32_e32 v168, v58, v194
	v_fmac_f32_e32 v169, v59, v194
	v_fmac_f32_e32 v167, v60, v194
	v_fmac_f32_e32 v166, v61, v194
	v_fmac_f32_e32 v165, v62, v194
	v_fmac_f32_e32 v103, v63, v194
	v_fmac_f32_e32 v197, v48, v194
	v_mul_f32_e32 v48, v195, v197
	v_cvt_pk_bf16_f32 v58, v48, s0
	v_or_b32_e32 v48, 32, v102
	v_ashrrev_i32_e32 v49, 31, v48
	v_lshlrev_b64 v[52:53], 2, v[48:49]
	global_store_dword v[88:89], v178, off sc1
	global_store_dword v[84:85], v177, off sc1
	global_store_dword v[82:83], v176, off sc1
	global_store_dword v[78:79], v175, off sc1
	global_store_dword v[72:73], v174, off sc1
	global_store_dword v[74:75], v173, off sc1
	global_store_dword v[76:77], v172, off sc1
	global_store_dword v[80:81], v171, off sc1
	global_store_dword v[86:87], v170, off sc1
	global_store_dword v[90:91], v168, off sc1
	global_store_dword v[92:93], v169, off sc1
	global_store_dword v[94:95], v167, off sc1
	global_store_dword v[96:97], v166, off sc1
	global_store_dword v[98:99], v165, off sc1
	global_store_dword v[100:101], v103, off sc1
	global_store_dword v[104:105], v197, off sc1
	v_lshl_add_u64 v[50:51], v[132:133], 1, s[8:9]
	v_lshl_add_u64 v[56:57], s[64:65], 0, v[52:53]
	v_mov_b32_e32 v196, v198
	v_lshl_add_u64 v[54:55], s[60:61], 0, v[52:53]
	v_mov_b32_e32 v132, v202
	v_mov_b32_e32 v133, v203
	v_mul_f32_e32 v49, v195, v178
	global_store_short v[50:51], v58, off sc1
	v_lshl_add_u64 v[50:51], s[62:63], 0, v[52:53]
	v_mov_b32_e32 v194, v204
	v_cvt_pk_bf16_f32 v49, v49, s0
	v_lshl_add_u64 v[50:51], v[134:135], 1, s[8:9]
	global_store_short v[50:51], v49, off sc1
	v_mul_f32_e32 v49, v195, v177
	v_cvt_pk_bf16_f32 v49, v49, s0
	v_lshl_add_u64 v[50:51], v[136:137], 1, s[8:9]
	global_store_short v[50:51], v49, off sc1
	v_mul_f32_e32 v49, v195, v176
	v_cvt_pk_bf16_f32 v49, v49, s0
	v_lshl_add_u64 v[50:51], v[130:131], 1, s[8:9]
	global_store_short v[50:51], v49, off sc1
	v_mul_f32_e32 v49, v195, v175
	v_cvt_pk_bf16_f32 v49, v49, s0
	v_lshl_add_u64 v[50:51], v[122:123], 1, s[8:9]
	global_store_short v[50:51], v49, off sc1
	v_mul_f32_e32 v49, v195, v174
	v_cvt_pk_bf16_f32 v49, v49, s0
	v_lshl_add_u64 v[50:51], v[114:115], 1, s[8:9]
	global_store_short v[50:51], v49, off sc1
	v_mul_f32_e32 v49, v195, v173
	v_mov_b32_e32 v62, v205
	v_mov_b32_e32 v60, v206
	v_mov_b32_e32 v59, v207
	v_mov_b32_e32 v58, v208
	v_mov_b32_e32 v56, v209
	v_mov_b32_e32 v57, v210
	v_mov_b32_e32 v55, v211
	v_mov_b32_e32 v61, v212
	v_mov_b32_e32 v54, v213
	v_mov_b32_e32 v53, v214
	v_mov_b32_e32 v52, v215
	v_mov_b32_e32 v51, v216
	v_mov_b32_e32 v50, v217
	v_cvt_pk_bf16_f32 v63, v49, s0
	v_mov_b32_e32 v49, v218
	v_fmac_f32_e32 v196, v32, v194
	global_store_short v[106:107], v63, off sc1
	v_mov_b32_e32 v63, v219
	v_mul_f32_e32 v106, v195, v172
	v_cvt_pk_bf16_f32 v114, v106, s0
	v_lshl_add_u64 v[106:107], v[108:109], 1, s[8:9]
	global_store_short v[106:107], v114, off sc1
	v_mul_f32_e32 v106, v195, v171
	v_cvt_pk_bf16_f32 v108, v106, s0
	v_lshl_add_u64 v[106:107], v[110:111], 1, s[8:9]
	global_store_short v[106:107], v108, off sc1
	v_mul_f32_e32 v106, v195, v170
	v_cvt_pk_bf16_f32 v108, v106, s0
	v_lshl_add_u64 v[106:107], v[112:113], 1, s[8:9]
	global_store_short v[106:107], v108, off sc1
	v_mul_f32_e32 v106, v195, v168
	v_cvt_pk_bf16_f32 v108, v106, s0
	v_lshl_add_u64 v[106:107], v[116:117], 1, s[8:9]
	global_store_short v[106:107], v108, off sc1
	v_mul_f32_e32 v106, v195, v169
	v_cvt_pk_bf16_f32 v108, v106, s0
	v_lshl_add_u64 v[106:107], v[118:119], 1, s[8:9]
	global_store_short v[106:107], v108, off sc1
	v_mul_f32_e32 v106, v195, v167
	v_cvt_pk_bf16_f32 v108, v106, s0
	v_lshl_add_u64 v[106:107], v[120:121], 1, s[8:9]
	global_store_short v[106:107], v108, off sc1
	v_mul_f32_e32 v106, v195, v166
	v_cvt_pk_bf16_f32 v108, v106, s0
	v_lshl_add_u64 v[106:107], v[124:125], 1, s[8:9]
	global_store_short v[106:107], v108, off sc1
	v_mul_f32_e32 v106, v195, v165
	v_cvt_pk_bf16_f32 v108, v106, s0
	v_lshl_add_u64 v[106:107], v[126:127], 1, s[8:9]
	global_store_short v[106:107], v108, off sc1
	v_mul_f32_e32 v106, v195, v103
	v_cvt_pk_bf16_f32 v108, v106, s0
	v_lshl_add_u64 v[106:107], v[128:129], 1, s[8:9]
	global_store_short v[106:107], v108, off sc1
	v_add_f32_e32 v106, 1.0, v132
	v_mul_f32_e32 v110, v133, v106
	v_add_u32_e32 v106, v188, v48
	v_fmac_f32_e32 v62, v34, v194
	v_fmac_f32_e32 v61, v35, v194
	v_fmac_f32_e32 v60, v36, v194
	v_fmac_f32_e32 v59, v37, v194
	v_fmac_f32_e32 v58, v38, v194
	v_fmac_f32_e32 v57, v39, v194
	v_fmac_f32_e32 v56, v40, v194
	v_fmac_f32_e32 v55, v41, v194
	v_fmac_f32_e32 v54, v42, v194
	v_fmac_f32_e32 v53, v43, v194
	v_fmac_f32_e32 v52, v44, v194
	v_fmac_f32_e32 v51, v45, v194
	v_fmac_f32_e32 v50, v46, v194
	v_fmac_f32_e32 v49, v47, v194
	v_ashrrev_i32_e32 v107, 31, v106
	global_store_dword v[104:105], v196, off offset:128 sc1
	v_mul_f32_e32 v32, v110, v196
	global_store_dword v[84:85], v62, off offset:128 sc1
	global_store_dword v[82:83], v61, off offset:128 sc1
	global_store_dword v[78:79], v60, off offset:128 sc1
	global_store_dword v[72:73], v59, off offset:128 sc1
	global_store_dword v[74:75], v58, off offset:128 sc1
	global_store_dword v[76:77], v57, off offset:128 sc1
	global_store_dword v[80:81], v56, off offset:128 sc1
	global_store_dword v[86:87], v55, off offset:128 sc1
	global_store_dword v[90:91], v54, off offset:128 sc1
	global_store_dword v[92:93], v53, off offset:128 sc1
	global_store_dword v[94:95], v52, off offset:128 sc1
	global_store_dword v[96:97], v51, off offset:128 sc1
	global_store_dword v[98:99], v50, off offset:128 sc1
	global_store_dword v[100:101], v49, off offset:128 sc1
	v_cvt_pk_bf16_f32 v32, v32, s0
	v_lshl_add_u64 v[106:107], v[106:107], 1, s[8:9]
	v_add_u32_e32 v108, v186, v48
	v_mov_b32_e32 v45, v220
	v_ashrrev_i32_e32 v109, 31, v108
	global_store_short v[106:107], v32, off sc1
	v_mul_f32_e32 v113, v110, v56
	v_cvt_pk_bf16_f32 v113, v113, s0
	v_mul_f32_e32 v106, v196, v196
	v_fmac_f32_e32 v63, v33, v194
	v_mul_f32_e32 v32, v110, v63
	v_cvt_pk_bf16_f32 v34, v32, s0
	v_lshl_add_u64 v[32:33], v[108:109], 1, s[8:9]
	global_store_short v[32:33], v34, off sc1
	v_add_u32_e32 v32, v184, v48
	v_ashrrev_i32_e32 v33, 31, v32
	v_mul_f32_e32 v34, v110, v62
	v_cvt_pk_bf16_f32 v34, v34, s0
	v_lshl_add_u64 v[32:33], v[32:33], 1, s[8:9]
	global_store_short v[32:33], v34, off sc1
	v_add_u32_e32 v32, v183, v48
	v_ashrrev_i32_e32 v33, 31, v32
	v_mul_f32_e32 v34, v110, v61
	v_cvt_pk_bf16_f32 v34, v34, s0
	v_lshl_add_u64 v[32:33], v[32:33], 1, s[8:9]
	global_store_short v[32:33], v34, off sc1
	v_add_u32_e32 v32, v181, v48
	v_ashrrev_i32_e32 v33, 31, v32
	v_mul_f32_e32 v34, v110, v60
	v_cvt_pk_bf16_f32 v34, v34, s0
	v_lshl_add_u64 v[32:33], v[32:33], 1, s[8:9]
	global_store_short v[32:33], v34, off sc1
	v_add_u32_e32 v32, v179, v48
	v_ashrrev_i32_e32 v33, 31, v32
	v_mul_f32_e32 v34, v110, v59
	v_cvt_pk_bf16_f32 v42, v34, s0
	v_lshl_add_u64 v[34:35], v[32:33], 1, s[8:9]
	v_or_b32_e32 v32, 64, v102
	v_ashrrev_i32_e32 v33, 31, v32
	v_lshlrev_b64 v[36:37], 2, v[32:33]
	global_store_dword v[88:89], v63, off offset:128 sc1
	v_lshl_add_u64 v[40:41], s[64:65], 0, v[36:37]
	v_lshl_add_u64 v[38:39], s[60:61], 0, v[36:37]
	v_mov_b32_e32 v107, v221
	v_mov_b32_e32 v111, v222
	v_mul_f32_e32 v33, v110, v58
	global_store_short v[34:35], v42, off sc1
	v_lshl_add_u64 v[34:35], s[62:63], 0, v[36:37]
	v_mov_b32_e32 v112, v223
	v_add_u32_e32 v34, v71, v48
	v_ashrrev_i32_e32 v35, 31, v34
	v_cvt_pk_bf16_f32 v33, v33, s0
	v_lshl_add_u64 v[34:35], v[34:35], 1, s[8:9]
	global_store_short v[34:35], v33, off sc1
	v_add_u32_e32 v34, v180, v48
	v_ashrrev_i32_e32 v35, 31, v34
	v_mul_f32_e32 v33, v110, v57
	v_cvt_pk_bf16_f32 v33, v33, s0
	v_lshl_add_u64 v[34:35], v[34:35], 1, s[8:9]
	v_mov_b32_e32 v38, v224
	v_mov_b32_e32 v37, v225
	v_mov_b32_e32 v36, v226
	v_mov_b32_e32 v114, v227
	v_mov_b32_e32 v47, v229
	v_mov_b32_e32 v39, v230
	v_mov_b32_e32 v46, v231
	v_mov_b32_e32 v44, v232
	v_mov_b32_e32 v43, v233
	v_mov_b32_e32 v42, v234
	v_mov_b32_e32 v40, v235
	v_mov_b32_e32 v41, v236
	v_add_u32_e32 v108, v182, v48
	global_store_short v[34:35], v33, off sc1
	v_mov_b32_e32 v35, v237
	v_ashrrev_i32_e32 v109, 31, v108
	v_mov_b32_e32 v34, v238
	v_mov_b32_e32 v33, v239
	v_lshl_add_u64 v[108:109], v[108:109], 1, s[8:9]
	global_store_short v[108:109], v113, off sc1
	v_add_u32_e32 v108, v185, v48
	v_ashrrev_i32_e32 v109, 31, v108
	v_mul_f32_e32 v113, v110, v55
	v_cvt_pk_bf16_f32 v113, v113, s0
	v_lshl_add_u64 v[108:109], v[108:109], 1, s[8:9]
	global_store_short v[108:109], v113, off sc1
	v_add_u32_e32 v108, v187, v48
	v_ashrrev_i32_e32 v109, 31, v108
	v_mul_f32_e32 v113, v110, v54
	v_cvt_pk_bf16_f32 v113, v113, s0
	v_lshl_add_u64 v[108:109], v[108:109], 1, s[8:9]
	global_store_short v[108:109], v113, off sc1
	v_add_u32_e32 v108, v189, v48
	v_ashrrev_i32_e32 v109, 31, v108
	v_mul_f32_e32 v113, v110, v53
	v_cvt_pk_bf16_f32 v113, v113, s0
	v_lshl_add_u64 v[108:109], v[108:109], 1, s[8:9]
	global_store_short v[108:109], v113, off sc1
	v_add_u32_e32 v108, v190, v48
	v_ashrrev_i32_e32 v109, 31, v108
	v_mul_f32_e32 v113, v110, v52
	v_cvt_pk_bf16_f32 v113, v113, s0
	v_lshl_add_u64 v[108:109], v[108:109], 1, s[8:9]
	global_store_short v[108:109], v113, off sc1
	v_add_u32_e32 v108, v191, v48
	v_ashrrev_i32_e32 v109, 31, v108
	v_mul_f32_e32 v113, v110, v51
	v_cvt_pk_bf16_f32 v113, v113, s0
	v_lshl_add_u64 v[108:109], v[108:109], 1, s[8:9]
	global_store_short v[108:109], v113, off sc1
	v_add_u32_e32 v108, v192, v48
	v_ashrrev_i32_e32 v109, 31, v108
	v_mul_f32_e32 v113, v110, v50
	v_cvt_pk_bf16_f32 v113, v113, s0
	v_lshl_add_u64 v[108:109], v[108:109], 1, s[8:9]
	global_store_short v[108:109], v113, off sc1
	v_add_u32_e32 v108, v193, v48
	v_ashrrev_i32_e32 v109, 31, v108
	v_mul_f32_e32 v48, v110, v49
	v_cvt_pk_bf16_f32 v48, v48, s0
	v_lshl_add_u64 v[108:109], v[108:109], 1, s[8:9]
	global_store_short v[108:109], v48, off sc1
	v_add_u32_e32 v108, v188, v32
	v_ashrrev_i32_e32 v109, 31, v108
	v_add_f32_e32 v48, 1.0, v107
	v_mul_f32_e32 v48, v111, v48
	v_fmac_f32_e32 v106, v197, v197
	v_fmac_f32_e32 v45, v17, v112
	global_store_dword v[88:89], v45, off offset:256 sc1
	v_fmac_f32_e32 v38, v26, v112
	v_fmac_f32_e32 v37, v27, v112
	v_fmac_f32_e32 v36, v28, v112
	v_fmac_f32_e32 v114, v16, v112
	v_mul_f32_e32 v16, v48, v114
	v_fmac_f32_e32 v47, v18, v112
	v_cvt_pk_bf16_f32 v18, v16, s0
	v_lshl_add_u64 v[16:17], v[108:109], 1, s[8:9]
	global_store_short v[16:17], v18, off sc1
	v_add_u32_e32 v16, v186, v32
	v_ashrrev_i32_e32 v17, 31, v16
	v_mul_f32_e32 v18, v48, v45
	v_cvt_pk_bf16_f32 v18, v18, s0
	v_lshl_add_u64 v[16:17], v[16:17], 1, s[8:9]
	global_store_short v[16:17], v18, off sc1
	v_add_u32_e32 v16, v184, v32
	v_ashrrev_i32_e32 v17, 31, v16
	v_mul_f32_e32 v18, v48, v47
	v_cvt_pk_bf16_f32 v18, v18, s0
	v_lshl_add_u64 v[16:17], v[16:17], 1, s[8:9]
	v_fmac_f32_e32 v46, v19, v112
	global_store_short v[16:17], v18, off sc1
	v_add_u32_e32 v16, v183, v32
	v_ashrrev_i32_e32 v17, 31, v16
	v_mul_f32_e32 v18, v48, v46
	v_fmac_f32_e32 v44, v20, v112
	v_cvt_pk_bf16_f32 v18, v18, s0
	v_lshl_add_u64 v[16:17], v[16:17], 1, s[8:9]
	global_store_short v[16:17], v18, off sc1
	v_mul_f32_e32 v16, v48, v44
	v_cvt_pk_bf16_f32 v26, v16, s0
	v_or_b32_e32 v16, 0x60, v102
	v_add_u32_e32 v18, v181, v32
	v_ashrrev_i32_e32 v17, 31, v16
	v_fmac_f32_e32 v43, v21, v112
	v_fmac_f32_e32 v42, v22, v112
	v_fmac_f32_e32 v41, v23, v112
	v_fmac_f32_e32 v40, v24, v112
	v_fmac_f32_e32 v39, v25, v112
	v_fmac_f32_e32 v35, v29, v112
	v_fmac_f32_e32 v34, v30, v112
	v_fmac_f32_e32 v33, v31, v112
	v_ashrrev_i32_e32 v19, 31, v18
	v_lshlrev_b64 v[20:21], 2, v[16:17]
	global_store_dword v[84:85], v47, off offset:256 sc1
	global_store_dword v[82:83], v46, off offset:256 sc1
	global_store_dword v[78:79], v44, off offset:256 sc1
	global_store_dword v[72:73], v43, off offset:256 sc1
	global_store_dword v[74:75], v42, off offset:256 sc1
	global_store_dword v[76:77], v41, off offset:256 sc1
	global_store_dword v[80:81], v40, off offset:256 sc1
	global_store_dword v[86:87], v39, off offset:256 sc1
	global_store_dword v[90:91], v38, off offset:256 sc1
	global_store_dword v[92:93], v37, off offset:256 sc1
	global_store_dword v[94:95], v36, off offset:256 sc1
	global_store_dword v[96:97], v35, off offset:256 sc1
	global_store_dword v[98:99], v34, off offset:256 sc1
	global_store_dword v[100:101], v33, off offset:256 sc1
	global_store_dword v[104:105], v114, off offset:256 sc1
	v_lshl_add_u64 v[24:25], s[64:65], 0, v[20:21]
	v_lshl_add_u64 v[18:19], v[18:19], 1, s[8:9]
	global_load_dword v29, v[104:105], off offset:384
	v_lshl_add_u64 v[22:23], s[60:61], 0, v[20:21]
	global_load_dword v17, v[24:25], off
	global_load_dword v30, v[22:23], off
	global_load_dword v28, v[88:89], off offset:384
	global_load_dword v27, v[84:85], off offset:384
	v_fmac_f32_e32 v106, v114, v114
	global_store_short v[18:19], v26, off sc1
	v_lshl_add_u64 v[18:19], s[62:63], 0, v[20:21]
	global_load_dword v102, v[18:19], off
	v_add_u32_e32 v18, v179, v32
	v_ashrrev_i32_e32 v19, 31, v18
	v_mul_f32_e32 v20, v48, v43
	v_cvt_pk_bf16_f32 v20, v20, s0
	v_lshl_add_u64 v[18:19], v[18:19], 1, s[8:9]
	global_store_short v[18:19], v20, off sc1
	v_add_u32_e32 v18, v71, v32
	v_ashrrev_i32_e32 v19, 31, v18
	v_mul_f32_e32 v20, v48, v42
	v_cvt_pk_bf16_f32 v20, v20, s0
	v_lshl_add_u64 v[18:19], v[18:19], 1, s[8:9]
	global_store_short v[18:19], v20, off sc1
	v_add_u32_e32 v18, v180, v32
	v_ashrrev_i32_e32 v19, 31, v18
	v_mul_f32_e32 v20, v48, v41
	v_cvt_pk_bf16_f32 v20, v20, s0
	v_lshl_add_u64 v[18:19], v[18:19], 1, s[8:9]
	global_store_short v[18:19], v20, off sc1
	v_add_u32_e32 v18, v182, v32
	v_ashrrev_i32_e32 v19, 31, v18
	v_mul_f32_e32 v20, v48, v40
	v_cvt_pk_bf16_f32 v20, v20, s0
	v_lshl_add_u64 v[18:19], v[18:19], 1, s[8:9]
	global_store_short v[18:19], v20, off sc1
	v_add_u32_e32 v18, v185, v32
	v_ashrrev_i32_e32 v19, 31, v18
	v_mul_f32_e32 v20, v48, v39
	v_cvt_pk_bf16_f32 v20, v20, s0
	v_lshl_add_u64 v[18:19], v[18:19], 1, s[8:9]
	global_store_short v[18:19], v20, off sc1
	v_add_u32_e32 v18, v187, v32
	v_ashrrev_i32_e32 v19, 31, v18
	v_mul_f32_e32 v20, v48, v38
	v_cvt_pk_bf16_f32 v20, v20, s0
	v_lshl_add_u64 v[18:19], v[18:19], 1, s[8:9]
	global_store_short v[18:19], v20, off sc1
	v_add_u32_e32 v18, v189, v32
	v_ashrrev_i32_e32 v19, 31, v18
	v_mul_f32_e32 v20, v48, v37
	v_cvt_pk_bf16_f32 v20, v20, s0
	v_lshl_add_u64 v[18:19], v[18:19], 1, s[8:9]
	global_store_short v[18:19], v20, off sc1
	v_add_u32_e32 v18, v190, v32
	v_ashrrev_i32_e32 v19, 31, v18
	v_mul_f32_e32 v20, v48, v36
	v_cvt_pk_bf16_f32 v20, v20, s0
	v_lshl_add_u64 v[18:19], v[18:19], 1, s[8:9]
	global_store_short v[18:19], v20, off sc1
	v_add_u32_e32 v18, v191, v32
	v_ashrrev_i32_e32 v19, 31, v18
	v_mul_f32_e32 v20, v48, v35
	v_cvt_pk_bf16_f32 v20, v20, s0
	v_lshl_add_u64 v[18:19], v[18:19], 1, s[8:9]
	global_store_short v[18:19], v20, off sc1
	v_add_u32_e32 v18, v192, v32
	v_ashrrev_i32_e32 v19, 31, v18
	v_mul_f32_e32 v20, v48, v34
	v_cvt_pk_bf16_f32 v20, v20, s0
	v_lshl_add_u64 v[18:19], v[18:19], 1, s[8:9]
	global_store_short v[18:19], v20, off sc1
	v_add_u32_e32 v18, v193, v32
	v_ashrrev_i32_e32 v19, 31, v18
	v_mul_f32_e32 v20, v48, v33
	v_cvt_pk_bf16_f32 v20, v20, s0
	v_lshl_add_u64 v[18:19], v[18:19], 1, s[8:9]
	global_store_short v[18:19], v20, off sc1
	global_load_dword v20, v[86:87], off offset:384
	v_add_u32_e32 v18, v188, v16
	global_load_dword v26, v[82:83], off offset:384
	global_load_dword v25, v[78:79], off offset:384
	global_load_dword v24, v[72:73], off offset:384
	global_load_dword v23, v[74:75], off offset:384
	global_load_dword v21, v[80:81], off offset:384
	global_load_dword v22, v[76:77], off offset:384
	s_waitcnt vmcnt(23)
	v_add_f32_e32 v17, 1.0, v17
	s_waitcnt vmcnt(22)
	v_mul_f32_e32 v32, v30, v17
	v_ashrrev_i32_e32 v19, 31, v18
	v_lshl_add_u64 v[18:19], v[18:19], 1, s[8:9]
	v_add_u32_e32 v30, v186, v16
	s_waitcnt vmcnt(18)
	v_fmac_f32_e32 v29, v0, v102
	v_mul_f32_e32 v0, v32, v29
	v_cvt_pk_bf16_f32 v0, v0, s0
	global_store_short v[18:19], v0, off sc1
	global_load_dword v19, v[90:91], off offset:384
	v_ashrrev_i32_e32 v31, 31, v30
	global_load_dword v18, v[92:93], off offset:384
	v_fmac_f32_e32 v28, v1, v102
	v_mul_f32_e32 v0, v32, v28
	v_cvt_pk_bf16_f32 v17, v0, s0
	v_lshl_add_u64 v[0:1], v[30:31], 1, s[8:9]
	global_store_short v[0:1], v17, off sc1
	v_add_u32_e32 v0, v184, v16
	v_fmac_f32_e32 v27, v2, v102
	global_load_dword v17, v[94:95], off offset:384
	v_ashrrev_i32_e32 v1, 31, v0
	v_mul_f32_e32 v2, v32, v27
	v_cvt_pk_bf16_f32 v2, v2, s0
	v_lshl_add_u64 v[0:1], v[0:1], 1, s[8:9]
	global_store_short v[0:1], v2, off sc1
	v_add_u32_e32 v0, v183, v16
	global_load_dword v2, v[96:97], off offset:384
	v_ashrrev_i32_e32 v1, 31, v0
	v_lshl_add_u64 v[0:1], v[0:1], 1, s[8:9]
	v_add_u32_e32 v30, v181, v16
	v_ashrrev_i32_e32 v31, 31, v30
	v_lshl_add_u64 v[30:31], v[30:31], 1, s[8:9]
	v_fmac_f32_e32 v106, v29, v29
	global_store_dword v[104:105], v29, off offset:384 sc1
	global_store_dword v[88:89], v28, off offset:384 sc1
	global_store_dword v[84:85], v27, off offset:384 sc1
	s_waitcnt vmcnt(16)
	v_fmac_f32_e32 v20, v9, v102
	global_store_dword v[86:87], v20, off offset:384 sc1
	s_waitcnt vmcnt(16)
	v_fmac_f32_e32 v26, v3, v102
	v_mul_f32_e32 v3, v32, v26
	v_cvt_pk_bf16_f32 v3, v3, s0
	global_store_short v[0:1], v3, off sc1
	global_load_dword v1, v[98:99], off offset:384
	s_waitcnt vmcnt(17)
	v_fmac_f32_e32 v25, v4, v102
	v_mul_f32_e32 v0, v32, v25
	v_cvt_pk_bf16_f32 v0, v0, s0
	global_store_short v[30:31], v0, off sc1
	global_load_dword v0, v[100:101], off offset:384
	v_add_u32_e32 v30, v179, v16
	s_waitcnt vmcnt(18)
	v_fmac_f32_e32 v24, v5, v102
	v_ashrrev_i32_e32 v31, 31, v30
	v_mul_f32_e32 v3, v32, v24
	v_cvt_pk_bf16_f32 v3, v3, s0
	v_lshl_add_u64 v[4:5], v[30:31], 1, s[8:9]
	global_store_short v[4:5], v3, off sc1
	v_add_u32_e32 v4, v71, v16
	s_waitcnt vmcnt(18)
	v_fmac_f32_e32 v23, v6, v102
	v_ashrrev_i32_e32 v5, 31, v4
	v_mul_f32_e32 v3, v32, v23
	v_cvt_pk_bf16_f32 v3, v3, s0
	v_lshl_add_u64 v[4:5], v[4:5], 1, s[8:9]
	global_store_short v[4:5], v3, off sc1
	v_add_u32_e32 v4, v180, v16
	s_waitcnt vmcnt(17)
	v_fmac_f32_e32 v22, v7, v102
	v_ashrrev_i32_e32 v5, 31, v4
	v_mul_f32_e32 v3, v32, v22
	v_cvt_pk_bf16_f32 v3, v3, s0
	v_lshl_add_u64 v[4:5], v[4:5], 1, s[8:9]
	global_store_short v[4:5], v3, off sc1
	v_add_u32_e32 v4, v182, v16
	v_fmac_f32_e32 v21, v8, v102
	v_ashrrev_i32_e32 v5, 31, v4
	v_mul_f32_e32 v3, v32, v21
	v_cvt_pk_bf16_f32 v3, v3, s0
	v_lshl_add_u64 v[4:5], v[4:5], 1, s[8:9]
	global_store_short v[4:5], v3, off sc1
	v_add_u32_e32 v4, v185, v16
	v_ashrrev_i32_e32 v5, 31, v4
	v_mul_f32_e32 v3, v32, v20
	v_cvt_pk_bf16_f32 v3, v3, s0
	v_lshl_add_u64 v[4:5], v[4:5], 1, s[8:9]
	global_store_short v[4:5], v3, off sc1
	v_add_u32_e32 v4, v187, v16
	s_waitcnt vmcnt(18)
	v_fmac_f32_e32 v19, v10, v102
	v_ashrrev_i32_e32 v5, 31, v4
	v_mul_f32_e32 v3, v32, v19
	v_cvt_pk_bf16_f32 v3, v3, s0
	v_lshl_add_u64 v[4:5], v[4:5], 1, s[8:9]
	global_store_short v[4:5], v3, off sc1
	v_add_u32_e32 v4, v189, v16
	s_waitcnt vmcnt(18)
	v_fmac_f32_e32 v18, v11, v102
	v_ashrrev_i32_e32 v5, 31, v4
	v_mul_f32_e32 v3, v32, v18
	v_cvt_pk_bf16_f32 v3, v3, s0
	v_lshl_add_u64 v[4:5], v[4:5], 1, s[8:9]
	global_store_short v[4:5], v3, off sc1
	v_add_u32_e32 v4, v190, v16
	s_waitcnt vmcnt(17)
	v_fmac_f32_e32 v17, v12, v102
	v_ashrrev_i32_e32 v5, 31, v4
	v_mul_f32_e32 v3, v32, v17
	v_cvt_pk_bf16_f32 v3, v3, s0
	v_lshl_add_u64 v[4:5], v[4:5], 1, s[8:9]
	global_store_short v[4:5], v3, off sc1
	v_add_u32_e32 v4, v191, v16
	s_waitcnt vmcnt(16)
	v_fmac_f32_e32 v2, v13, v102
	v_ashrrev_i32_e32 v5, 31, v4
	v_mul_f32_e32 v3, v32, v2
	v_cvt_pk_bf16_f32 v3, v3, s0
	v_lshl_add_u64 v[4:5], v[4:5], 1, s[8:9]
	global_store_short v[4:5], v3, off sc1
	v_add_u32_e32 v4, v192, v16
	v_ashrrev_i32_e32 v5, 31, v4
	v_lshl_add_u64 v[4:5], v[4:5], 1, s[8:9]
	v_xor_b32_e32 v13, 16, v164
	v_add_u32_e32 v10, v193, v16
	v_ashrrev_i32_e32 v11, 31, v10
	v_lshl_add_u64 v[10:11], v[10:11], 1, s[8:9]
	v_ashrrev_i32_e32 v71, 31, v70
	global_store_dword v[82:83], v26, off offset:384 sc1
	global_store_dword v[78:79], v25, off offset:384 sc1
	global_store_dword v[72:73], v24, off offset:384 sc1
	global_store_dword v[74:75], v23, off offset:384 sc1
	s_waitcnt vmcnt(15)
	v_fmac_f32_e32 v1, v14, v102
	v_mul_f32_e32 v3, v32, v1
	v_cvt_pk_bf16_f32 v3, v3, s0
	global_store_short v[4:5], v3, off sc1
	v_and_b32_e32 v4, 64, v164
	v_xor_b32_e32 v3, 1, v164
	v_add_u32_e32 v7, 64, v4
	v_cmp_lt_i32_e32 vcc, v3, v7
	v_xor_b32_e32 v4, 2, v164
	s_waitcnt vmcnt(14)
	v_fmac_f32_e32 v0, v15, v102
	v_cndmask_b32_e32 v3, v164, v3, vcc
	v_lshlrev_b32_e32 v3, 2, v3
	ds_bpermute_b32 v5, v3, v106
	v_cmp_lt_i32_e32 vcc, v4, v7
	v_mul_f32_e32 v12, v32, v0
	v_cvt_pk_bf16_f32 v12, v12, s0
	v_cndmask_b32_e32 v4, v164, v4, vcc
	v_lshlrev_b32_e32 v4, 2, v4
	s_waitcnt lgkmcnt(0)
	v_add_f32_e32 v6, v106, v5
	ds_bpermute_b32 v8, v4, v6
	v_xor_b32_e32 v5, 4, v164
	v_cmp_lt_i32_e32 vcc, v5, v7
	global_store_dword v[76:77], v22, off offset:384 sc1
	global_store_dword v[80:81], v21, off offset:384 sc1
	v_cndmask_b32_e32 v5, v164, v5, vcc
	v_lshlrev_b32_e32 v5, 2, v5
	s_waitcnt lgkmcnt(0)
	v_add_f32_e32 v8, v6, v8
	ds_bpermute_b32 v9, v5, v8
	v_xor_b32_e32 v6, 8, v164
	v_cmp_lt_i32_e32 vcc, v6, v7
	global_store_dword v[90:91], v19, off offset:384 sc1
	global_store_dword v[92:93], v18, off offset:384 sc1
	v_cndmask_b32_e32 v6, v164, v6, vcc
	v_lshlrev_b32_e32 v6, 2, v6
	s_waitcnt lgkmcnt(0)
	v_add_f32_e32 v8, v8, v9
	ds_bpermute_b32 v9, v6, v8
	v_cmp_lt_i32_e32 vcc, v13, v7
	global_store_dword v[94:95], v17, off offset:384 sc1
	global_store_dword v[96:97], v2, off offset:384 sc1
	v_cndmask_b32_e32 v7, v164, v13, vcc
	v_lshlrev_b32_e32 v7, 2, v7
	s_waitcnt lgkmcnt(0)
	v_add_f32_e32 v8, v8, v9
	ds_bpermute_b32 v9, v7, v8
	global_store_dword v[98:99], v1, off offset:384 sc1
	global_store_dword v[100:101], v0, off offset:384 sc1
	global_store_short v[10:11], v12, off sc1
	s_and_saveexec_b64 s[60:61], s[0:1]
	s_cbranch_execz .LBB0_1052
	s_waitcnt lgkmcnt(0)
	v_add_f32_e32 v10, v8, v9
	v_lshl_add_u64 v[8:9], v[70:71], 2, s[58:59]
	global_store_dword v[8:9], v10, off sc1

.LBB0_1122:
	s_add_i32 s58, s67, 0xffffe000
	s_lshr_b32 s58, s58, 12
	s_mulk_i32 s58, 0x1800
	s_addk_i32 s58, 0x1800
	s_cmp_gt_i32 s6, 63
	s_cselect_b32 s62, s58, 0
	s_add_i32 s6, s62, 0x4800
	s_lshl_b64 s[58:59], s[6:7], 2
	s_add_u32 s6, s14, s58
	s_addc_u32 s58, s15, s59
	s_add_u32 s60, s6, 0x5ba5000
	s_addc_u32 s61, s58, 0
	s_add_i32 s6, s62, 0x9000
	s_lshl_b64 s[58:59], s[6:7], 2
	v_mov_b32_e32 v70, s66
	s_add_u32 s6, s14, s58
	ds_read_b64 v[70:71], v70
	s_addc_u32 s69, s15, s59
	s_lshl_b32 s58, s64, 14
	s_add_i32 s58, s58, 0x80000
	s_ashr_i32 s59, s58, 31
	s_lshl_b64 s[58:59], s[58:59], 2
	s_add_u32 s58, s10, s58
	s_waitcnt lgkmcnt(0)
	v_readfirstlane_b32 s63, v70
	s_addc_u32 s59, s11, s59
	v_or_b32_e32 v102, s68, v138
	v_add_u32_e32 v70, s67, v139
	v_readfirstlane_b32 s65, v71
	s_add_u32 s62, s63, 0x2000
	v_ashrrev_i32_e32 v103, 31, v102
	v_lshlrev_b32_e32 v191, 10, v70
	s_addc_u32 s63, s65, 0
	v_lshlrev_b64 v[72:73], 2, v[102:103]
	v_or_b32_e32 v187, 0x400, v191
	v_or_b32_e32 v186, 0x4400, v191
	v_or_b32_e32 v189, 0x4c00, v191
	v_or_b32_e32 v194, 0x6c00, v191
	s_add_u32 s64, s6, 0x5ba1000
	v_lshl_add_u64 v[74:75], s[60:61], 0, v[72:73]
	v_add_u32_e32 v130, v191, v102
	v_add_u32_e32 v132, v187, v102
	v_or_b32_e32 v185, 0x800, v191
	v_or_b32_e32 v184, 0xc00, v191
	v_or_b32_e32 v182, 0x2000, v191
	v_or_b32_e32 v180, 0x2400, v191
	v_or_b32_e32 v71, 0x2800, v191
	v_or_b32_e32 v181, 0x2c00, v191
	v_or_b32_e32 v183, 0x4000, v191
	v_add_u32_e32 v112, v186, v102
	v_or_b32_e32 v188, 0x4800, v191
	v_add_u32_e32 v116, v189, v102
	v_or_b32_e32 v190, 0x6000, v191
	v_or_b32_e32 v192, 0x6400, v191
	v_or_b32_e32 v193, 0x6800, v191
	v_add_u32_e32 v128, v194, v102
	s_addc_u32 s65, s69, 0
	global_load_dword v195, v[74:75], off
	global_load_dword v205, v[74:75], off offset:128
	global_load_dword v224, v[74:75], off offset:256
	v_lshl_add_u64 v[74:75], s[62:63], 0, v[72:73]
	v_ashrrev_i32_e32 v133, 31, v132
	v_add_u32_e32 v134, v185, v102
	v_add_u32_e32 v136, v184, v102
	v_add_u32_e32 v126, v182, v102
	v_add_u32_e32 v118, v180, v102
	v_add_u32_e32 v110, v71, v102
	v_add_u32_e32 v106, v181, v102
	v_add_u32_e32 v108, v183, v102
	v_ashrrev_i32_e32 v113, 31, v112
	v_add_u32_e32 v114, v188, v102
	v_ashrrev_i32_e32 v117, 31, v116
	v_add_u32_e32 v120, v190, v102
	v_add_u32_e32 v122, v192, v102
	v_add_u32_e32 v124, v193, v102
	v_ashrrev_i32_e32 v129, 31, v128
	v_ashrrev_i32_e32 v131, 31, v130
	v_lshl_add_u64 v[72:73], s[64:65], 0, v[72:73]
	global_load_dword v196, v[74:75], off
	global_load_dword v204, v[74:75], off offset:128
	global_load_dword v223, v[74:75], off offset:256
	global_load_dword v197, v[72:73], off
	global_load_dword v203, v[72:73], off offset:128
	global_load_dword v222, v[72:73], off offset:256
	v_lshl_add_u64 v[88:89], v[132:133], 2, s[12:13]
	v_ashrrev_i32_e32 v135, 31, v134
	v_ashrrev_i32_e32 v137, 31, v136
	v_ashrrev_i32_e32 v127, 31, v126
	v_ashrrev_i32_e32 v119, 31, v118
	v_ashrrev_i32_e32 v111, 31, v110
	v_ashrrev_i32_e32 v107, 31, v106
	v_ashrrev_i32_e32 v109, 31, v108
	v_lshl_add_u64 v[86:87], v[112:113], 2, s[12:13]
	v_ashrrev_i32_e32 v115, 31, v114
	v_lshl_add_u64 v[92:93], v[116:117], 2, s[12:13]
	v_ashrrev_i32_e32 v121, 31, v120
	v_ashrrev_i32_e32 v123, 31, v122
	v_ashrrev_i32_e32 v125, 31, v124
	v_lshl_add_u64 v[100:101], v[128:129], 2, s[12:13]
	v_lshl_add_u64 v[104:105], v[130:131], 2, s[12:13]
	v_lshl_add_u64 v[84:85], v[134:135], 2, s[12:13]
	v_lshl_add_u64 v[82:83], v[136:137], 2, s[12:13]
	v_lshl_add_u64 v[78:79], v[126:127], 2, s[12:13]
	v_lshl_add_u64 v[72:73], v[118:119], 2, s[12:13]
	v_lshl_add_u64 v[74:75], v[110:111], 2, s[12:13]
	v_lshl_add_u64 v[76:77], v[106:107], 2, s[12:13]
	v_lshl_add_u64 v[80:81], v[108:109], 2, s[12:13]
	global_load_dword v179, v[88:89], off
	global_load_dword v178, v[84:85], off
	global_load_dword v177, v[82:83], off
	global_load_dword v176, v[78:79], off
	global_load_dword v175, v[72:73], off
	global_load_dword v174, v[74:75], off
	global_load_dword v173, v[76:77], off
	global_load_dword v172, v[80:81], off
	v_lshl_add_u64 v[90:91], v[114:115], 2, s[12:13]
	global_load_dword v171, v[86:87], off
	global_load_dword v169, v[90:91], off
	v_lshl_add_u64 v[94:95], v[120:121], 2, s[12:13]
	v_lshl_add_u64 v[96:97], v[122:123], 2, s[12:13]
	v_lshl_add_u64 v[98:99], v[124:125], 2, s[12:13]
	global_load_dword v170, v[92:93], off
	global_load_dword v168, v[94:95], off
	global_load_dword v167, v[96:97], off
	global_load_dword v166, v[98:99], off
	global_load_dword v103, v[100:101], off
	global_load_dword v198, v[104:105], off
	v_lshl_add_u64 v[110:111], v[110:111], 1, s[8:9]
	v_lshl_add_u64 v[106:107], v[106:107], 1, s[8:9]
	global_load_dword v202, v[104:105], off offset:128
	global_load_dword v206, v[84:85], off offset:128
	global_load_dword v207, v[78:79], off offset:128
	global_load_dword v208, v[72:73], off offset:128
	global_load_dword v209, v[74:75], off offset:128
	global_load_dword v210, v[80:81], off offset:128
	global_load_dword v211, v[76:77], off offset:128
	global_load_dword v212, v[86:87], off offset:128
	global_load_dword v213, v[82:83], off offset:128
	global_load_dword v214, v[90:91], off offset:128
	global_load_dword v215, v[92:93], off offset:128
	global_load_dword v216, v[94:95], off offset:128
	global_load_dword v217, v[96:97], off offset:128
	global_load_dword v218, v[98:99], off offset:128
	global_load_dword v219, v[100:101], off offset:128
	global_load_dword v220, v[88:89], off offset:128
	global_load_dword v221, v[88:89], off offset:256
	global_load_dword v225, v[90:91], off offset:256
	global_load_dword v226, v[92:93], off offset:256
	global_load_dword v227, v[94:95], off offset:256
	global_load_dword v229, v[104:105], off offset:256
	global_load_dword v230, v[84:85], off offset:256
	global_load_dword v231, v[86:87], off offset:256
	global_load_dword v232, v[82:83], off offset:256
	global_load_dword v233, v[78:79], off offset:256
	global_load_dword v234, v[72:73], off offset:256
	global_load_dword v235, v[74:75], off offset:256
	global_load_dword v236, v[80:81], off offset:256
	global_load_dword v237, v[76:77], off offset:256
	global_load_dword v238, v[96:97], off offset:256
	global_load_dword v239, v[98:99], off offset:256
	global_load_dword v240, v[100:101], off offset:256
	s_waitcnt vmcnt(0)
	v_add_f32_e32 v197, 1.0, v197
	v_mul_f32_e32 v196, v196, v197
	v_fmac_f32_e32 v179, v49, v195
	v_fmac_f32_e32 v178, v50, v195
	v_fmac_f32_e32 v177, v51, v195
	v_fmac_f32_e32 v176, v52, v195
	v_fmac_f32_e32 v175, v53, v195
	v_fmac_f32_e32 v174, v54, v195
	v_fmac_f32_e32 v173, v55, v195
	v_fmac_f32_e32 v172, v56, v195
	v_fmac_f32_e32 v171, v57, v195
	v_fmac_f32_e32 v169, v58, v195
	v_fmac_f32_e32 v170, v59, v195
	v_fmac_f32_e32 v168, v60, v195
	v_fmac_f32_e32 v167, v61, v195
	v_fmac_f32_e32 v166, v62, v195
	v_fmac_f32_e32 v103, v63, v195
	v_fmac_f32_e32 v198, v48, v195
	v_mul_f32_e32 v48, v196, v198
	v_cvt_pk_bf16_f32 v58, v48, s0
	v_or_b32_e32 v48, 32, v102
	v_ashrrev_i32_e32 v49, 31, v48
	v_lshlrev_b64 v[52:53], 2, v[48:49]
	global_store_dword v[88:89], v179, off sc1
	global_store_dword v[84:85], v178, off sc1
	global_store_dword v[82:83], v177, off sc1
	global_store_dword v[78:79], v176, off sc1
	global_store_dword v[72:73], v175, off sc1
	global_store_dword v[74:75], v174, off sc1
	global_store_dword v[76:77], v173, off sc1
	global_store_dword v[80:81], v172, off sc1
	global_store_dword v[86:87], v171, off sc1
	global_store_dword v[90:91], v169, off sc1
	global_store_dword v[92:93], v170, off sc1
	global_store_dword v[94:95], v168, off sc1
	global_store_dword v[96:97], v167, off sc1
	global_store_dword v[98:99], v166, off sc1
	global_store_dword v[100:101], v103, off sc1
	global_store_dword v[104:105], v198, off sc1
	v_lshl_add_u64 v[50:51], v[130:131], 1, s[8:9]
	v_lshl_add_u64 v[56:57], s[64:65], 0, v[52:53]
	v_mov_b32_e32 v197, v202
	v_lshl_add_u64 v[54:55], s[62:63], 0, v[52:53]
	v_mov_b32_e32 v130, v203
	v_mov_b32_e32 v131, v204
	v_mul_f32_e32 v49, v196, v179
	global_store_short v[50:51], v58, off sc1
	v_lshl_add_u64 v[50:51], s[60:61], 0, v[52:53]
	v_mov_b32_e32 v195, v205
	v_lshl_add_u64 v[50:51], v[132:133], 1, s[8:9]
	v_cvt_pk_bf16_f32 v49, v49, s0
	global_store_short v[50:51], v49, off sc1
	v_mul_f32_e32 v49, v196, v178
	v_lshl_add_u64 v[50:51], v[134:135], 1, s[8:9]
	v_cvt_pk_bf16_f32 v49, v49, s0
	global_store_short v[50:51], v49, off sc1
	v_mul_f32_e32 v49, v196, v177
	v_lshl_add_u64 v[50:51], v[136:137], 1, s[8:9]
	v_cvt_pk_bf16_f32 v49, v49, s0
	global_store_short v[50:51], v49, off sc1
	v_mul_f32_e32 v49, v196, v176
	v_lshl_add_u64 v[50:51], v[126:127], 1, s[8:9]
	v_cvt_pk_bf16_f32 v49, v49, s0
	global_store_short v[50:51], v49, off sc1
	v_mul_f32_e32 v49, v196, v175
	v_lshl_add_u64 v[50:51], v[118:119], 1, s[8:9]
	v_cvt_pk_bf16_f32 v49, v49, s0
	v_mov_b32_e32 v62, v206
	v_mov_b32_e32 v60, v207
	v_mov_b32_e32 v59, v208
	v_mov_b32_e32 v58, v209
	v_mov_b32_e32 v56, v210
	v_mov_b32_e32 v57, v211
	v_mov_b32_e32 v55, v212
	v_mov_b32_e32 v61, v213
	v_mov_b32_e32 v54, v214
	v_mov_b32_e32 v53, v215
	v_mov_b32_e32 v52, v216
	v_mul_f32_e32 v63, v196, v174
	global_store_short v[50:51], v49, off sc1
	v_mov_b32_e32 v51, v217
	v_cvt_pk_bf16_f32 v63, v63, s0
	v_mov_b32_e32 v50, v218
	v_mov_b32_e32 v49, v219
	v_fmac_f32_e32 v197, v32, v195
	global_store_short v[110:111], v63, off sc1
	v_mov_b32_e32 v63, v220
	v_mul_f32_e32 v110, v196, v173
	v_cvt_pk_bf16_f32 v110, v110, s0
	global_store_short v[106:107], v110, off sc1
	v_lshl_add_u64 v[106:107], v[108:109], 1, s[8:9]
	v_mul_f32_e32 v108, v196, v172
	v_cvt_pk_bf16_f32 v108, v108, s0
	global_store_short v[106:107], v108, off sc1
	v_mul_f32_e32 v108, v196, v171
	v_lshl_add_u64 v[106:107], v[112:113], 1, s[8:9]
	v_cvt_pk_bf16_f32 v108, v108, s0
	global_store_short v[106:107], v108, off sc1
	v_mul_f32_e32 v108, v196, v169
	v_lshl_add_u64 v[106:107], v[114:115], 1, s[8:9]
	v_cvt_pk_bf16_f32 v108, v108, s0
	global_store_short v[106:107], v108, off sc1
	v_mul_f32_e32 v108, v196, v170
	v_lshl_add_u64 v[106:107], v[116:117], 1, s[8:9]
	v_cvt_pk_bf16_f32 v108, v108, s0
	global_store_short v[106:107], v108, off sc1
	v_mul_f32_e32 v108, v196, v168
	v_lshl_add_u64 v[106:107], v[120:121], 1, s[8:9]
	v_cvt_pk_bf16_f32 v108, v108, s0
	global_store_short v[106:107], v108, off sc1
	v_mul_f32_e32 v108, v196, v167
	v_lshl_add_u64 v[106:107], v[122:123], 1, s[8:9]
	v_cvt_pk_bf16_f32 v108, v108, s0
	global_store_short v[106:107], v108, off sc1
	v_mul_f32_e32 v108, v196, v166
	v_lshl_add_u64 v[106:107], v[124:125], 1, s[8:9]
	v_cvt_pk_bf16_f32 v108, v108, s0
	global_store_short v[106:107], v108, off sc1
	v_mul_f32_e32 v108, v196, v103
	v_lshl_add_u64 v[106:107], v[128:129], 1, s[8:9]
	v_cvt_pk_bf16_f32 v108, v108, s0
	global_store_short v[106:107], v108, off sc1
	v_add_f32_e32 v106, 1.0, v130
	v_mul_f32_e32 v107, v131, v106
	v_add_u32_e32 v108, v191, v48
	v_ashrrev_i32_e32 v109, 31, v108
	v_mul_f32_e32 v32, v107, v197
	v_fmac_f32_e32 v62, v34, v195
	v_fmac_f32_e32 v61, v35, v195
	v_fmac_f32_e32 v60, v36, v195
	v_fmac_f32_e32 v59, v37, v195
	v_fmac_f32_e32 v58, v38, v195
	v_fmac_f32_e32 v57, v39, v195
	v_fmac_f32_e32 v56, v40, v195
	v_fmac_f32_e32 v55, v41, v195
	v_fmac_f32_e32 v54, v42, v195
	v_fmac_f32_e32 v53, v43, v195
	v_fmac_f32_e32 v52, v44, v195
	v_fmac_f32_e32 v51, v45, v195
	v_fmac_f32_e32 v50, v46, v195
	v_fmac_f32_e32 v49, v47, v195
	global_store_dword v[104:105], v197, off offset:128 sc1
	v_lshl_add_u64 v[108:109], v[108:109], 1, s[8:9]
	v_cvt_pk_bf16_f32 v32, v32, s0
	global_store_dword v[84:85], v62, off offset:128 sc1
	global_store_dword v[82:83], v61, off offset:128 sc1
	global_store_dword v[78:79], v60, off offset:128 sc1
	global_store_dword v[72:73], v59, off offset:128 sc1
	global_store_dword v[74:75], v58, off offset:128 sc1
	global_store_dword v[76:77], v57, off offset:128 sc1
	global_store_dword v[80:81], v56, off offset:128 sc1
	global_store_dword v[86:87], v55, off offset:128 sc1
	global_store_dword v[90:91], v54, off offset:128 sc1
	global_store_dword v[92:93], v53, off offset:128 sc1
	global_store_dword v[94:95], v52, off offset:128 sc1
	global_store_dword v[96:97], v51, off offset:128 sc1
	global_store_dword v[98:99], v50, off offset:128 sc1
	global_store_dword v[100:101], v49, off offset:128 sc1
	global_store_short v[108:109], v32, off sc1
	v_add_u32_e32 v108, v187, v48
	v_mov_b32_e32 v45, v221
	v_ashrrev_i32_e32 v109, 31, v108
	v_mul_f32_e32 v113, v107, v56
	v_cvt_pk_bf16_f32 v113, v113, s0
	v_mul_f32_e32 v106, v197, v197
	v_fmac_f32_e32 v106, v198, v198
	v_fmac_f32_e32 v63, v33, v195
	v_mul_f32_e32 v34, v107, v63
	v_lshl_add_u64 v[32:33], v[108:109], 1, s[8:9]
	v_cvt_pk_bf16_f32 v34, v34, s0
	global_store_short v[32:33], v34, off sc1
	v_add_u32_e32 v32, v185, v48
	v_ashrrev_i32_e32 v33, 31, v32
	v_mul_f32_e32 v34, v107, v62
	v_lshl_add_u64 v[32:33], v[32:33], 1, s[8:9]
	v_cvt_pk_bf16_f32 v34, v34, s0
	global_store_short v[32:33], v34, off sc1
	v_add_u32_e32 v32, v184, v48
	v_ashrrev_i32_e32 v33, 31, v32
	v_mul_f32_e32 v34, v107, v61
	v_lshl_add_u64 v[32:33], v[32:33], 1, s[8:9]
	v_cvt_pk_bf16_f32 v34, v34, s0
	global_store_short v[32:33], v34, off sc1
	v_add_u32_e32 v32, v182, v48
	v_ashrrev_i32_e32 v33, 31, v32
	v_mul_f32_e32 v34, v107, v60
	v_lshl_add_u64 v[32:33], v[32:33], 1, s[8:9]
	v_cvt_pk_bf16_f32 v34, v34, s0
	global_store_short v[32:33], v34, off sc1
	v_add_u32_e32 v32, v180, v48
	v_ashrrev_i32_e32 v33, 31, v32
	v_lshl_add_u64 v[34:35], v[32:33], 1, s[8:9]
	v_mul_f32_e32 v32, v107, v59
	v_cvt_pk_bf16_f32 v42, v32, s0
	v_or_b32_e32 v32, 64, v102
	v_ashrrev_i32_e32 v33, 31, v32
	v_lshlrev_b64 v[36:37], 2, v[32:33]
	global_store_dword v[88:89], v63, off offset:128 sc1
	v_lshl_add_u64 v[40:41], s[64:65], 0, v[36:37]
	v_lshl_add_u64 v[38:39], s[62:63], 0, v[36:37]
	v_mov_b32_e32 v110, v222
	v_mov_b32_e32 v111, v223
	v_mul_f32_e32 v33, v107, v58
	global_store_short v[34:35], v42, off sc1
	v_lshl_add_u64 v[34:35], s[60:61], 0, v[36:37]
	v_mov_b32_e32 v112, v224
	v_add_u32_e32 v34, v71, v48
	v_ashrrev_i32_e32 v35, 31, v34
	v_lshl_add_u64 v[34:35], v[34:35], 1, s[8:9]
	v_cvt_pk_bf16_f32 v33, v33, s0
	global_store_short v[34:35], v33, off sc1
	v_add_u32_e32 v34, v181, v48
	v_ashrrev_i32_e32 v35, 31, v34
	v_mul_f32_e32 v33, v107, v57
	v_lshl_add_u64 v[34:35], v[34:35], 1, s[8:9]
	v_cvt_pk_bf16_f32 v33, v33, s0
	v_mov_b32_e32 v38, v225
	v_mov_b32_e32 v37, v226
	v_mov_b32_e32 v36, v227
	v_mov_b32_e32 v114, v229
	v_mov_b32_e32 v47, v230
	v_mov_b32_e32 v39, v231
	v_mov_b32_e32 v46, v232
	v_mov_b32_e32 v44, v233
	v_mov_b32_e32 v43, v234
	v_mov_b32_e32 v42, v235
	v_mov_b32_e32 v40, v236
	v_mov_b32_e32 v41, v237
	v_add_u32_e32 v108, v183, v48
	global_store_short v[34:35], v33, off sc1
	v_mov_b32_e32 v35, v238
	v_ashrrev_i32_e32 v109, 31, v108
	v_mov_b32_e32 v34, v239
	v_mov_b32_e32 v33, v240
	v_lshl_add_u64 v[108:109], v[108:109], 1, s[8:9]
	global_store_short v[108:109], v113, off sc1
	v_add_u32_e32 v108, v186, v48
	v_ashrrev_i32_e32 v109, 31, v108
	v_mul_f32_e32 v113, v107, v55
	v_lshl_add_u64 v[108:109], v[108:109], 1, s[8:9]
	v_cvt_pk_bf16_f32 v113, v113, s0
	global_store_short v[108:109], v113, off sc1
	v_add_u32_e32 v108, v188, v48
	v_ashrrev_i32_e32 v109, 31, v108
	v_mul_f32_e32 v113, v107, v54
	v_lshl_add_u64 v[108:109], v[108:109], 1, s[8:9]
	v_cvt_pk_bf16_f32 v113, v113, s0
	global_store_short v[108:109], v113, off sc1
	v_add_u32_e32 v108, v189, v48
	v_ashrrev_i32_e32 v109, 31, v108
	v_mul_f32_e32 v113, v107, v53
	v_lshl_add_u64 v[108:109], v[108:109], 1, s[8:9]
	v_cvt_pk_bf16_f32 v113, v113, s0
	global_store_short v[108:109], v113, off sc1
	v_add_u32_e32 v108, v190, v48
	v_ashrrev_i32_e32 v109, 31, v108
	v_mul_f32_e32 v113, v107, v52
	v_lshl_add_u64 v[108:109], v[108:109], 1, s[8:9]
	v_cvt_pk_bf16_f32 v113, v113, s0
	global_store_short v[108:109], v113, off sc1
	v_add_u32_e32 v108, v192, v48
	v_ashrrev_i32_e32 v109, 31, v108
	v_mul_f32_e32 v113, v107, v51
	v_lshl_add_u64 v[108:109], v[108:109], 1, s[8:9]
	v_cvt_pk_bf16_f32 v113, v113, s0
	global_store_short v[108:109], v113, off sc1
	v_add_u32_e32 v108, v193, v48
	v_ashrrev_i32_e32 v109, 31, v108
	v_mul_f32_e32 v113, v107, v50
	v_lshl_add_u64 v[108:109], v[108:109], 1, s[8:9]
	v_cvt_pk_bf16_f32 v113, v113, s0
	global_store_short v[108:109], v113, off sc1
	v_add_u32_e32 v108, v194, v48
	v_ashrrev_i32_e32 v109, 31, v108
	v_mul_f32_e32 v48, v107, v49
	v_lshl_add_u64 v[108:109], v[108:109], 1, s[8:9]
	v_cvt_pk_bf16_f32 v48, v48, s0
	global_store_short v[108:109], v48, off sc1
	v_add_u32_e32 v108, v191, v32
	v_ashrrev_i32_e32 v109, 31, v108
	v_add_f32_e32 v48, 1.0, v110
	v_mul_f32_e32 v48, v111, v48
	v_fmac_f32_e32 v45, v17, v112
	global_store_dword v[88:89], v45, off offset:256 sc1
	v_fmac_f32_e32 v38, v26, v112
	v_fmac_f32_e32 v37, v27, v112
	v_fmac_f32_e32 v36, v28, v112
	v_fmac_f32_e32 v114, v16, v112
	v_fmac_f32_e32 v47, v18, v112
	v_mul_f32_e32 v18, v48, v114
	v_lshl_add_u64 v[16:17], v[108:109], 1, s[8:9]
	v_cvt_pk_bf16_f32 v18, v18, s0
	global_store_short v[16:17], v18, off sc1
	v_add_u32_e32 v16, v187, v32
	v_ashrrev_i32_e32 v17, 31, v16
	v_mul_f32_e32 v18, v48, v45
	v_lshl_add_u64 v[16:17], v[16:17], 1, s[8:9]
	v_cvt_pk_bf16_f32 v18, v18, s0
	global_store_short v[16:17], v18, off sc1
	v_add_u32_e32 v16, v185, v32
	v_ashrrev_i32_e32 v17, 31, v16
	v_mul_f32_e32 v18, v48, v47
	v_lshl_add_u64 v[16:17], v[16:17], 1, s[8:9]
	v_cvt_pk_bf16_f32 v18, v18, s0
	v_fmac_f32_e32 v46, v19, v112
	global_store_short v[16:17], v18, off sc1
	v_add_u32_e32 v16, v184, v32
	v_ashrrev_i32_e32 v17, 31, v16
	v_mul_f32_e32 v18, v48, v46
	v_lshl_add_u64 v[16:17], v[16:17], 1, s[8:9]
	v_cvt_pk_bf16_f32 v18, v18, s0
	global_store_short v[16:17], v18, off sc1
	v_add_u32_e32 v16, v182, v32
	v_ashrrev_i32_e32 v17, 31, v16
	v_lshl_add_u64 v[18:19], v[16:17], 1, s[8:9]
	v_or_b32_e32 v16, 0x60, v102
	v_ashrrev_i32_e32 v17, 31, v16
	v_fmac_f32_e32 v44, v20, v112
	v_fmac_f32_e32 v43, v21, v112
	v_fmac_f32_e32 v42, v22, v112
	v_fmac_f32_e32 v41, v23, v112
	v_fmac_f32_e32 v40, v24, v112
	v_fmac_f32_e32 v39, v25, v112
	v_fmac_f32_e32 v35, v29, v112
	v_fmac_f32_e32 v34, v30, v112
	v_fmac_f32_e32 v33, v31, v112
	v_lshlrev_b64 v[20:21], 2, v[16:17]
	global_store_dword v[84:85], v47, off offset:256 sc1
	global_store_dword v[82:83], v46, off offset:256 sc1
	global_store_dword v[78:79], v44, off offset:256 sc1
	global_store_dword v[72:73], v43, off offset:256 sc1
	global_store_dword v[74:75], v42, off offset:256 sc1
	global_store_dword v[76:77], v41, off offset:256 sc1
	global_store_dword v[80:81], v40, off offset:256 sc1
	global_store_dword v[86:87], v39, off offset:256 sc1
	global_store_dword v[90:91], v38, off offset:256 sc1
	global_store_dword v[92:93], v37, off offset:256 sc1
	global_store_dword v[94:95], v36, off offset:256 sc1
	global_store_dword v[96:97], v35, off offset:256 sc1
	global_store_dword v[98:99], v34, off offset:256 sc1
	global_store_dword v[100:101], v33, off offset:256 sc1
	global_store_dword v[104:105], v114, off offset:256 sc1
	v_mul_f32_e32 v26, v48, v44
	v_lshl_add_u64 v[22:23], s[62:63], 0, v[20:21]
	v_lshl_add_u64 v[24:25], s[64:65], 0, v[20:21]
	global_load_dword v29, v[104:105], off offset:384
	global_load_dword v17, v[24:25], off
	global_load_dword v30, v[22:23], off
	v_cvt_pk_bf16_f32 v22, v26, s0
	global_store_short v[18:19], v22, off sc1
	v_lshl_add_u64 v[18:19], s[60:61], 0, v[20:21]
	global_load_dword v102, v[18:19], off
	v_add_u32_e32 v18, v180, v32
	v_ashrrev_i32_e32 v19, 31, v18
	v_mul_f32_e32 v20, v48, v43
	v_lshl_add_u64 v[18:19], v[18:19], 1, s[8:9]
	v_cvt_pk_bf16_f32 v20, v20, s0
	global_store_short v[18:19], v20, off sc1
	v_add_u32_e32 v18, v71, v32
	v_ashrrev_i32_e32 v19, 31, v18
	v_mul_f32_e32 v20, v48, v42
	v_lshl_add_u64 v[18:19], v[18:19], 1, s[8:9]
	v_cvt_pk_bf16_f32 v20, v20, s0
	global_store_short v[18:19], v20, off sc1
	v_add_u32_e32 v18, v181, v32
	v_ashrrev_i32_e32 v19, 31, v18
	v_mul_f32_e32 v20, v48, v41
	v_lshl_add_u64 v[18:19], v[18:19], 1, s[8:9]
	v_cvt_pk_bf16_f32 v20, v20, s0
	global_store_short v[18:19], v20, off sc1
	v_add_u32_e32 v18, v183, v32
	v_ashrrev_i32_e32 v19, 31, v18
	v_mul_f32_e32 v20, v48, v40
	v_lshl_add_u64 v[18:19], v[18:19], 1, s[8:9]
	v_cvt_pk_bf16_f32 v20, v20, s0
	global_store_short v[18:19], v20, off sc1
	v_add_u32_e32 v18, v186, v32
	v_ashrrev_i32_e32 v19, 31, v18
	v_mul_f32_e32 v20, v48, v39
	v_lshl_add_u64 v[18:19], v[18:19], 1, s[8:9]
	v_cvt_pk_bf16_f32 v20, v20, s0
	global_store_short v[18:19], v20, off sc1
	v_add_u32_e32 v18, v188, v32
	v_ashrrev_i32_e32 v19, 31, v18
	v_mul_f32_e32 v20, v48, v38
	v_lshl_add_u64 v[18:19], v[18:19], 1, s[8:9]
	v_cvt_pk_bf16_f32 v20, v20, s0
	global_store_short v[18:19], v20, off sc1
	v_add_u32_e32 v18, v189, v32
	v_ashrrev_i32_e32 v19, 31, v18
	v_mul_f32_e32 v20, v48, v37
	v_lshl_add_u64 v[18:19], v[18:19], 1, s[8:9]
	v_cvt_pk_bf16_f32 v20, v20, s0
	global_store_short v[18:19], v20, off sc1
	v_add_u32_e32 v18, v190, v32
	v_ashrrev_i32_e32 v19, 31, v18
	v_mul_f32_e32 v20, v48, v36
	v_lshl_add_u64 v[18:19], v[18:19], 1, s[8:9]
	v_cvt_pk_bf16_f32 v20, v20, s0
	global_store_short v[18:19], v20, off sc1
	v_add_u32_e32 v18, v192, v32
	v_ashrrev_i32_e32 v19, 31, v18
	v_mul_f32_e32 v20, v48, v35
	v_lshl_add_u64 v[18:19], v[18:19], 1, s[8:9]
	v_cvt_pk_bf16_f32 v20, v20, s0
	global_load_dword v28, v[88:89], off offset:384
	global_load_dword v27, v[84:85], off offset:384
	global_load_dword v25, v[78:79], off offset:384
	global_load_dword v24, v[72:73], off offset:384
	global_load_dword v23, v[74:75], off offset:384
	global_load_dword v21, v[80:81], off offset:384
	global_load_dword v22, v[76:77], off offset:384
	v_fmac_f32_e32 v106, v114, v114
	global_store_short v[18:19], v20, off sc1
	v_add_u32_e32 v18, v193, v32
	v_ashrrev_i32_e32 v19, 31, v18
	v_mul_f32_e32 v20, v48, v34
	v_lshl_add_u64 v[18:19], v[18:19], 1, s[8:9]
	v_cvt_pk_bf16_f32 v20, v20, s0
	global_store_short v[18:19], v20, off sc1
	v_add_u32_e32 v18, v194, v32
	v_ashrrev_i32_e32 v19, 31, v18
	v_mul_f32_e32 v20, v48, v33
	v_lshl_add_u64 v[18:19], v[18:19], 1, s[8:9]
	v_cvt_pk_bf16_f32 v20, v20, s0
	global_store_short v[18:19], v20, off sc1
	global_load_dword v20, v[86:87], off offset:384
	s_waitcnt vmcnt(22)
	v_add_f32_e32 v17, 1.0, v17
	global_load_dword v26, v[82:83], off offset:384
	s_waitcnt vmcnt(22)
	v_mul_f32_e32 v32, v30, v17
	v_add_u32_e32 v18, v191, v16
	s_waitcnt vmcnt(20)
	v_fmac_f32_e32 v29, v0, v102
	v_ashrrev_i32_e32 v19, 31, v18
	v_mul_f32_e32 v0, v32, v29
	v_lshl_add_u64 v[18:19], v[18:19], 1, s[8:9]
	v_cvt_pk_bf16_f32 v0, v0, s0
	global_store_short v[18:19], v0, off sc1
	global_load_dword v19, v[90:91], off offset:384
	v_add_u32_e32 v30, v187, v16
	global_load_dword v18, v[92:93], off offset:384
	v_ashrrev_i32_e32 v31, 31, v30
	v_fmac_f32_e32 v106, v29, v29
	global_store_dword v[104:105], v29, off offset:384 sc1
	s_waitcnt vmcnt(15)
	v_fmac_f32_e32 v28, v1, v102
	v_mul_f32_e32 v17, v32, v28
	v_lshl_add_u64 v[0:1], v[30:31], 1, s[8:9]
	v_cvt_pk_bf16_f32 v17, v17, s0
	global_store_short v[0:1], v17, off sc1
	v_add_u32_e32 v0, v185, v16
	s_waitcnt vmcnt(15)
	v_fmac_f32_e32 v27, v2, v102
	global_load_dword v17, v[94:95], off offset:384
	v_ashrrev_i32_e32 v1, 31, v0
	v_mul_f32_e32 v2, v32, v27
	v_lshl_add_u64 v[0:1], v[0:1], 1, s[8:9]
	v_cvt_pk_bf16_f32 v2, v2, s0
	global_store_short v[0:1], v2, off sc1
	v_add_u32_e32 v0, v184, v16
	global_load_dword v2, v[96:97], off offset:384
	v_ashrrev_i32_e32 v1, 31, v0
	v_lshl_add_u64 v[0:1], v[0:1], 1, s[8:9]
	v_add_u32_e32 v30, v182, v16
	s_waitcnt vmcnt(17)
	v_fmac_f32_e32 v25, v4, v102
	v_ashrrev_i32_e32 v31, 31, v30
	v_lshl_add_u64 v[30:31], v[30:31], 1, s[8:9]
	s_waitcnt vmcnt(16)
	v_fmac_f32_e32 v24, v5, v102
	s_waitcnt vmcnt(15)
	v_fmac_f32_e32 v23, v6, v102
	s_waitcnt vmcnt(8)
	v_fmac_f32_e32 v26, v3, v102
	v_mul_f32_e32 v3, v32, v26
	v_cvt_pk_bf16_f32 v3, v3, s0
	global_store_short v[0:1], v3, off sc1
	global_load_dword v1, v[98:99], off offset:384
	v_mul_f32_e32 v0, v32, v25
	v_cvt_pk_bf16_f32 v0, v0, s0
	global_store_short v[30:31], v0, off sc1
	global_load_dword v0, v[100:101], off offset:384
	v_add_u32_e32 v30, v180, v16
	v_ashrrev_i32_e32 v31, 31, v30
	v_mul_f32_e32 v3, v32, v24
	v_lshl_add_u64 v[4:5], v[30:31], 1, s[8:9]
	v_cvt_pk_bf16_f32 v3, v3, s0
	global_store_short v[4:5], v3, off sc1
	v_add_u32_e32 v4, v71, v16
	v_ashrrev_i32_e32 v5, 31, v4
	v_mul_f32_e32 v3, v32, v23
	v_lshl_add_u64 v[4:5], v[4:5], 1, s[8:9]
	v_cvt_pk_bf16_f32 v3, v3, s0
	global_store_short v[4:5], v3, off sc1
	v_add_u32_e32 v4, v181, v16
	v_fmac_f32_e32 v22, v7, v102
	v_ashrrev_i32_e32 v5, 31, v4
	v_mul_f32_e32 v3, v32, v22
	v_lshl_add_u64 v[4:5], v[4:5], 1, s[8:9]
	v_cvt_pk_bf16_f32 v3, v3, s0
	global_store_short v[4:5], v3, off sc1
	v_add_u32_e32 v4, v183, v16
	v_fmac_f32_e32 v21, v8, v102
	v_ashrrev_i32_e32 v5, 31, v4
	v_mul_f32_e32 v3, v32, v21
	v_lshl_add_u64 v[4:5], v[4:5], 1, s[8:9]
	v_cvt_pk_bf16_f32 v3, v3, s0
	global_store_short v[4:5], v3, off sc1
	v_add_u32_e32 v4, v186, v16
	v_fmac_f32_e32 v20, v9, v102
	v_ashrrev_i32_e32 v5, 31, v4
	v_mul_f32_e32 v3, v32, v20
	v_lshl_add_u64 v[4:5], v[4:5], 1, s[8:9]
	v_cvt_pk_bf16_f32 v3, v3, s0
	global_store_short v[4:5], v3, off sc1
	v_add_u32_e32 v4, v188, v16
	s_waitcnt vmcnt(15)
	v_fmac_f32_e32 v19, v10, v102
	v_ashrrev_i32_e32 v5, 31, v4
	v_mul_f32_e32 v3, v32, v19
	v_lshl_add_u64 v[4:5], v[4:5], 1, s[8:9]
	v_cvt_pk_bf16_f32 v3, v3, s0
	global_store_short v[4:5], v3, off sc1
	v_add_u32_e32 v4, v189, v16
	s_waitcnt vmcnt(15)
	v_fmac_f32_e32 v18, v11, v102
	v_ashrrev_i32_e32 v5, 31, v4
	v_mul_f32_e32 v3, v32, v18
	v_lshl_add_u64 v[4:5], v[4:5], 1, s[8:9]
	v_cvt_pk_bf16_f32 v3, v3, s0
	global_store_short v[4:5], v3, off sc1
	v_add_u32_e32 v4, v190, v16
	v_ashrrev_i32_e32 v5, 31, v4
	v_lshl_add_u64 v[4:5], v[4:5], 1, s[8:9]
	v_ashrrev_i32_e32 v71, 31, v70
	global_store_dword v[88:89], v28, off offset:384 sc1
	global_store_dword v[84:85], v27, off offset:384 sc1
	global_store_dword v[82:83], v26, off offset:384 sc1
	global_store_dword v[78:79], v25, off offset:384 sc1
	s_waitcnt vmcnt(17)
	v_fmac_f32_e32 v17, v12, v102
	v_mul_f32_e32 v3, v32, v17
	v_cvt_pk_bf16_f32 v3, v3, s0
	global_store_short v[4:5], v3, off sc1
	v_add_u32_e32 v4, v192, v16
	v_ashrrev_i32_e32 v5, 31, v4
	v_lshl_add_u64 v[4:5], v[4:5], 1, s[8:9]
	s_waitcnt vmcnt(16)
	v_fmac_f32_e32 v2, v13, v102
	v_mul_f32_e32 v3, v32, v2
	v_cvt_pk_bf16_f32 v3, v3, s0
	global_store_short v[4:5], v3, off sc1
	v_add_u32_e32 v4, v193, v16
	v_ashrrev_i32_e32 v5, 31, v4
	v_lshl_add_u64 v[4:5], v[4:5], 1, s[8:9]
	v_xor_b32_e32 v12, 16, v165
	global_store_dword v[72:73], v24, off offset:384 sc1
	global_store_dword v[74:75], v23, off offset:384 sc1
	global_store_dword v[76:77], v22, off offset:384 sc1
	global_store_dword v[80:81], v21, off offset:384 sc1
	global_store_dword v[86:87], v20, off offset:384 sc1
	s_waitcnt vmcnt(20)
	v_fmac_f32_e32 v1, v14, v102
	v_mul_f32_e32 v3, v32, v1
	v_cvt_pk_bf16_f32 v3, v3, s0
	global_store_short v[4:5], v3, off sc1
	v_add_u32_e32 v4, v194, v16
	v_ashrrev_i32_e32 v5, 31, v4
	v_lshl_add_u64 v[10:11], v[4:5], 1, s[8:9]
	v_and_b32_e32 v4, 64, v165
	v_xor_b32_e32 v3, 1, v165
	v_add_u32_e32 v7, 64, v4
	v_cmp_lt_i32_e32 vcc, v3, v7
	v_xor_b32_e32 v4, 2, v165
	s_waitcnt vmcnt(19)
	v_fmac_f32_e32 v0, v15, v102
	v_cndmask_b32_e32 v3, v165, v3, vcc
	v_lshlrev_b32_e32 v3, 2, v3
	ds_bpermute_b32 v5, v3, v106
	v_cmp_lt_i32_e32 vcc, v4, v7
	global_store_dword v[90:91], v19, off offset:384 sc1
	global_store_dword v[92:93], v18, off offset:384 sc1
	v_cndmask_b32_e32 v4, v165, v4, vcc
	v_lshlrev_b32_e32 v4, 2, v4
	s_waitcnt lgkmcnt(0)
	v_add_f32_e32 v6, v106, v5
	ds_bpermute_b32 v8, v4, v6
	v_xor_b32_e32 v5, 4, v165
	v_cmp_lt_i32_e32 vcc, v5, v7
	global_store_dword v[94:95], v17, off offset:384 sc1
	global_store_dword v[96:97], v2, off offset:384 sc1
	v_cndmask_b32_e32 v5, v165, v5, vcc
	v_lshlrev_b32_e32 v5, 2, v5
	s_waitcnt lgkmcnt(0)
	v_add_f32_e32 v8, v6, v8
	ds_bpermute_b32 v9, v5, v8
	v_xor_b32_e32 v6, 8, v165
	v_cmp_lt_i32_e32 vcc, v6, v7
	global_store_dword v[98:99], v1, off offset:384 sc1
	global_store_dword v[100:101], v0, off offset:384 sc1
	v_cndmask_b32_e32 v6, v165, v6, vcc
	v_lshlrev_b32_e32 v6, 2, v6
	s_waitcnt lgkmcnt(0)
	v_add_f32_e32 v8, v8, v9
	ds_bpermute_b32 v9, v6, v8
	v_cmp_lt_i32_e32 vcc, v12, v7
	s_waitcnt lgkmcnt(0)
	v_add_f32_e32 v8, v8, v9
	v_cndmask_b32_e32 v7, v165, v12, vcc
	v_lshlrev_b32_e32 v7, 2, v7
	ds_bpermute_b32 v9, v7, v8
	v_mul_f32_e32 v12, v32, v0
	v_cvt_pk_bf16_f32 v12, v12, s0
	global_store_short v[10:11], v12, off sc1
	s_and_saveexec_b64 s[60:61], s[0:1]
	s_cbranch_execz .LBB0_1124
	s_waitcnt lgkmcnt(0)
	v_add_f32_e32 v10, v8, v9
	v_lshl_add_u64 v[8:9], v[70:71], 2, s[58:59]
	global_store_dword v[8:9], v10, off sc1

.LBB0_1326:
	s_add_i32 s58, s66, 0xffffe000
	s_lshr_b32 s58, s58, 12
	s_mulk_i32 s58, 0x1800
	v_mov_b32_e32 v70, s70
	s_add_i32 s58, s58, 0xa800
	ds_read_b64 v[70:71], v70
	s_cmp_gt_i32 s6, 63
	s_cselect_b32 s6, s58, 0x9000
	s_lshl_b64 s[58:59], s[6:7], 2
	s_add_u32 s6, s14, s58
	s_addc_u32 s65, s15, s59
	s_waitcnt lgkmcnt(0)
	v_readfirstlane_b32 s58, v70
	v_readfirstlane_b32 s59, v71
	s_add_u32 s60, s58, 0x2000
	s_addc_u32 s61, s59, 0
	s_lshl_b32 s58, s64, 14
	s_add_i32 s58, s58, 0xa0000
	s_ashr_i32 s59, s58, 31
	s_lshl_b64 s[58:59], s[58:59], 2
	s_add_u32 s58, s10, s58
	s_addc_u32 s59, s11, s59
	s_add_u32 s62, s6, 0x5ba2000
	v_or_b32_e32 v102, s68, v138
	v_add_u32_e32 v70, s66, v139
	s_addc_u32 s63, s65, 0
	v_lshlrev_b32_e32 v188, 10, v70
	v_ashrrev_i32_e32 v103, 31, v102
	s_add_u32 s64, s6, 0x5ba4000
	v_lshlrev_b64 v[72:73], 2, v[102:103]
	v_or_b32_e32 v186, 0x400, v188
	v_or_b32_e32 v185, 0x4400, v188
	v_or_b32_e32 v189, 0x4c00, v188
	v_or_b32_e32 v193, 0x6c00, v188
	s_addc_u32 s65, s65, 0
	v_lshl_add_u64 v[74:75], s[62:63], 0, v[72:73]
	v_add_u32_e32 v132, v188, v102
	v_add_u32_e32 v134, v186, v102
	v_or_b32_e32 v184, 0x800, v188
	v_or_b32_e32 v183, 0xc00, v188
	v_or_b32_e32 v181, 0x2000, v188
	v_or_b32_e32 v179, 0x2400, v188
	v_or_b32_e32 v71, 0x2800, v188
	v_or_b32_e32 v180, 0x2c00, v188
	v_or_b32_e32 v182, 0x4000, v188
	v_add_u32_e32 v112, v185, v102
	v_or_b32_e32 v187, 0x4800, v188
	v_add_u32_e32 v118, v189, v102
	v_or_b32_e32 v190, 0x6000, v188
	v_or_b32_e32 v191, 0x6400, v188
	v_or_b32_e32 v192, 0x6800, v188
	v_add_u32_e32 v128, v193, v102
	global_load_dword v194, v[74:75], off
	global_load_dword v204, v[74:75], off offset:128
	global_load_dword v223, v[74:75], off offset:256
	v_lshl_add_u64 v[74:75], s[60:61], 0, v[72:73]
	v_lshl_add_u64 v[72:73], s[64:65], 0, v[72:73]
	v_ashrrev_i32_e32 v135, 31, v134
	v_add_u32_e32 v136, v184, v102
	v_add_u32_e32 v130, v183, v102
	v_add_u32_e32 v122, v181, v102
	v_add_u32_e32 v114, v179, v102
	v_add_u32_e32 v106, v71, v102
	v_add_u32_e32 v108, v180, v102
	v_add_u32_e32 v110, v182, v102
	v_ashrrev_i32_e32 v113, 31, v112
	v_add_u32_e32 v116, v187, v102
	v_ashrrev_i32_e32 v119, 31, v118
	v_add_u32_e32 v120, v190, v102
	v_add_u32_e32 v124, v191, v102
	v_add_u32_e32 v126, v192, v102
	v_ashrrev_i32_e32 v129, 31, v128
	v_ashrrev_i32_e32 v133, 31, v132
	global_load_dword v196, v[72:73], off
	global_load_dword v202, v[72:73], off offset:128
	global_load_dword v221, v[72:73], off offset:256
	v_lshl_add_u64 v[88:89], v[134:135], 2, s[12:13]
	v_ashrrev_i32_e32 v137, 31, v136
	v_ashrrev_i32_e32 v131, 31, v130
	v_ashrrev_i32_e32 v123, 31, v122
	v_ashrrev_i32_e32 v115, 31, v114
	v_ashrrev_i32_e32 v107, 31, v106
	v_ashrrev_i32_e32 v109, 31, v108
	v_ashrrev_i32_e32 v111, 31, v110
	v_lshl_add_u64 v[86:87], v[112:113], 2, s[12:13]
	v_ashrrev_i32_e32 v117, 31, v116
	v_lshl_add_u64 v[92:93], v[118:119], 2, s[12:13]
	v_ashrrev_i32_e32 v121, 31, v120
	v_ashrrev_i32_e32 v125, 31, v124
	v_ashrrev_i32_e32 v127, 31, v126
	v_lshl_add_u64 v[100:101], v[128:129], 2, s[12:13]
	v_lshl_add_u64 v[104:105], v[132:133], 2, s[12:13]
	global_load_dword v195, v[74:75], off
	global_load_dword v203, v[74:75], off offset:128
	global_load_dword v222, v[74:75], off offset:256
	v_lshl_add_u64 v[84:85], v[136:137], 2, s[12:13]
	v_lshl_add_u64 v[82:83], v[130:131], 2, s[12:13]
	v_lshl_add_u64 v[78:79], v[122:123], 2, s[12:13]
	v_lshl_add_u64 v[72:73], v[114:115], 2, s[12:13]
	v_lshl_add_u64 v[74:75], v[106:107], 2, s[12:13]
	v_lshl_add_u64 v[76:77], v[108:109], 2, s[12:13]
	v_lshl_add_u64 v[80:81], v[110:111], 2, s[12:13]
	global_load_dword v178, v[88:89], off
	global_load_dword v177, v[84:85], off
	global_load_dword v176, v[82:83], off
	global_load_dword v175, v[78:79], off
	global_load_dword v174, v[72:73], off
	global_load_dword v173, v[74:75], off
	global_load_dword v172, v[76:77], off
	global_load_dword v171, v[80:81], off
	v_lshl_add_u64 v[90:91], v[116:117], 2, s[12:13]
	global_load_dword v170, v[86:87], off
	global_load_dword v168, v[90:91], off
	v_lshl_add_u64 v[94:95], v[120:121], 2, s[12:13]
	v_lshl_add_u64 v[96:97], v[124:125], 2, s[12:13]
	v_lshl_add_u64 v[98:99], v[126:127], 2, s[12:13]
	global_load_dword v169, v[92:93], off
	global_load_dword v167, v[94:95], off
	global_load_dword v166, v[96:97], off
	global_load_dword v165, v[98:99], off
	global_load_dword v103, v[100:101], off
	global_load_dword v197, v[104:105], off
	v_lshl_add_u64 v[106:107], v[106:107], 1, s[8:9]
	global_load_dword v198, v[104:105], off offset:128
	global_load_dword v205, v[84:85], off offset:128
	global_load_dword v206, v[78:79], off offset:128
	global_load_dword v207, v[72:73], off offset:128
	global_load_dword v208, v[74:75], off offset:128
	global_load_dword v209, v[80:81], off offset:128
	global_load_dword v210, v[76:77], off offset:128
	global_load_dword v211, v[86:87], off offset:128
	global_load_dword v212, v[82:83], off offset:128
	global_load_dword v213, v[90:91], off offset:128
	global_load_dword v214, v[92:93], off offset:128
	global_load_dword v215, v[94:95], off offset:128
	global_load_dword v216, v[96:97], off offset:128
	global_load_dword v217, v[98:99], off offset:128
	global_load_dword v218, v[100:101], off offset:128
	global_load_dword v219, v[88:89], off offset:128
	global_load_dword v220, v[88:89], off offset:256
	global_load_dword v224, v[90:91], off offset:256
	global_load_dword v225, v[92:93], off offset:256
	global_load_dword v226, v[94:95], off offset:256
	global_load_dword v227, v[104:105], off offset:256
	global_load_dword v229, v[84:85], off offset:256
	global_load_dword v230, v[86:87], off offset:256
	global_load_dword v231, v[82:83], off offset:256
	global_load_dword v232, v[78:79], off offset:256
	global_load_dword v233, v[72:73], off offset:256
	global_load_dword v234, v[74:75], off offset:256
	global_load_dword v235, v[80:81], off offset:256
	global_load_dword v236, v[76:77], off offset:256
	global_load_dword v237, v[96:97], off offset:256
	global_load_dword v238, v[98:99], off offset:256
	global_load_dword v239, v[100:101], off offset:256
	s_waitcnt vmcnt(0)
	v_add_f32_e32 v196, 1.0, v196
	v_mul_f32_e32 v195, v195, v196
	v_fmac_f32_e32 v178, v49, v194
	v_fmac_f32_e32 v177, v50, v194
	v_fmac_f32_e32 v176, v51, v194
	v_fmac_f32_e32 v175, v52, v194
	v_fmac_f32_e32 v174, v53, v194
	v_fmac_f32_e32 v173, v54, v194
	v_fmac_f32_e32 v172, v55, v194
	v_fmac_f32_e32 v171, v56, v194
	v_fmac_f32_e32 v170, v57, v194
	v_fmac_f32_e32 v168, v58, v194
	v_fmac_f32_e32 v169, v59, v194
	v_fmac_f32_e32 v167, v60, v194
	v_fmac_f32_e32 v166, v61, v194
	v_fmac_f32_e32 v165, v62, v194
	v_fmac_f32_e32 v103, v63, v194
	v_fmac_f32_e32 v197, v48, v194
	v_mul_f32_e32 v48, v195, v197
	v_cvt_pk_bf16_f32 v58, v48, s0
	v_or_b32_e32 v48, 32, v102
	v_ashrrev_i32_e32 v49, 31, v48
	v_lshlrev_b64 v[52:53], 2, v[48:49]
	global_store_dword v[88:89], v178, off sc1
	global_store_dword v[84:85], v177, off sc1
	global_store_dword v[82:83], v176, off sc1
	global_store_dword v[78:79], v175, off sc1
	global_store_dword v[72:73], v174, off sc1
	global_store_dword v[74:75], v173, off sc1
	global_store_dword v[76:77], v172, off sc1
	global_store_dword v[80:81], v171, off sc1
	global_store_dword v[86:87], v170, off sc1
	global_store_dword v[90:91], v168, off sc1
	global_store_dword v[92:93], v169, off sc1
	global_store_dword v[94:95], v167, off sc1
	global_store_dword v[96:97], v166, off sc1
	global_store_dword v[98:99], v165, off sc1
	global_store_dword v[100:101], v103, off sc1
	global_store_dword v[104:105], v197, off sc1
	v_lshl_add_u64 v[50:51], v[132:133], 1, s[8:9]
	v_lshl_add_u64 v[56:57], s[64:65], 0, v[52:53]
	v_mov_b32_e32 v196, v198
	v_lshl_add_u64 v[54:55], s[60:61], 0, v[52:53]
	v_mov_b32_e32 v132, v202
	v_mov_b32_e32 v133, v203
	v_mul_f32_e32 v49, v195, v178
	global_store_short v[50:51], v58, off sc1
	v_lshl_add_u64 v[50:51], s[62:63], 0, v[52:53]
	v_mov_b32_e32 v194, v204
	v_cvt_pk_bf16_f32 v49, v49, s0
	v_lshl_add_u64 v[50:51], v[134:135], 1, s[8:9]
	global_store_short v[50:51], v49, off sc1
	v_mul_f32_e32 v49, v195, v177
	v_cvt_pk_bf16_f32 v49, v49, s0
	v_lshl_add_u64 v[50:51], v[136:137], 1, s[8:9]
	global_store_short v[50:51], v49, off sc1
	v_mul_f32_e32 v49, v195, v176
	v_cvt_pk_bf16_f32 v49, v49, s0
	v_lshl_add_u64 v[50:51], v[130:131], 1, s[8:9]
	global_store_short v[50:51], v49, off sc1
	v_mul_f32_e32 v49, v195, v175
	v_cvt_pk_bf16_f32 v49, v49, s0
	v_lshl_add_u64 v[50:51], v[122:123], 1, s[8:9]
	global_store_short v[50:51], v49, off sc1
	v_mul_f32_e32 v49, v195, v174
	v_cvt_pk_bf16_f32 v49, v49, s0
	v_lshl_add_u64 v[50:51], v[114:115], 1, s[8:9]
	global_store_short v[50:51], v49, off sc1
	v_mul_f32_e32 v49, v195, v173
	v_mov_b32_e32 v62, v205
	v_mov_b32_e32 v60, v206
	v_mov_b32_e32 v59, v207
	v_mov_b32_e32 v58, v208
	v_mov_b32_e32 v56, v209
	v_mov_b32_e32 v57, v210
	v_mov_b32_e32 v55, v211
	v_mov_b32_e32 v61, v212
	v_mov_b32_e32 v54, v213
	v_mov_b32_e32 v53, v214
	v_mov_b32_e32 v52, v215
	v_mov_b32_e32 v51, v216
	v_mov_b32_e32 v50, v217
	v_cvt_pk_bf16_f32 v63, v49, s0
	v_mov_b32_e32 v49, v218
	v_fmac_f32_e32 v196, v32, v194
	global_store_short v[106:107], v63, off sc1
	v_mov_b32_e32 v63, v219
	v_mul_f32_e32 v106, v195, v172
	v_cvt_pk_bf16_f32 v114, v106, s0
	v_lshl_add_u64 v[106:107], v[108:109], 1, s[8:9]
	global_store_short v[106:107], v114, off sc1
	v_mul_f32_e32 v106, v195, v171
	v_cvt_pk_bf16_f32 v108, v106, s0
	v_lshl_add_u64 v[106:107], v[110:111], 1, s[8:9]
	global_store_short v[106:107], v108, off sc1
	v_mul_f32_e32 v106, v195, v170
	v_cvt_pk_bf16_f32 v108, v106, s0
	v_lshl_add_u64 v[106:107], v[112:113], 1, s[8:9]
	global_store_short v[106:107], v108, off sc1
	v_mul_f32_e32 v106, v195, v168
	v_cvt_pk_bf16_f32 v108, v106, s0
	v_lshl_add_u64 v[106:107], v[116:117], 1, s[8:9]
	global_store_short v[106:107], v108, off sc1
	v_mul_f32_e32 v106, v195, v169
	v_cvt_pk_bf16_f32 v108, v106, s0
	v_lshl_add_u64 v[106:107], v[118:119], 1, s[8:9]
	global_store_short v[106:107], v108, off sc1
	v_mul_f32_e32 v106, v195, v167
	v_cvt_pk_bf16_f32 v108, v106, s0
	v_lshl_add_u64 v[106:107], v[120:121], 1, s[8:9]
	global_store_short v[106:107], v108, off sc1
	v_mul_f32_e32 v106, v195, v166
	v_cvt_pk_bf16_f32 v108, v106, s0
	v_lshl_add_u64 v[106:107], v[124:125], 1, s[8:9]
	global_store_short v[106:107], v108, off sc1
	v_mul_f32_e32 v106, v195, v165
	v_cvt_pk_bf16_f32 v108, v106, s0
	v_lshl_add_u64 v[106:107], v[126:127], 1, s[8:9]
	global_store_short v[106:107], v108, off sc1
	v_mul_f32_e32 v106, v195, v103
	v_cvt_pk_bf16_f32 v108, v106, s0
	v_lshl_add_u64 v[106:107], v[128:129], 1, s[8:9]
	global_store_short v[106:107], v108, off sc1
	v_add_f32_e32 v106, 1.0, v132
	v_mul_f32_e32 v110, v133, v106
	v_add_u32_e32 v106, v188, v48
	v_fmac_f32_e32 v62, v34, v194
	v_fmac_f32_e32 v61, v35, v194
	v_fmac_f32_e32 v60, v36, v194
	v_fmac_f32_e32 v59, v37, v194
	v_fmac_f32_e32 v58, v38, v194
	v_fmac_f32_e32 v57, v39, v194
	v_fmac_f32_e32 v56, v40, v194
	v_fmac_f32_e32 v55, v41, v194
	v_fmac_f32_e32 v54, v42, v194
	v_fmac_f32_e32 v53, v43, v194
	v_fmac_f32_e32 v52, v44, v194
	v_fmac_f32_e32 v51, v45, v194
	v_fmac_f32_e32 v50, v46, v194
	v_fmac_f32_e32 v49, v47, v194
	v_ashrrev_i32_e32 v107, 31, v106
	global_store_dword v[104:105], v196, off offset:128 sc1
	v_mul_f32_e32 v32, v110, v196
	global_store_dword v[84:85], v62, off offset:128 sc1
	global_store_dword v[82:83], v61, off offset:128 sc1
	global_store_dword v[78:79], v60, off offset:128 sc1
	global_store_dword v[72:73], v59, off offset:128 sc1
	global_store_dword v[74:75], v58, off offset:128 sc1
	global_store_dword v[76:77], v57, off offset:128 sc1
	global_store_dword v[80:81], v56, off offset:128 sc1
	global_store_dword v[86:87], v55, off offset:128 sc1
	global_store_dword v[90:91], v54, off offset:128 sc1
	global_store_dword v[92:93], v53, off offset:128 sc1
	global_store_dword v[94:95], v52, off offset:128 sc1
	global_store_dword v[96:97], v51, off offset:128 sc1
	global_store_dword v[98:99], v50, off offset:128 sc1
	global_store_dword v[100:101], v49, off offset:128 sc1
	v_cvt_pk_bf16_f32 v32, v32, s0
	v_lshl_add_u64 v[106:107], v[106:107], 1, s[8:9]
	v_add_u32_e32 v108, v186, v48
	v_mov_b32_e32 v45, v220
	v_ashrrev_i32_e32 v109, 31, v108
	global_store_short v[106:107], v32, off sc1
	v_mul_f32_e32 v113, v110, v56
	v_cvt_pk_bf16_f32 v113, v113, s0
	v_mul_f32_e32 v106, v196, v196
	v_fmac_f32_e32 v63, v33, v194
	v_mul_f32_e32 v32, v110, v63
	v_cvt_pk_bf16_f32 v34, v32, s0
	v_lshl_add_u64 v[32:33], v[108:109], 1, s[8:9]
	global_store_short v[32:33], v34, off sc1
	v_add_u32_e32 v32, v184, v48
	v_ashrrev_i32_e32 v33, 31, v32
	v_mul_f32_e32 v34, v110, v62
	v_cvt_pk_bf16_f32 v34, v34, s0
	v_lshl_add_u64 v[32:33], v[32:33], 1, s[8:9]
	global_store_short v[32:33], v34, off sc1
	v_add_u32_e32 v32, v183, v48
	v_ashrrev_i32_e32 v33, 31, v32
	v_mul_f32_e32 v34, v110, v61
	v_cvt_pk_bf16_f32 v34, v34, s0
	v_lshl_add_u64 v[32:33], v[32:33], 1, s[8:9]
	global_store_short v[32:33], v34, off sc1
	v_add_u32_e32 v32, v181, v48
	v_ashrrev_i32_e32 v33, 31, v32
	v_mul_f32_e32 v34, v110, v60
	v_cvt_pk_bf16_f32 v34, v34, s0
	v_lshl_add_u64 v[32:33], v[32:33], 1, s[8:9]
	global_store_short v[32:33], v34, off sc1
	v_add_u32_e32 v32, v179, v48
	v_ashrrev_i32_e32 v33, 31, v32
	v_mul_f32_e32 v34, v110, v59
	v_cvt_pk_bf16_f32 v42, v34, s0
	v_lshl_add_u64 v[34:35], v[32:33], 1, s[8:9]
	v_or_b32_e32 v32, 64, v102
	v_ashrrev_i32_e32 v33, 31, v32
	v_lshlrev_b64 v[36:37], 2, v[32:33]
	global_store_dword v[88:89], v63, off offset:128 sc1
	v_lshl_add_u64 v[40:41], s[64:65], 0, v[36:37]
	v_lshl_add_u64 v[38:39], s[60:61], 0, v[36:37]
	v_mov_b32_e32 v107, v221
	v_mov_b32_e32 v111, v222
	v_mul_f32_e32 v33, v110, v58
	global_store_short v[34:35], v42, off sc1
	v_lshl_add_u64 v[34:35], s[62:63], 0, v[36:37]
	v_mov_b32_e32 v112, v223
	v_add_u32_e32 v34, v71, v48
	v_ashrrev_i32_e32 v35, 31, v34
	v_cvt_pk_bf16_f32 v33, v33, s0
	v_lshl_add_u64 v[34:35], v[34:35], 1, s[8:9]
	global_store_short v[34:35], v33, off sc1
	v_add_u32_e32 v34, v180, v48
	v_ashrrev_i32_e32 v35, 31, v34
	v_mul_f32_e32 v33, v110, v57
	v_cvt_pk_bf16_f32 v33, v33, s0
	v_lshl_add_u64 v[34:35], v[34:35], 1, s[8:9]
	v_mov_b32_e32 v38, v224
	v_mov_b32_e32 v37, v225
	v_mov_b32_e32 v36, v226
	v_mov_b32_e32 v114, v227
	v_mov_b32_e32 v47, v229
	v_mov_b32_e32 v39, v230
	v_mov_b32_e32 v46, v231
	v_mov_b32_e32 v44, v232
	v_mov_b32_e32 v43, v233
	v_mov_b32_e32 v42, v234
	v_mov_b32_e32 v40, v235
	v_mov_b32_e32 v41, v236
	v_add_u32_e32 v108, v182, v48
	global_store_short v[34:35], v33, off sc1
	v_mov_b32_e32 v35, v237
	v_ashrrev_i32_e32 v109, 31, v108
	v_mov_b32_e32 v34, v238
	v_mov_b32_e32 v33, v239
	v_lshl_add_u64 v[108:109], v[108:109], 1, s[8:9]
	global_store_short v[108:109], v113, off sc1
	v_add_u32_e32 v108, v185, v48
	v_ashrrev_i32_e32 v109, 31, v108
	v_mul_f32_e32 v113, v110, v55
	v_cvt_pk_bf16_f32 v113, v113, s0
	v_lshl_add_u64 v[108:109], v[108:109], 1, s[8:9]
	global_store_short v[108:109], v113, off sc1
	v_add_u32_e32 v108, v187, v48
	v_ashrrev_i32_e32 v109, 31, v108
	v_mul_f32_e32 v113, v110, v54
	v_cvt_pk_bf16_f32 v113, v113, s0
	v_lshl_add_u64 v[108:109], v[108:109], 1, s[8:9]
	global_store_short v[108:109], v113, off sc1
	v_add_u32_e32 v108, v189, v48
	v_ashrrev_i32_e32 v109, 31, v108
	v_mul_f32_e32 v113, v110, v53
	v_cvt_pk_bf16_f32 v113, v113, s0
	v_lshl_add_u64 v[108:109], v[108:109], 1, s[8:9]
	global_store_short v[108:109], v113, off sc1
	v_add_u32_e32 v108, v190, v48
	v_ashrrev_i32_e32 v109, 31, v108
	v_mul_f32_e32 v113, v110, v52
	v_cvt_pk_bf16_f32 v113, v113, s0
	v_lshl_add_u64 v[108:109], v[108:109], 1, s[8:9]
	global_store_short v[108:109], v113, off sc1
	v_add_u32_e32 v108, v191, v48
	v_ashrrev_i32_e32 v109, 31, v108
	v_mul_f32_e32 v113, v110, v51
	v_cvt_pk_bf16_f32 v113, v113, s0
	v_lshl_add_u64 v[108:109], v[108:109], 1, s[8:9]
	global_store_short v[108:109], v113, off sc1
	v_add_u32_e32 v108, v192, v48
	v_ashrrev_i32_e32 v109, 31, v108
	v_mul_f32_e32 v113, v110, v50
	v_cvt_pk_bf16_f32 v113, v113, s0
	v_lshl_add_u64 v[108:109], v[108:109], 1, s[8:9]
	global_store_short v[108:109], v113, off sc1
	v_add_u32_e32 v108, v193, v48
	v_ashrrev_i32_e32 v109, 31, v108
	v_mul_f32_e32 v48, v110, v49
	v_cvt_pk_bf16_f32 v48, v48, s0
	v_lshl_add_u64 v[108:109], v[108:109], 1, s[8:9]
	global_store_short v[108:109], v48, off sc1
	v_add_u32_e32 v108, v188, v32
	v_ashrrev_i32_e32 v109, 31, v108
	v_add_f32_e32 v48, 1.0, v107
	v_mul_f32_e32 v48, v111, v48
	v_fmac_f32_e32 v106, v197, v197
	v_fmac_f32_e32 v45, v17, v112
	global_store_dword v[88:89], v45, off offset:256 sc1
	v_fmac_f32_e32 v38, v26, v112
	v_fmac_f32_e32 v37, v27, v112
	v_fmac_f32_e32 v36, v28, v112
	v_fmac_f32_e32 v114, v16, v112
	v_mul_f32_e32 v16, v48, v114
	v_fmac_f32_e32 v47, v18, v112
	v_cvt_pk_bf16_f32 v18, v16, s0
	v_lshl_add_u64 v[16:17], v[108:109], 1, s[8:9]
	global_store_short v[16:17], v18, off sc1
	v_add_u32_e32 v16, v186, v32
	v_ashrrev_i32_e32 v17, 31, v16
	v_mul_f32_e32 v18, v48, v45
	v_cvt_pk_bf16_f32 v18, v18, s0
	v_lshl_add_u64 v[16:17], v[16:17], 1, s[8:9]
	global_store_short v[16:17], v18, off sc1
	v_add_u32_e32 v16, v184, v32
	v_ashrrev_i32_e32 v17, 31, v16
	v_mul_f32_e32 v18, v48, v47
	v_cvt_pk_bf16_f32 v18, v18, s0
	v_lshl_add_u64 v[16:17], v[16:17], 1, s[8:9]
	v_fmac_f32_e32 v46, v19, v112
	global_store_short v[16:17], v18, off sc1
	v_add_u32_e32 v16, v183, v32
	v_ashrrev_i32_e32 v17, 31, v16
	v_mul_f32_e32 v18, v48, v46
	v_fmac_f32_e32 v44, v20, v112
	v_cvt_pk_bf16_f32 v18, v18, s0
	v_lshl_add_u64 v[16:17], v[16:17], 1, s[8:9]
	global_store_short v[16:17], v18, off sc1
	v_mul_f32_e32 v16, v48, v44
	v_cvt_pk_bf16_f32 v26, v16, s0
	v_or_b32_e32 v16, 0x60, v102
	v_add_u32_e32 v18, v181, v32
	v_ashrrev_i32_e32 v17, 31, v16
	v_fmac_f32_e32 v43, v21, v112
	v_fmac_f32_e32 v42, v22, v112
	v_fmac_f32_e32 v41, v23, v112
	v_fmac_f32_e32 v40, v24, v112
	v_fmac_f32_e32 v39, v25, v112
	v_fmac_f32_e32 v35, v29, v112
	v_fmac_f32_e32 v34, v30, v112
	v_fmac_f32_e32 v33, v31, v112
	v_ashrrev_i32_e32 v19, 31, v18
	v_lshlrev_b64 v[20:21], 2, v[16:17]
	global_store_dword v[84:85], v47, off offset:256 sc1
	global_store_dword v[82:83], v46, off offset:256 sc1
	global_store_dword v[78:79], v44, off offset:256 sc1
	global_store_dword v[72:73], v43, off offset:256 sc1
	global_store_dword v[74:75], v42, off offset:256 sc1
	global_store_dword v[76:77], v41, off offset:256 sc1
	global_store_dword v[80:81], v40, off offset:256 sc1
	global_store_dword v[86:87], v39, off offset:256 sc1
	global_store_dword v[90:91], v38, off offset:256 sc1
	global_store_dword v[92:93], v37, off offset:256 sc1
	global_store_dword v[94:95], v36, off offset:256 sc1
	global_store_dword v[96:97], v35, off offset:256 sc1
	global_store_dword v[98:99], v34, off offset:256 sc1
	global_store_dword v[100:101], v33, off offset:256 sc1
	global_store_dword v[104:105], v114, off offset:256 sc1
	v_lshl_add_u64 v[24:25], s[64:65], 0, v[20:21]
	v_lshl_add_u64 v[18:19], v[18:19], 1, s[8:9]
	global_load_dword v29, v[104:105], off offset:384
	v_lshl_add_u64 v[22:23], s[60:61], 0, v[20:21]
	global_load_dword v17, v[24:25], off
	global_load_dword v30, v[22:23], off
	global_load_dword v28, v[88:89], off offset:384
	global_load_dword v27, v[84:85], off offset:384
	v_fmac_f32_e32 v106, v114, v114
	global_store_short v[18:19], v26, off sc1
	v_lshl_add_u64 v[18:19], s[62:63], 0, v[20:21]
	global_load_dword v102, v[18:19], off
	v_add_u32_e32 v18, v179, v32
	v_ashrrev_i32_e32 v19, 31, v18
	v_mul_f32_e32 v20, v48, v43
	v_cvt_pk_bf16_f32 v20, v20, s0
	v_lshl_add_u64 v[18:19], v[18:19], 1, s[8:9]
	global_store_short v[18:19], v20, off sc1
	v_add_u32_e32 v18, v71, v32
	v_ashrrev_i32_e32 v19, 31, v18
	v_mul_f32_e32 v20, v48, v42
	v_cvt_pk_bf16_f32 v20, v20, s0
	v_lshl_add_u64 v[18:19], v[18:19], 1, s[8:9]
	global_store_short v[18:19], v20, off sc1
	v_add_u32_e32 v18, v180, v32
	v_ashrrev_i32_e32 v19, 31, v18
	v_mul_f32_e32 v20, v48, v41
	v_cvt_pk_bf16_f32 v20, v20, s0
	v_lshl_add_u64 v[18:19], v[18:19], 1, s[8:9]
	global_store_short v[18:19], v20, off sc1
	v_add_u32_e32 v18, v182, v32
	v_ashrrev_i32_e32 v19, 31, v18
	v_mul_f32_e32 v20, v48, v40
	v_cvt_pk_bf16_f32 v20, v20, s0
	v_lshl_add_u64 v[18:19], v[18:19], 1, s[8:9]
	global_store_short v[18:19], v20, off sc1
	v_add_u32_e32 v18, v185, v32
	v_ashrrev_i32_e32 v19, 31, v18
	v_mul_f32_e32 v20, v48, v39
	v_cvt_pk_bf16_f32 v20, v20, s0
	v_lshl_add_u64 v[18:19], v[18:19], 1, s[8:9]
	global_store_short v[18:19], v20, off sc1
	v_add_u32_e32 v18, v187, v32
	v_ashrrev_i32_e32 v19, 31, v18
	v_mul_f32_e32 v20, v48, v38
	v_cvt_pk_bf16_f32 v20, v20, s0
	v_lshl_add_u64 v[18:19], v[18:19], 1, s[8:9]
	global_store_short v[18:19], v20, off sc1
	v_add_u32_e32 v18, v189, v32
	v_ashrrev_i32_e32 v19, 31, v18
	v_mul_f32_e32 v20, v48, v37
	v_cvt_pk_bf16_f32 v20, v20, s0
	v_lshl_add_u64 v[18:19], v[18:19], 1, s[8:9]
	global_store_short v[18:19], v20, off sc1
	v_add_u32_e32 v18, v190, v32
	v_ashrrev_i32_e32 v19, 31, v18
	v_mul_f32_e32 v20, v48, v36
	v_cvt_pk_bf16_f32 v20, v20, s0
	v_lshl_add_u64 v[18:19], v[18:19], 1, s[8:9]
	global_store_short v[18:19], v20, off sc1
	v_add_u32_e32 v18, v191, v32
	v_ashrrev_i32_e32 v19, 31, v18
	v_mul_f32_e32 v20, v48, v35
	v_cvt_pk_bf16_f32 v20, v20, s0
	v_lshl_add_u64 v[18:19], v[18:19], 1, s[8:9]
	global_store_short v[18:19], v20, off sc1
	v_add_u32_e32 v18, v192, v32
	v_ashrrev_i32_e32 v19, 31, v18
	v_mul_f32_e32 v20, v48, v34
	v_cvt_pk_bf16_f32 v20, v20, s0
	v_lshl_add_u64 v[18:19], v[18:19], 1, s[8:9]
	global_store_short v[18:19], v20, off sc1
	v_add_u32_e32 v18, v193, v32
	v_ashrrev_i32_e32 v19, 31, v18
	v_mul_f32_e32 v20, v48, v33
	v_cvt_pk_bf16_f32 v20, v20, s0
	v_lshl_add_u64 v[18:19], v[18:19], 1, s[8:9]
	global_store_short v[18:19], v20, off sc1
	global_load_dword v20, v[86:87], off offset:384
	v_add_u32_e32 v18, v188, v16
	global_load_dword v26, v[82:83], off offset:384
	global_load_dword v25, v[78:79], off offset:384
	global_load_dword v24, v[72:73], off offset:384
	global_load_dword v23, v[74:75], off offset:384
	global_load_dword v21, v[80:81], off offset:384
	global_load_dword v22, v[76:77], off offset:384
	s_waitcnt vmcnt(23)
	v_add_f32_e32 v17, 1.0, v17
	s_waitcnt vmcnt(22)
	v_mul_f32_e32 v32, v30, v17
	v_ashrrev_i32_e32 v19, 31, v18
	v_lshl_add_u64 v[18:19], v[18:19], 1, s[8:9]
	v_add_u32_e32 v30, v186, v16
	s_waitcnt vmcnt(18)
	v_fmac_f32_e32 v29, v0, v102
	v_mul_f32_e32 v0, v32, v29
	v_cvt_pk_bf16_f32 v0, v0, s0
	global_store_short v[18:19], v0, off sc1
	global_load_dword v19, v[90:91], off offset:384
	v_ashrrev_i32_e32 v31, 31, v30
	global_load_dword v18, v[92:93], off offset:384
	v_fmac_f32_e32 v28, v1, v102
	v_mul_f32_e32 v0, v32, v28
	v_cvt_pk_bf16_f32 v17, v0, s0
	v_lshl_add_u64 v[0:1], v[30:31], 1, s[8:9]
	global_store_short v[0:1], v17, off sc1
	v_add_u32_e32 v0, v184, v16
	v_fmac_f32_e32 v27, v2, v102
	global_load_dword v17, v[94:95], off offset:384
	v_ashrrev_i32_e32 v1, 31, v0
	v_mul_f32_e32 v2, v32, v27
	v_cvt_pk_bf16_f32 v2, v2, s0
	v_lshl_add_u64 v[0:1], v[0:1], 1, s[8:9]
	global_store_short v[0:1], v2, off sc1
	v_add_u32_e32 v0, v183, v16
	global_load_dword v2, v[96:97], off offset:384
	v_ashrrev_i32_e32 v1, 31, v0
	v_lshl_add_u64 v[0:1], v[0:1], 1, s[8:9]
	v_add_u32_e32 v30, v181, v16
	v_ashrrev_i32_e32 v31, 31, v30
	v_lshl_add_u64 v[30:31], v[30:31], 1, s[8:9]
	v_fmac_f32_e32 v106, v29, v29
	global_store_dword v[104:105], v29, off offset:384 sc1
	global_store_dword v[88:89], v28, off offset:384 sc1
	global_store_dword v[84:85], v27, off offset:384 sc1
	s_waitcnt vmcnt(16)
	v_fmac_f32_e32 v20, v9, v102
	global_store_dword v[86:87], v20, off offset:384 sc1
	s_waitcnt vmcnt(16)
	v_fmac_f32_e32 v26, v3, v102
	v_mul_f32_e32 v3, v32, v26
	v_cvt_pk_bf16_f32 v3, v3, s0
	global_store_short v[0:1], v3, off sc1
	global_load_dword v1, v[98:99], off offset:384
	s_waitcnt vmcnt(17)
	v_fmac_f32_e32 v25, v4, v102
	v_mul_f32_e32 v0, v32, v25
	v_cvt_pk_bf16_f32 v0, v0, s0
	global_store_short v[30:31], v0, off sc1
	global_load_dword v0, v[100:101], off offset:384
	v_add_u32_e32 v30, v179, v16
	s_waitcnt vmcnt(18)
	v_fmac_f32_e32 v24, v5, v102
	v_ashrrev_i32_e32 v31, 31, v30
	v_mul_f32_e32 v3, v32, v24
	v_cvt_pk_bf16_f32 v3, v3, s0
	v_lshl_add_u64 v[4:5], v[30:31], 1, s[8:9]
	global_store_short v[4:5], v3, off sc1
	v_add_u32_e32 v4, v71, v16
	s_waitcnt vmcnt(18)
	v_fmac_f32_e32 v23, v6, v102
	v_ashrrev_i32_e32 v5, 31, v4
	v_mul_f32_e32 v3, v32, v23
	v_cvt_pk_bf16_f32 v3, v3, s0
	v_lshl_add_u64 v[4:5], v[4:5], 1, s[8:9]
	global_store_short v[4:5], v3, off sc1
	v_add_u32_e32 v4, v180, v16
	s_waitcnt vmcnt(17)
	v_fmac_f32_e32 v22, v7, v102
	v_ashrrev_i32_e32 v5, 31, v4
	v_mul_f32_e32 v3, v32, v22
	v_cvt_pk_bf16_f32 v3, v3, s0
	v_lshl_add_u64 v[4:5], v[4:5], 1, s[8:9]
	global_store_short v[4:5], v3, off sc1
	v_add_u32_e32 v4, v182, v16
	v_fmac_f32_e32 v21, v8, v102
	v_ashrrev_i32_e32 v5, 31, v4
	v_mul_f32_e32 v3, v32, v21
	v_cvt_pk_bf16_f32 v3, v3, s0
	v_lshl_add_u64 v[4:5], v[4:5], 1, s[8:9]
	global_store_short v[4:5], v3, off sc1
	v_add_u32_e32 v4, v185, v16
	v_ashrrev_i32_e32 v5, 31, v4
	v_mul_f32_e32 v3, v32, v20
	v_cvt_pk_bf16_f32 v3, v3, s0
	v_lshl_add_u64 v[4:5], v[4:5], 1, s[8:9]
	global_store_short v[4:5], v3, off sc1
	v_add_u32_e32 v4, v187, v16
	s_waitcnt vmcnt(18)
	v_fmac_f32_e32 v19, v10, v102
	v_ashrrev_i32_e32 v5, 31, v4
	v_mul_f32_e32 v3, v32, v19
	v_cvt_pk_bf16_f32 v3, v3, s0
	v_lshl_add_u64 v[4:5], v[4:5], 1, s[8:9]
	global_store_short v[4:5], v3, off sc1
	v_add_u32_e32 v4, v189, v16
	s_waitcnt vmcnt(18)
	v_fmac_f32_e32 v18, v11, v102
	v_ashrrev_i32_e32 v5, 31, v4
	v_mul_f32_e32 v3, v32, v18
	v_cvt_pk_bf16_f32 v3, v3, s0
	v_lshl_add_u64 v[4:5], v[4:5], 1, s[8:9]
	global_store_short v[4:5], v3, off sc1
	v_add_u32_e32 v4, v190, v16
	s_waitcnt vmcnt(17)
	v_fmac_f32_e32 v17, v12, v102
	v_ashrrev_i32_e32 v5, 31, v4
	v_mul_f32_e32 v3, v32, v17
	v_cvt_pk_bf16_f32 v3, v3, s0
	v_lshl_add_u64 v[4:5], v[4:5], 1, s[8:9]
	global_store_short v[4:5], v3, off sc1
	v_add_u32_e32 v4, v191, v16
	s_waitcnt vmcnt(16)
	v_fmac_f32_e32 v2, v13, v102
	v_ashrrev_i32_e32 v5, 31, v4
	v_mul_f32_e32 v3, v32, v2
	v_cvt_pk_bf16_f32 v3, v3, s0
	v_lshl_add_u64 v[4:5], v[4:5], 1, s[8:9]
	global_store_short v[4:5], v3, off sc1
	v_add_u32_e32 v4, v192, v16
	v_ashrrev_i32_e32 v5, 31, v4
	v_lshl_add_u64 v[4:5], v[4:5], 1, s[8:9]
	v_xor_b32_e32 v13, 16, v164
	v_add_u32_e32 v10, v193, v16
	v_ashrrev_i32_e32 v11, 31, v10
	v_lshl_add_u64 v[10:11], v[10:11], 1, s[8:9]
	v_ashrrev_i32_e32 v71, 31, v70
	global_store_dword v[82:83], v26, off offset:384 sc1
	global_store_dword v[78:79], v25, off offset:384 sc1
	global_store_dword v[72:73], v24, off offset:384 sc1
	global_store_dword v[74:75], v23, off offset:384 sc1
	s_waitcnt vmcnt(15)
	v_fmac_f32_e32 v1, v14, v102
	v_mul_f32_e32 v3, v32, v1
	v_cvt_pk_bf16_f32 v3, v3, s0
	global_store_short v[4:5], v3, off sc1
	v_and_b32_e32 v4, 64, v164
	v_xor_b32_e32 v3, 1, v164
	v_add_u32_e32 v7, 64, v4
	v_cmp_lt_i32_e32 vcc, v3, v7
	v_xor_b32_e32 v4, 2, v164
	s_waitcnt vmcnt(14)
	v_fmac_f32_e32 v0, v15, v102
	v_cndmask_b32_e32 v3, v164, v3, vcc
	v_lshlrev_b32_e32 v3, 2, v3
	ds_bpermute_b32 v5, v3, v106
	v_cmp_lt_i32_e32 vcc, v4, v7
	v_mul_f32_e32 v12, v32, v0
	v_cvt_pk_bf16_f32 v12, v12, s0
	v_cndmask_b32_e32 v4, v164, v4, vcc
	v_lshlrev_b32_e32 v4, 2, v4
	s_waitcnt lgkmcnt(0)
	v_add_f32_e32 v6, v106, v5
	ds_bpermute_b32 v8, v4, v6
	v_xor_b32_e32 v5, 4, v164
	v_cmp_lt_i32_e32 vcc, v5, v7
	global_store_dword v[76:77], v22, off offset:384 sc1
	global_store_dword v[80:81], v21, off offset:384 sc1
	v_cndmask_b32_e32 v5, v164, v5, vcc
	v_lshlrev_b32_e32 v5, 2, v5
	s_waitcnt lgkmcnt(0)
	v_add_f32_e32 v8, v6, v8
	ds_bpermute_b32 v9, v5, v8
	v_xor_b32_e32 v6, 8, v164
	v_cmp_lt_i32_e32 vcc, v6, v7
	global_store_dword v[90:91], v19, off offset:384 sc1
	global_store_dword v[92:93], v18, off offset:384 sc1
	v_cndmask_b32_e32 v6, v164, v6, vcc
	v_lshlrev_b32_e32 v6, 2, v6
	s_waitcnt lgkmcnt(0)
	v_add_f32_e32 v8, v8, v9
	ds_bpermute_b32 v9, v6, v8
	v_cmp_lt_i32_e32 vcc, v13, v7
	global_store_dword v[94:95], v17, off offset:384 sc1
	global_store_dword v[96:97], v2, off offset:384 sc1
	v_cndmask_b32_e32 v7, v164, v13, vcc
	v_lshlrev_b32_e32 v7, 2, v7
	s_waitcnt lgkmcnt(0)
	v_add_f32_e32 v8, v8, v9
	ds_bpermute_b32 v9, v7, v8
	global_store_dword v[98:99], v1, off offset:384 sc1
	global_store_dword v[100:101], v0, off offset:384 sc1
	global_store_short v[10:11], v12, off sc1
	s_and_saveexec_b64 s[60:61], s[0:1]
	s_cbranch_execz .LBB0_1328
	s_waitcnt lgkmcnt(0)
	v_add_f32_e32 v10, v8, v9
	v_lshl_add_u64 v[8:9], v[70:71], 2, s[58:59]
	global_store_dword v[8:9], v10, off sc1

.LBB0_1398:
	s_add_i32 s58, s67, 0xffffe000
	s_lshr_b32 s58, s58, 12
	s_mulk_i32 s58, 0x1800
	s_addk_i32 s58, 0x1800
	s_cmp_gt_i32 s6, 63
	s_cselect_b32 s62, s58, 0
	s_add_i32 s6, s62, 0x9000
	s_lshl_b64 s[58:59], s[6:7], 2
	s_add_u32 s6, s14, s58
	s_addc_u32 s58, s15, s59
	s_add_u32 s60, s6, 0x5ba5000
	s_addc_u32 s61, s58, 0
	s_add_i32 s6, s62, 0xd800
	s_lshl_b64 s[58:59], s[6:7], 2
	v_mov_b32_e32 v70, s66
	s_add_u32 s6, s14, s58
	ds_read_b64 v[70:71], v70
	s_addc_u32 s69, s15, s59
	s_lshl_b32 s58, s64, 14
	s_add_i32 s58, s58, 0xc0000
	s_ashr_i32 s59, s58, 31
	s_lshl_b64 s[58:59], s[58:59], 2
	s_add_u32 s58, s10, s58
	s_waitcnt lgkmcnt(0)
	v_readfirstlane_b32 s63, v70
	s_addc_u32 s59, s11, s59
	v_or_b32_e32 v102, s68, v138
	v_add_u32_e32 v70, s67, v139
	v_readfirstlane_b32 s65, v71
	s_add_u32 s62, s63, 0x3000
	v_ashrrev_i32_e32 v103, 31, v102
	v_lshlrev_b32_e32 v191, 10, v70
	s_addc_u32 s63, s65, 0
	v_lshlrev_b64 v[72:73], 2, v[102:103]
	v_or_b32_e32 v187, 0x400, v191
	v_or_b32_e32 v186, 0x4400, v191
	v_or_b32_e32 v189, 0x4c00, v191
	v_or_b32_e32 v194, 0x6c00, v191
	s_add_u32 s64, s6, 0x5ba1000
	v_lshl_add_u64 v[74:75], s[60:61], 0, v[72:73]
	v_add_u32_e32 v130, v191, v102
	v_add_u32_e32 v132, v187, v102
	v_or_b32_e32 v185, 0x800, v191
	v_or_b32_e32 v184, 0xc00, v191
	v_or_b32_e32 v182, 0x2000, v191
	v_or_b32_e32 v180, 0x2400, v191
	v_or_b32_e32 v71, 0x2800, v191
	v_or_b32_e32 v181, 0x2c00, v191
	v_or_b32_e32 v183, 0x4000, v191
	v_add_u32_e32 v112, v186, v102
	v_or_b32_e32 v188, 0x4800, v191
	v_add_u32_e32 v116, v189, v102
	v_or_b32_e32 v190, 0x6000, v191
	v_or_b32_e32 v192, 0x6400, v191
	v_or_b32_e32 v193, 0x6800, v191
	v_add_u32_e32 v128, v194, v102
	s_addc_u32 s65, s69, 0
	global_load_dword v195, v[74:75], off
	global_load_dword v205, v[74:75], off offset:128
	global_load_dword v224, v[74:75], off offset:256
	v_lshl_add_u64 v[74:75], s[62:63], 0, v[72:73]
	v_ashrrev_i32_e32 v133, 31, v132
	v_add_u32_e32 v134, v185, v102
	v_add_u32_e32 v136, v184, v102
	v_add_u32_e32 v126, v182, v102
	v_add_u32_e32 v118, v180, v102
	v_add_u32_e32 v110, v71, v102
	v_add_u32_e32 v106, v181, v102
	v_add_u32_e32 v108, v183, v102
	v_ashrrev_i32_e32 v113, 31, v112
	v_add_u32_e32 v114, v188, v102
	v_ashrrev_i32_e32 v117, 31, v116
	v_add_u32_e32 v120, v190, v102
	v_add_u32_e32 v122, v192, v102
	v_add_u32_e32 v124, v193, v102
	v_ashrrev_i32_e32 v129, 31, v128
	v_ashrrev_i32_e32 v131, 31, v130
	v_lshl_add_u64 v[72:73], s[64:65], 0, v[72:73]
	global_load_dword v196, v[74:75], off
	global_load_dword v204, v[74:75], off offset:128
	global_load_dword v223, v[74:75], off offset:256
	global_load_dword v197, v[72:73], off
	global_load_dword v203, v[72:73], off offset:128
	global_load_dword v222, v[72:73], off offset:256
	v_lshl_add_u64 v[88:89], v[132:133], 2, s[12:13]
	v_ashrrev_i32_e32 v135, 31, v134
	v_ashrrev_i32_e32 v137, 31, v136
	v_ashrrev_i32_e32 v127, 31, v126
	v_ashrrev_i32_e32 v119, 31, v118
	v_ashrrev_i32_e32 v111, 31, v110
	v_ashrrev_i32_e32 v107, 31, v106
	v_ashrrev_i32_e32 v109, 31, v108
	v_lshl_add_u64 v[86:87], v[112:113], 2, s[12:13]
	v_ashrrev_i32_e32 v115, 31, v114
	v_lshl_add_u64 v[92:93], v[116:117], 2, s[12:13]
	v_ashrrev_i32_e32 v121, 31, v120
	v_ashrrev_i32_e32 v123, 31, v122
	v_ashrrev_i32_e32 v125, 31, v124
	v_lshl_add_u64 v[100:101], v[128:129], 2, s[12:13]
	v_lshl_add_u64 v[104:105], v[130:131], 2, s[12:13]
	v_lshl_add_u64 v[84:85], v[134:135], 2, s[12:13]
	v_lshl_add_u64 v[82:83], v[136:137], 2, s[12:13]
	v_lshl_add_u64 v[78:79], v[126:127], 2, s[12:13]
	v_lshl_add_u64 v[72:73], v[118:119], 2, s[12:13]
	v_lshl_add_u64 v[74:75], v[110:111], 2, s[12:13]
	v_lshl_add_u64 v[76:77], v[106:107], 2, s[12:13]
	v_lshl_add_u64 v[80:81], v[108:109], 2, s[12:13]
	global_load_dword v179, v[88:89], off
	global_load_dword v178, v[84:85], off
	global_load_dword v177, v[82:83], off
	global_load_dword v176, v[78:79], off
	global_load_dword v175, v[72:73], off
	global_load_dword v174, v[74:75], off
	global_load_dword v173, v[76:77], off
	global_load_dword v172, v[80:81], off
	v_lshl_add_u64 v[90:91], v[114:115], 2, s[12:13]
	global_load_dword v171, v[86:87], off
	global_load_dword v169, v[90:91], off
	v_lshl_add_u64 v[94:95], v[120:121], 2, s[12:13]
	v_lshl_add_u64 v[96:97], v[122:123], 2, s[12:13]
	v_lshl_add_u64 v[98:99], v[124:125], 2, s[12:13]
	global_load_dword v170, v[92:93], off
	global_load_dword v168, v[94:95], off
	global_load_dword v167, v[96:97], off
	global_load_dword v166, v[98:99], off
	global_load_dword v103, v[100:101], off
	global_load_dword v198, v[104:105], off
	v_lshl_add_u64 v[110:111], v[110:111], 1, s[8:9]
	v_lshl_add_u64 v[106:107], v[106:107], 1, s[8:9]
	global_load_dword v202, v[104:105], off offset:128
	global_load_dword v206, v[84:85], off offset:128
	global_load_dword v207, v[78:79], off offset:128
	global_load_dword v208, v[72:73], off offset:128
	global_load_dword v209, v[74:75], off offset:128
	global_load_dword v210, v[80:81], off offset:128
	global_load_dword v211, v[76:77], off offset:128
	global_load_dword v212, v[86:87], off offset:128
	global_load_dword v213, v[82:83], off offset:128
	global_load_dword v214, v[90:91], off offset:128
	global_load_dword v215, v[92:93], off offset:128
	global_load_dword v216, v[94:95], off offset:128
	global_load_dword v217, v[96:97], off offset:128
	global_load_dword v218, v[98:99], off offset:128
	global_load_dword v219, v[100:101], off offset:128
	global_load_dword v220, v[88:89], off offset:128
	global_load_dword v221, v[88:89], off offset:256
	global_load_dword v225, v[90:91], off offset:256
	global_load_dword v226, v[92:93], off offset:256
	global_load_dword v227, v[94:95], off offset:256
	global_load_dword v229, v[104:105], off offset:256
	global_load_dword v230, v[84:85], off offset:256
	global_load_dword v231, v[86:87], off offset:256
	global_load_dword v232, v[82:83], off offset:256
	global_load_dword v233, v[78:79], off offset:256
	global_load_dword v234, v[72:73], off offset:256
	global_load_dword v235, v[74:75], off offset:256
	global_load_dword v236, v[80:81], off offset:256
	global_load_dword v237, v[76:77], off offset:256
	global_load_dword v238, v[96:97], off offset:256
	global_load_dword v239, v[98:99], off offset:256
	global_load_dword v240, v[100:101], off offset:256
	s_waitcnt vmcnt(0)
	v_add_f32_e32 v197, 1.0, v197
	v_mul_f32_e32 v196, v196, v197
	v_fmac_f32_e32 v179, v49, v195
	v_fmac_f32_e32 v178, v50, v195
	v_fmac_f32_e32 v177, v51, v195
	v_fmac_f32_e32 v176, v52, v195
	v_fmac_f32_e32 v175, v53, v195
	v_fmac_f32_e32 v174, v54, v195
	v_fmac_f32_e32 v173, v55, v195
	v_fmac_f32_e32 v172, v56, v195
	v_fmac_f32_e32 v171, v57, v195
	v_fmac_f32_e32 v169, v58, v195
	v_fmac_f32_e32 v170, v59, v195
	v_fmac_f32_e32 v168, v60, v195
	v_fmac_f32_e32 v167, v61, v195
	v_fmac_f32_e32 v166, v62, v195
	v_fmac_f32_e32 v103, v63, v195
	v_fmac_f32_e32 v198, v48, v195
	v_mul_f32_e32 v48, v196, v198
	v_cvt_pk_bf16_f32 v58, v48, s0
	v_or_b32_e32 v48, 32, v102
	v_ashrrev_i32_e32 v49, 31, v48
	v_lshlrev_b64 v[52:53], 2, v[48:49]
	global_store_dword v[88:89], v179, off sc1
	global_store_dword v[84:85], v178, off sc1
	global_store_dword v[82:83], v177, off sc1
	global_store_dword v[78:79], v176, off sc1
	global_store_dword v[72:73], v175, off sc1
	global_store_dword v[74:75], v174, off sc1
	global_store_dword v[76:77], v173, off sc1
	global_store_dword v[80:81], v172, off sc1
	global_store_dword v[86:87], v171, off sc1
	global_store_dword v[90:91], v169, off sc1
	global_store_dword v[92:93], v170, off sc1
	global_store_dword v[94:95], v168, off sc1
	global_store_dword v[96:97], v167, off sc1
	global_store_dword v[98:99], v166, off sc1
	global_store_dword v[100:101], v103, off sc1
	global_store_dword v[104:105], v198, off sc1
	v_lshl_add_u64 v[50:51], v[130:131], 1, s[8:9]
	v_lshl_add_u64 v[56:57], s[64:65], 0, v[52:53]
	v_mov_b32_e32 v197, v202
	v_lshl_add_u64 v[54:55], s[62:63], 0, v[52:53]
	v_mov_b32_e32 v130, v203
	v_mov_b32_e32 v131, v204
	v_mul_f32_e32 v49, v196, v179
	global_store_short v[50:51], v58, off sc1
	v_lshl_add_u64 v[50:51], s[60:61], 0, v[52:53]
	v_mov_b32_e32 v195, v205
	v_lshl_add_u64 v[50:51], v[132:133], 1, s[8:9]
	v_cvt_pk_bf16_f32 v49, v49, s0
	global_store_short v[50:51], v49, off sc1
	v_mul_f32_e32 v49, v196, v178
	v_lshl_add_u64 v[50:51], v[134:135], 1, s[8:9]
	v_cvt_pk_bf16_f32 v49, v49, s0
	global_store_short v[50:51], v49, off sc1
	v_mul_f32_e32 v49, v196, v177
	v_lshl_add_u64 v[50:51], v[136:137], 1, s[8:9]
	v_cvt_pk_bf16_f32 v49, v49, s0
	global_store_short v[50:51], v49, off sc1
	v_mul_f32_e32 v49, v196, v176
	v_lshl_add_u64 v[50:51], v[126:127], 1, s[8:9]
	v_cvt_pk_bf16_f32 v49, v49, s0
	global_store_short v[50:51], v49, off sc1
	v_mul_f32_e32 v49, v196, v175
	v_lshl_add_u64 v[50:51], v[118:119], 1, s[8:9]
	v_cvt_pk_bf16_f32 v49, v49, s0
	v_mov_b32_e32 v62, v206
	v_mov_b32_e32 v60, v207
	v_mov_b32_e32 v59, v208
	v_mov_b32_e32 v58, v209
	v_mov_b32_e32 v56, v210
	v_mov_b32_e32 v57, v211
	v_mov_b32_e32 v55, v212
	v_mov_b32_e32 v61, v213
	v_mov_b32_e32 v54, v214
	v_mov_b32_e32 v53, v215
	v_mov_b32_e32 v52, v216
	v_mul_f32_e32 v63, v196, v174
	global_store_short v[50:51], v49, off sc1
	v_mov_b32_e32 v51, v217
	v_cvt_pk_bf16_f32 v63, v63, s0
	v_mov_b32_e32 v50, v218
	v_mov_b32_e32 v49, v219
	v_fmac_f32_e32 v197, v32, v195
	global_store_short v[110:111], v63, off sc1
	v_mov_b32_e32 v63, v220
	v_mul_f32_e32 v110, v196, v173
	v_cvt_pk_bf16_f32 v110, v110, s0
	global_store_short v[106:107], v110, off sc1
	v_lshl_add_u64 v[106:107], v[108:109], 1, s[8:9]
	v_mul_f32_e32 v108, v196, v172
	v_cvt_pk_bf16_f32 v108, v108, s0
	global_store_short v[106:107], v108, off sc1
	v_mul_f32_e32 v108, v196, v171
	v_lshl_add_u64 v[106:107], v[112:113], 1, s[8:9]
	v_cvt_pk_bf16_f32 v108, v108, s0
	global_store_short v[106:107], v108, off sc1
	v_mul_f32_e32 v108, v196, v169
	v_lshl_add_u64 v[106:107], v[114:115], 1, s[8:9]
	v_cvt_pk_bf16_f32 v108, v108, s0
	global_store_short v[106:107], v108, off sc1
	v_mul_f32_e32 v108, v196, v170
	v_lshl_add_u64 v[106:107], v[116:117], 1, s[8:9]
	v_cvt_pk_bf16_f32 v108, v108, s0
	global_store_short v[106:107], v108, off sc1
	v_mul_f32_e32 v108, v196, v168
	v_lshl_add_u64 v[106:107], v[120:121], 1, s[8:9]
	v_cvt_pk_bf16_f32 v108, v108, s0
	global_store_short v[106:107], v108, off sc1
	v_mul_f32_e32 v108, v196, v167
	v_lshl_add_u64 v[106:107], v[122:123], 1, s[8:9]
	v_cvt_pk_bf16_f32 v108, v108, s0
	global_store_short v[106:107], v108, off sc1
	v_mul_f32_e32 v108, v196, v166
	v_lshl_add_u64 v[106:107], v[124:125], 1, s[8:9]
	v_cvt_pk_bf16_f32 v108, v108, s0
	global_store_short v[106:107], v108, off sc1
	v_mul_f32_e32 v108, v196, v103
	v_lshl_add_u64 v[106:107], v[128:129], 1, s[8:9]
	v_cvt_pk_bf16_f32 v108, v108, s0
	global_store_short v[106:107], v108, off sc1
	v_add_f32_e32 v106, 1.0, v130
	v_mul_f32_e32 v107, v131, v106
	v_add_u32_e32 v108, v191, v48
	v_ashrrev_i32_e32 v109, 31, v108
	v_mul_f32_e32 v32, v107, v197
	v_fmac_f32_e32 v62, v34, v195
	v_fmac_f32_e32 v61, v35, v195
	v_fmac_f32_e32 v60, v36, v195
	v_fmac_f32_e32 v59, v37, v195
	v_fmac_f32_e32 v58, v38, v195
	v_fmac_f32_e32 v57, v39, v195
	v_fmac_f32_e32 v56, v40, v195
	v_fmac_f32_e32 v55, v41, v195
	v_fmac_f32_e32 v54, v42, v195
	v_fmac_f32_e32 v53, v43, v195
	v_fmac_f32_e32 v52, v44, v195
	v_fmac_f32_e32 v51, v45, v195
	v_fmac_f32_e32 v50, v46, v195
	v_fmac_f32_e32 v49, v47, v195
	global_store_dword v[104:105], v197, off offset:128 sc1
	v_lshl_add_u64 v[108:109], v[108:109], 1, s[8:9]
	v_cvt_pk_bf16_f32 v32, v32, s0
	global_store_dword v[84:85], v62, off offset:128 sc1
	global_store_dword v[82:83], v61, off offset:128 sc1
	global_store_dword v[78:79], v60, off offset:128 sc1
	global_store_dword v[72:73], v59, off offset:128 sc1
	global_store_dword v[74:75], v58, off offset:128 sc1
	global_store_dword v[76:77], v57, off offset:128 sc1
	global_store_dword v[80:81], v56, off offset:128 sc1
	global_store_dword v[86:87], v55, off offset:128 sc1
	global_store_dword v[90:91], v54, off offset:128 sc1
	global_store_dword v[92:93], v53, off offset:128 sc1
	global_store_dword v[94:95], v52, off offset:128 sc1
	global_store_dword v[96:97], v51, off offset:128 sc1
	global_store_dword v[98:99], v50, off offset:128 sc1
	global_store_dword v[100:101], v49, off offset:128 sc1
	global_store_short v[108:109], v32, off sc1
	v_add_u32_e32 v108, v187, v48
	v_mov_b32_e32 v45, v221
	v_ashrrev_i32_e32 v109, 31, v108
	v_mul_f32_e32 v113, v107, v56
	v_cvt_pk_bf16_f32 v113, v113, s0
	v_mul_f32_e32 v106, v197, v197
	v_fmac_f32_e32 v106, v198, v198
	v_fmac_f32_e32 v63, v33, v195
	v_mul_f32_e32 v34, v107, v63
	v_lshl_add_u64 v[32:33], v[108:109], 1, s[8:9]
	v_cvt_pk_bf16_f32 v34, v34, s0
	global_store_short v[32:33], v34, off sc1
	v_add_u32_e32 v32, v185, v48
	v_ashrrev_i32_e32 v33, 31, v32
	v_mul_f32_e32 v34, v107, v62
	v_lshl_add_u64 v[32:33], v[32:33], 1, s[8:9]
	v_cvt_pk_bf16_f32 v34, v34, s0
	global_store_short v[32:33], v34, off sc1
	v_add_u32_e32 v32, v184, v48
	v_ashrrev_i32_e32 v33, 31, v32
	v_mul_f32_e32 v34, v107, v61
	v_lshl_add_u64 v[32:33], v[32:33], 1, s[8:9]
	v_cvt_pk_bf16_f32 v34, v34, s0
	global_store_short v[32:33], v34, off sc1
	v_add_u32_e32 v32, v182, v48
	v_ashrrev_i32_e32 v33, 31, v32
	v_mul_f32_e32 v34, v107, v60
	v_lshl_add_u64 v[32:33], v[32:33], 1, s[8:9]
	v_cvt_pk_bf16_f32 v34, v34, s0
	global_store_short v[32:33], v34, off sc1
	v_add_u32_e32 v32, v180, v48
	v_ashrrev_i32_e32 v33, 31, v32
	v_lshl_add_u64 v[34:35], v[32:33], 1, s[8:9]
	v_mul_f32_e32 v32, v107, v59
	v_cvt_pk_bf16_f32 v42, v32, s0
	v_or_b32_e32 v32, 64, v102
	v_ashrrev_i32_e32 v33, 31, v32
	v_lshlrev_b64 v[36:37], 2, v[32:33]
	global_store_dword v[88:89], v63, off offset:128 sc1
	v_lshl_add_u64 v[40:41], s[64:65], 0, v[36:37]
	v_lshl_add_u64 v[38:39], s[62:63], 0, v[36:37]
	v_mov_b32_e32 v110, v222
	v_mov_b32_e32 v111, v223
	v_mul_f32_e32 v33, v107, v58
	global_store_short v[34:35], v42, off sc1
	v_lshl_add_u64 v[34:35], s[60:61], 0, v[36:37]
	v_mov_b32_e32 v112, v224
	v_add_u32_e32 v34, v71, v48
	v_ashrrev_i32_e32 v35, 31, v34
	v_lshl_add_u64 v[34:35], v[34:35], 1, s[8:9]
	v_cvt_pk_bf16_f32 v33, v33, s0
	global_store_short v[34:35], v33, off sc1
	v_add_u32_e32 v34, v181, v48
	v_ashrrev_i32_e32 v35, 31, v34
	v_mul_f32_e32 v33, v107, v57
	v_lshl_add_u64 v[34:35], v[34:35], 1, s[8:9]
	v_cvt_pk_bf16_f32 v33, v33, s0
	v_mov_b32_e32 v38, v225
	v_mov_b32_e32 v37, v226
	v_mov_b32_e32 v36, v227
	v_mov_b32_e32 v114, v229
	v_mov_b32_e32 v47, v230
	v_mov_b32_e32 v39, v231
	v_mov_b32_e32 v46, v232
	v_mov_b32_e32 v44, v233
	v_mov_b32_e32 v43, v234
	v_mov_b32_e32 v42, v235
	v_mov_b32_e32 v40, v236
	v_mov_b32_e32 v41, v237
	v_add_u32_e32 v108, v183, v48
	global_store_short v[34:35], v33, off sc1
	v_mov_b32_e32 v35, v238
	v_ashrrev_i32_e32 v109, 31, v108
	v_mov_b32_e32 v34, v239
	v_mov_b32_e32 v33, v240
	v_lshl_add_u64 v[108:109], v[108:109], 1, s[8:9]
	global_store_short v[108:109], v113, off sc1
	v_add_u32_e32 v108, v186, v48
	v_ashrrev_i32_e32 v109, 31, v108
	v_mul_f32_e32 v113, v107, v55
	v_lshl_add_u64 v[108:109], v[108:109], 1, s[8:9]
	v_cvt_pk_bf16_f32 v113, v113, s0
	global_store_short v[108:109], v113, off sc1
	v_add_u32_e32 v108, v188, v48
	v_ashrrev_i32_e32 v109, 31, v108
	v_mul_f32_e32 v113, v107, v54
	v_lshl_add_u64 v[108:109], v[108:109], 1, s[8:9]
	v_cvt_pk_bf16_f32 v113, v113, s0
	global_store_short v[108:109], v113, off sc1
	v_add_u32_e32 v108, v189, v48
	v_ashrrev_i32_e32 v109, 31, v108
	v_mul_f32_e32 v113, v107, v53
	v_lshl_add_u64 v[108:109], v[108:109], 1, s[8:9]
	v_cvt_pk_bf16_f32 v113, v113, s0
	global_store_short v[108:109], v113, off sc1
	v_add_u32_e32 v108, v190, v48
	v_ashrrev_i32_e32 v109, 31, v108
	v_mul_f32_e32 v113, v107, v52
	v_lshl_add_u64 v[108:109], v[108:109], 1, s[8:9]
	v_cvt_pk_bf16_f32 v113, v113, s0
	global_store_short v[108:109], v113, off sc1
	v_add_u32_e32 v108, v192, v48
	v_ashrrev_i32_e32 v109, 31, v108
	v_mul_f32_e32 v113, v107, v51
	v_lshl_add_u64 v[108:109], v[108:109], 1, s[8:9]
	v_cvt_pk_bf16_f32 v113, v113, s0
	global_store_short v[108:109], v113, off sc1
	v_add_u32_e32 v108, v193, v48
	v_ashrrev_i32_e32 v109, 31, v108
	v_mul_f32_e32 v113, v107, v50
	v_lshl_add_u64 v[108:109], v[108:109], 1, s[8:9]
	v_cvt_pk_bf16_f32 v113, v113, s0
	global_store_short v[108:109], v113, off sc1
	v_add_u32_e32 v108, v194, v48
	v_ashrrev_i32_e32 v109, 31, v108
	v_mul_f32_e32 v48, v107, v49
	v_lshl_add_u64 v[108:109], v[108:109], 1, s[8:9]
	v_cvt_pk_bf16_f32 v48, v48, s0
	global_store_short v[108:109], v48, off sc1
	v_add_u32_e32 v108, v191, v32
	v_ashrrev_i32_e32 v109, 31, v108
	v_add_f32_e32 v48, 1.0, v110
	v_mul_f32_e32 v48, v111, v48
	v_fmac_f32_e32 v45, v17, v112
	global_store_dword v[88:89], v45, off offset:256 sc1
	v_fmac_f32_e32 v38, v26, v112
	v_fmac_f32_e32 v37, v27, v112
	v_fmac_f32_e32 v36, v28, v112
	v_fmac_f32_e32 v114, v16, v112
	v_fmac_f32_e32 v47, v18, v112
	v_mul_f32_e32 v18, v48, v114
	v_lshl_add_u64 v[16:17], v[108:109], 1, s[8:9]
	v_cvt_pk_bf16_f32 v18, v18, s0
	global_store_short v[16:17], v18, off sc1
	v_add_u32_e32 v16, v187, v32
	v_ashrrev_i32_e32 v17, 31, v16
	v_mul_f32_e32 v18, v48, v45
	v_lshl_add_u64 v[16:17], v[16:17], 1, s[8:9]
	v_cvt_pk_bf16_f32 v18, v18, s0
	global_store_short v[16:17], v18, off sc1
	v_add_u32_e32 v16, v185, v32
	v_ashrrev_i32_e32 v17, 31, v16
	v_mul_f32_e32 v18, v48, v47
	v_lshl_add_u64 v[16:17], v[16:17], 1, s[8:9]
	v_cvt_pk_bf16_f32 v18, v18, s0
	v_fmac_f32_e32 v46, v19, v112
	global_store_short v[16:17], v18, off sc1
	v_add_u32_e32 v16, v184, v32
	v_ashrrev_i32_e32 v17, 31, v16
	v_mul_f32_e32 v18, v48, v46
	v_lshl_add_u64 v[16:17], v[16:17], 1, s[8:9]
	v_cvt_pk_bf16_f32 v18, v18, s0
	global_store_short v[16:17], v18, off sc1
	v_add_u32_e32 v16, v182, v32
	v_ashrrev_i32_e32 v17, 31, v16
	v_lshl_add_u64 v[18:19], v[16:17], 1, s[8:9]
	v_or_b32_e32 v16, 0x60, v102
	v_ashrrev_i32_e32 v17, 31, v16
	v_fmac_f32_e32 v44, v20, v112
	v_fmac_f32_e32 v43, v21, v112
	v_fmac_f32_e32 v42, v22, v112
	v_fmac_f32_e32 v41, v23, v112
	v_fmac_f32_e32 v40, v24, v112
	v_fmac_f32_e32 v39, v25, v112
	v_fmac_f32_e32 v35, v29, v112
	v_fmac_f32_e32 v34, v30, v112
	v_fmac_f32_e32 v33, v31, v112
	v_lshlrev_b64 v[20:21], 2, v[16:17]
	global_store_dword v[84:85], v47, off offset:256 sc1
	global_store_dword v[82:83], v46, off offset:256 sc1
	global_store_dword v[78:79], v44, off offset:256 sc1
	global_store_dword v[72:73], v43, off offset:256 sc1
	global_store_dword v[74:75], v42, off offset:256 sc1
	global_store_dword v[76:77], v41, off offset:256 sc1
	global_store_dword v[80:81], v40, off offset:256 sc1
	global_store_dword v[86:87], v39, off offset:256 sc1
	global_store_dword v[90:91], v38, off offset:256 sc1
	global_store_dword v[92:93], v37, off offset:256 sc1
	global_store_dword v[94:95], v36, off offset:256 sc1
	global_store_dword v[96:97], v35, off offset:256 sc1
	global_store_dword v[98:99], v34, off offset:256 sc1
	global_store_dword v[100:101], v33, off offset:256 sc1
	global_store_dword v[104:105], v114, off offset:256 sc1
	v_mul_f32_e32 v26, v48, v44
	v_lshl_add_u64 v[22:23], s[62:63], 0, v[20:21]
	v_lshl_add_u64 v[24:25], s[64:65], 0, v[20:21]
	global_load_dword v29, v[104:105], off offset:384
	global_load_dword v17, v[24:25], off
	global_load_dword v30, v[22:23], off
	v_cvt_pk_bf16_f32 v22, v26, s0
	global_store_short v[18:19], v22, off sc1
	v_lshl_add_u64 v[18:19], s[60:61], 0, v[20:21]
	global_load_dword v102, v[18:19], off
	v_add_u32_e32 v18, v180, v32
	v_ashrrev_i32_e32 v19, 31, v18
	v_mul_f32_e32 v20, v48, v43
	v_lshl_add_u64 v[18:19], v[18:19], 1, s[8:9]
	v_cvt_pk_bf16_f32 v20, v20, s0
	global_store_short v[18:19], v20, off sc1
	v_add_u32_e32 v18, v71, v32
	v_ashrrev_i32_e32 v19, 31, v18
	v_mul_f32_e32 v20, v48, v42
	v_lshl_add_u64 v[18:19], v[18:19], 1, s[8:9]
	v_cvt_pk_bf16_f32 v20, v20, s0
	global_store_short v[18:19], v20, off sc1
	v_add_u32_e32 v18, v181, v32
	v_ashrrev_i32_e32 v19, 31, v18
	v_mul_f32_e32 v20, v48, v41
	v_lshl_add_u64 v[18:19], v[18:19], 1, s[8:9]
	v_cvt_pk_bf16_f32 v20, v20, s0
	global_store_short v[18:19], v20, off sc1
	v_add_u32_e32 v18, v183, v32
	v_ashrrev_i32_e32 v19, 31, v18
	v_mul_f32_e32 v20, v48, v40
	v_lshl_add_u64 v[18:19], v[18:19], 1, s[8:9]
	v_cvt_pk_bf16_f32 v20, v20, s0
	global_store_short v[18:19], v20, off sc1
	v_add_u32_e32 v18, v186, v32
	v_ashrrev_i32_e32 v19, 31, v18
	v_mul_f32_e32 v20, v48, v39
	v_lshl_add_u64 v[18:19], v[18:19], 1, s[8:9]
	v_cvt_pk_bf16_f32 v20, v20, s0
	global_store_short v[18:19], v20, off sc1
	v_add_u32_e32 v18, v188, v32
	v_ashrrev_i32_e32 v19, 31, v18
	v_mul_f32_e32 v20, v48, v38
	v_lshl_add_u64 v[18:19], v[18:19], 1, s[8:9]
	v_cvt_pk_bf16_f32 v20, v20, s0
	global_store_short v[18:19], v20, off sc1
	v_add_u32_e32 v18, v189, v32
	v_ashrrev_i32_e32 v19, 31, v18
	v_mul_f32_e32 v20, v48, v37
	v_lshl_add_u64 v[18:19], v[18:19], 1, s[8:9]
	v_cvt_pk_bf16_f32 v20, v20, s0
	global_store_short v[18:19], v20, off sc1
	v_add_u32_e32 v18, v190, v32
	v_ashrrev_i32_e32 v19, 31, v18
	v_mul_f32_e32 v20, v48, v36
	v_lshl_add_u64 v[18:19], v[18:19], 1, s[8:9]
	v_cvt_pk_bf16_f32 v20, v20, s0
	global_store_short v[18:19], v20, off sc1
	v_add_u32_e32 v18, v192, v32
	v_ashrrev_i32_e32 v19, 31, v18
	v_mul_f32_e32 v20, v48, v35
	v_lshl_add_u64 v[18:19], v[18:19], 1, s[8:9]
	v_cvt_pk_bf16_f32 v20, v20, s0
	global_load_dword v28, v[88:89], off offset:384
	global_load_dword v27, v[84:85], off offset:384
	global_load_dword v25, v[78:79], off offset:384
	global_load_dword v24, v[72:73], off offset:384
	global_load_dword v23, v[74:75], off offset:384
	global_load_dword v21, v[80:81], off offset:384
	global_load_dword v22, v[76:77], off offset:384
	v_fmac_f32_e32 v106, v114, v114
	global_store_short v[18:19], v20, off sc1
	v_add_u32_e32 v18, v193, v32
	v_ashrrev_i32_e32 v19, 31, v18
	v_mul_f32_e32 v20, v48, v34
	v_lshl_add_u64 v[18:19], v[18:19], 1, s[8:9]
	v_cvt_pk_bf16_f32 v20, v20, s0
	global_store_short v[18:19], v20, off sc1
	v_add_u32_e32 v18, v194, v32
	v_ashrrev_i32_e32 v19, 31, v18
	v_mul_f32_e32 v20, v48, v33
	v_lshl_add_u64 v[18:19], v[18:19], 1, s[8:9]
	v_cvt_pk_bf16_f32 v20, v20, s0
	global_store_short v[18:19], v20, off sc1
	global_load_dword v20, v[86:87], off offset:384
	s_waitcnt vmcnt(22)
	v_add_f32_e32 v17, 1.0, v17
	global_load_dword v26, v[82:83], off offset:384
	s_waitcnt vmcnt(22)
	v_mul_f32_e32 v32, v30, v17
	v_add_u32_e32 v18, v191, v16
	s_waitcnt vmcnt(20)
	v_fmac_f32_e32 v29, v0, v102
	v_ashrrev_i32_e32 v19, 31, v18
	v_mul_f32_e32 v0, v32, v29
	v_lshl_add_u64 v[18:19], v[18:19], 1, s[8:9]
	v_cvt_pk_bf16_f32 v0, v0, s0
	global_store_short v[18:19], v0, off sc1
	global_load_dword v19, v[90:91], off offset:384
	v_add_u32_e32 v30, v187, v16
	global_load_dword v18, v[92:93], off offset:384
	v_ashrrev_i32_e32 v31, 31, v30
	v_fmac_f32_e32 v106, v29, v29
	global_store_dword v[104:105], v29, off offset:384 sc1
	s_waitcnt vmcnt(15)
	v_fmac_f32_e32 v28, v1, v102
	v_mul_f32_e32 v17, v32, v28
	v_lshl_add_u64 v[0:1], v[30:31], 1, s[8:9]
	v_cvt_pk_bf16_f32 v17, v17, s0
	global_store_short v[0:1], v17, off sc1
	v_add_u32_e32 v0, v185, v16
	s_waitcnt vmcnt(15)
	v_fmac_f32_e32 v27, v2, v102
	global_load_dword v17, v[94:95], off offset:384
	v_ashrrev_i32_e32 v1, 31, v0
	v_mul_f32_e32 v2, v32, v27
	v_lshl_add_u64 v[0:1], v[0:1], 1, s[8:9]
	v_cvt_pk_bf16_f32 v2, v2, s0
	global_store_short v[0:1], v2, off sc1
	v_add_u32_e32 v0, v184, v16
	global_load_dword v2, v[96:97], off offset:384
	v_ashrrev_i32_e32 v1, 31, v0
	v_lshl_add_u64 v[0:1], v[0:1], 1, s[8:9]
	v_add_u32_e32 v30, v182, v16
	s_waitcnt vmcnt(17)
	v_fmac_f32_e32 v25, v4, v102
	v_ashrrev_i32_e32 v31, 31, v30
	v_lshl_add_u64 v[30:31], v[30:31], 1, s[8:9]
	s_waitcnt vmcnt(16)
	v_fmac_f32_e32 v24, v5, v102
	s_waitcnt vmcnt(15)
	v_fmac_f32_e32 v23, v6, v102
	s_waitcnt vmcnt(8)
	v_fmac_f32_e32 v26, v3, v102
	v_mul_f32_e32 v3, v32, v26
	v_cvt_pk_bf16_f32 v3, v3, s0
	global_store_short v[0:1], v3, off sc1
	global_load_dword v1, v[98:99], off offset:384
	v_mul_f32_e32 v0, v32, v25
	v_cvt_pk_bf16_f32 v0, v0, s0
	global_store_short v[30:31], v0, off sc1
	global_load_dword v0, v[100:101], off offset:384
	v_add_u32_e32 v30, v180, v16
	v_ashrrev_i32_e32 v31, 31, v30
	v_mul_f32_e32 v3, v32, v24
	v_lshl_add_u64 v[4:5], v[30:31], 1, s[8:9]
	v_cvt_pk_bf16_f32 v3, v3, s0
	global_store_short v[4:5], v3, off sc1
	v_add_u32_e32 v4, v71, v16
	v_ashrrev_i32_e32 v5, 31, v4
	v_mul_f32_e32 v3, v32, v23
	v_lshl_add_u64 v[4:5], v[4:5], 1, s[8:9]
	v_cvt_pk_bf16_f32 v3, v3, s0
	global_store_short v[4:5], v3, off sc1
	v_add_u32_e32 v4, v181, v16
	v_fmac_f32_e32 v22, v7, v102
	v_ashrrev_i32_e32 v5, 31, v4
	v_mul_f32_e32 v3, v32, v22
	v_lshl_add_u64 v[4:5], v[4:5], 1, s[8:9]
	v_cvt_pk_bf16_f32 v3, v3, s0
	global_store_short v[4:5], v3, off sc1
	v_add_u32_e32 v4, v183, v16
	v_fmac_f32_e32 v21, v8, v102
	v_ashrrev_i32_e32 v5, 31, v4
	v_mul_f32_e32 v3, v32, v21
	v_lshl_add_u64 v[4:5], v[4:5], 1, s[8:9]
	v_cvt_pk_bf16_f32 v3, v3, s0
	global_store_short v[4:5], v3, off sc1
	v_add_u32_e32 v4, v186, v16
	v_fmac_f32_e32 v20, v9, v102
	v_ashrrev_i32_e32 v5, 31, v4
	v_mul_f32_e32 v3, v32, v20
	v_lshl_add_u64 v[4:5], v[4:5], 1, s[8:9]
	v_cvt_pk_bf16_f32 v3, v3, s0
	global_store_short v[4:5], v3, off sc1
	v_add_u32_e32 v4, v188, v16
	s_waitcnt vmcnt(15)
	v_fmac_f32_e32 v19, v10, v102
	v_ashrrev_i32_e32 v5, 31, v4
	v_mul_f32_e32 v3, v32, v19
	v_lshl_add_u64 v[4:5], v[4:5], 1, s[8:9]
	v_cvt_pk_bf16_f32 v3, v3, s0
	global_store_short v[4:5], v3, off sc1
	v_add_u32_e32 v4, v189, v16
	s_waitcnt vmcnt(15)
	v_fmac_f32_e32 v18, v11, v102
	v_ashrrev_i32_e32 v5, 31, v4
	v_mul_f32_e32 v3, v32, v18
	v_lshl_add_u64 v[4:5], v[4:5], 1, s[8:9]
	v_cvt_pk_bf16_f32 v3, v3, s0
	global_store_short v[4:5], v3, off sc1
	v_add_u32_e32 v4, v190, v16
	v_ashrrev_i32_e32 v5, 31, v4
	v_lshl_add_u64 v[4:5], v[4:5], 1, s[8:9]
	v_ashrrev_i32_e32 v71, 31, v70
	global_store_dword v[88:89], v28, off offset:384 sc1
	global_store_dword v[84:85], v27, off offset:384 sc1
	global_store_dword v[82:83], v26, off offset:384 sc1
	global_store_dword v[78:79], v25, off offset:384 sc1
	s_waitcnt vmcnt(17)
	v_fmac_f32_e32 v17, v12, v102
	v_mul_f32_e32 v3, v32, v17
	v_cvt_pk_bf16_f32 v3, v3, s0
	global_store_short v[4:5], v3, off sc1
	v_add_u32_e32 v4, v192, v16
	v_ashrrev_i32_e32 v5, 31, v4
	v_lshl_add_u64 v[4:5], v[4:5], 1, s[8:9]
	s_waitcnt vmcnt(16)
	v_fmac_f32_e32 v2, v13, v102
	v_mul_f32_e32 v3, v32, v2
	v_cvt_pk_bf16_f32 v3, v3, s0
	global_store_short v[4:5], v3, off sc1
	v_add_u32_e32 v4, v193, v16
	v_ashrrev_i32_e32 v5, 31, v4
	v_lshl_add_u64 v[4:5], v[4:5], 1, s[8:9]
	v_xor_b32_e32 v12, 16, v165
	global_store_dword v[72:73], v24, off offset:384 sc1
	global_store_dword v[74:75], v23, off offset:384 sc1
	global_store_dword v[76:77], v22, off offset:384 sc1
	global_store_dword v[80:81], v21, off offset:384 sc1
	global_store_dword v[86:87], v20, off offset:384 sc1
	s_waitcnt vmcnt(20)
	v_fmac_f32_e32 v1, v14, v102
	v_mul_f32_e32 v3, v32, v1
	v_cvt_pk_bf16_f32 v3, v3, s0
	global_store_short v[4:5], v3, off sc1
	v_add_u32_e32 v4, v194, v16
	v_ashrrev_i32_e32 v5, 31, v4
	v_lshl_add_u64 v[10:11], v[4:5], 1, s[8:9]
	v_and_b32_e32 v4, 64, v165
	v_xor_b32_e32 v3, 1, v165
	v_add_u32_e32 v7, 64, v4
	v_cmp_lt_i32_e32 vcc, v3, v7
	v_xor_b32_e32 v4, 2, v165
	s_waitcnt vmcnt(19)
	v_fmac_f32_e32 v0, v15, v102
	v_cndmask_b32_e32 v3, v165, v3, vcc
	v_lshlrev_b32_e32 v3, 2, v3
	ds_bpermute_b32 v5, v3, v106
	v_cmp_lt_i32_e32 vcc, v4, v7
	global_store_dword v[90:91], v19, off offset:384 sc1
	global_store_dword v[92:93], v18, off offset:384 sc1
	v_cndmask_b32_e32 v4, v165, v4, vcc
	v_lshlrev_b32_e32 v4, 2, v4
	s_waitcnt lgkmcnt(0)
	v_add_f32_e32 v6, v106, v5
	ds_bpermute_b32 v8, v4, v6
	v_xor_b32_e32 v5, 4, v165
	v_cmp_lt_i32_e32 vcc, v5, v7
	global_store_dword v[94:95], v17, off offset:384 sc1
	global_store_dword v[96:97], v2, off offset:384 sc1
	v_cndmask_b32_e32 v5, v165, v5, vcc
	v_lshlrev_b32_e32 v5, 2, v5
	s_waitcnt lgkmcnt(0)
	v_add_f32_e32 v8, v6, v8
	ds_bpermute_b32 v9, v5, v8
	v_xor_b32_e32 v6, 8, v165
	v_cmp_lt_i32_e32 vcc, v6, v7
	global_store_dword v[98:99], v1, off offset:384 sc1
	global_store_dword v[100:101], v0, off offset:384 sc1
	v_cndmask_b32_e32 v6, v165, v6, vcc
	v_lshlrev_b32_e32 v6, 2, v6
	s_waitcnt lgkmcnt(0)
	v_add_f32_e32 v8, v8, v9
	ds_bpermute_b32 v9, v6, v8
	v_cmp_lt_i32_e32 vcc, v12, v7
	s_waitcnt lgkmcnt(0)
	v_add_f32_e32 v8, v8, v9
	v_cndmask_b32_e32 v7, v165, v12, vcc
	v_lshlrev_b32_e32 v7, 2, v7
	ds_bpermute_b32 v9, v7, v8
	v_mul_f32_e32 v12, v32, v0
	v_cvt_pk_bf16_f32 v12, v12, s0
	global_store_short v[10:11], v12, off sc1
	s_and_saveexec_b64 s[60:61], s[0:1]
	s_cbranch_execz .LBB0_1400
	s_waitcnt lgkmcnt(0)
	v_add_f32_e32 v10, v8, v9
	v_lshl_add_u64 v[8:9], v[70:71], 2, s[58:59]
	global_store_dword v[8:9], v10, off sc1

.LBB0_1569:
	s_add_i32 s58, s66, 0xffffe000
	s_lshr_b32 s58, s58, 12
	s_mulk_i32 s58, 0x1800
	v_mov_b32_e32 v70, s70
	s_add_i32 s58, s58, 0xf000
	ds_read_b64 v[70:71], v70
	s_cmp_gt_i32 s6, 63
	s_cselect_b32 s6, s58, 0xd800
	s_lshl_b64 s[58:59], s[6:7], 2
	s_add_u32 s6, s14, s58
	s_addc_u32 s65, s15, s59
	s_waitcnt lgkmcnt(0)
	v_readfirstlane_b32 s58, v70
	v_readfirstlane_b32 s59, v71
	s_add_u32 s60, s58, 0x3000
	s_addc_u32 s61, s59, 0
	s_lshl_b32 s58, s64, 14
	s_add_i32 s58, s58, 0xe0000
	s_ashr_i32 s59, s58, 31
	s_lshl_b64 s[58:59], s[58:59], 2
	s_add_u32 s58, s10, s58
	s_addc_u32 s59, s11, s59
	s_add_u32 s62, s6, 0x5ba2000
	v_or_b32_e32 v102, s68, v138
	v_add_u32_e32 v70, s66, v139
	s_addc_u32 s63, s65, 0
	v_lshlrev_b32_e32 v188, 10, v70
	v_ashrrev_i32_e32 v103, 31, v102
	s_add_u32 s64, s6, 0x5ba4000
	v_lshlrev_b64 v[72:73], 2, v[102:103]
	v_or_b32_e32 v186, 0x400, v188
	v_or_b32_e32 v185, 0x4400, v188
	v_or_b32_e32 v189, 0x4c00, v188
	v_or_b32_e32 v193, 0x6c00, v188
	s_addc_u32 s65, s65, 0
	v_lshl_add_u64 v[74:75], s[62:63], 0, v[72:73]
	v_add_u32_e32 v132, v188, v102
	v_add_u32_e32 v134, v186, v102
	v_or_b32_e32 v184, 0x800, v188
	v_or_b32_e32 v183, 0xc00, v188
	v_or_b32_e32 v181, 0x2000, v188
	v_or_b32_e32 v179, 0x2400, v188
	v_or_b32_e32 v71, 0x2800, v188
	v_or_b32_e32 v180, 0x2c00, v188
	v_or_b32_e32 v182, 0x4000, v188
	v_add_u32_e32 v112, v185, v102
	v_or_b32_e32 v187, 0x4800, v188
	v_add_u32_e32 v118, v189, v102
	v_or_b32_e32 v190, 0x6000, v188
	v_or_b32_e32 v191, 0x6400, v188
	v_or_b32_e32 v192, 0x6800, v188
	v_add_u32_e32 v128, v193, v102
	global_load_dword v194, v[74:75], off
	global_load_dword v204, v[74:75], off offset:128
	global_load_dword v223, v[74:75], off offset:256
	v_lshl_add_u64 v[74:75], s[60:61], 0, v[72:73]
	v_lshl_add_u64 v[72:73], s[64:65], 0, v[72:73]
	v_ashrrev_i32_e32 v135, 31, v134
	v_add_u32_e32 v136, v184, v102
	v_add_u32_e32 v130, v183, v102
	v_add_u32_e32 v122, v181, v102
	v_add_u32_e32 v114, v179, v102
	v_add_u32_e32 v106, v71, v102
	v_add_u32_e32 v108, v180, v102
	v_add_u32_e32 v110, v182, v102
	v_ashrrev_i32_e32 v113, 31, v112
	v_add_u32_e32 v116, v187, v102
	v_ashrrev_i32_e32 v119, 31, v118
	v_add_u32_e32 v120, v190, v102
	v_add_u32_e32 v124, v191, v102
	v_add_u32_e32 v126, v192, v102
	v_ashrrev_i32_e32 v129, 31, v128
	v_ashrrev_i32_e32 v133, 31, v132
	global_load_dword v196, v[72:73], off
	global_load_dword v202, v[72:73], off offset:128
	global_load_dword v221, v[72:73], off offset:256
	v_lshl_add_u64 v[88:89], v[134:135], 2, s[12:13]
	v_ashrrev_i32_e32 v137, 31, v136
	v_ashrrev_i32_e32 v131, 31, v130
	v_ashrrev_i32_e32 v123, 31, v122
	v_ashrrev_i32_e32 v115, 31, v114
	v_ashrrev_i32_e32 v107, 31, v106
	v_ashrrev_i32_e32 v109, 31, v108
	v_ashrrev_i32_e32 v111, 31, v110
	v_lshl_add_u64 v[86:87], v[112:113], 2, s[12:13]
	v_ashrrev_i32_e32 v117, 31, v116
	v_lshl_add_u64 v[92:93], v[118:119], 2, s[12:13]
	v_ashrrev_i32_e32 v121, 31, v120
	v_ashrrev_i32_e32 v125, 31, v124
	v_ashrrev_i32_e32 v127, 31, v126
	v_lshl_add_u64 v[100:101], v[128:129], 2, s[12:13]
	v_lshl_add_u64 v[104:105], v[132:133], 2, s[12:13]
	global_load_dword v195, v[74:75], off
	global_load_dword v203, v[74:75], off offset:128
	global_load_dword v222, v[74:75], off offset:256
	v_lshl_add_u64 v[84:85], v[136:137], 2, s[12:13]
	v_lshl_add_u64 v[82:83], v[130:131], 2, s[12:13]
	v_lshl_add_u64 v[78:79], v[122:123], 2, s[12:13]
	v_lshl_add_u64 v[72:73], v[114:115], 2, s[12:13]
	v_lshl_add_u64 v[74:75], v[106:107], 2, s[12:13]
	v_lshl_add_u64 v[76:77], v[108:109], 2, s[12:13]
	v_lshl_add_u64 v[80:81], v[110:111], 2, s[12:13]
	global_load_dword v178, v[88:89], off
	global_load_dword v177, v[84:85], off
	global_load_dword v176, v[82:83], off
	global_load_dword v175, v[78:79], off
	global_load_dword v174, v[72:73], off
	global_load_dword v173, v[74:75], off
	global_load_dword v172, v[76:77], off
	global_load_dword v171, v[80:81], off
	v_lshl_add_u64 v[90:91], v[116:117], 2, s[12:13]
	global_load_dword v170, v[86:87], off
	global_load_dword v168, v[90:91], off
	v_lshl_add_u64 v[94:95], v[120:121], 2, s[12:13]
	v_lshl_add_u64 v[96:97], v[124:125], 2, s[12:13]
	v_lshl_add_u64 v[98:99], v[126:127], 2, s[12:13]
	global_load_dword v169, v[92:93], off
	global_load_dword v167, v[94:95], off
	global_load_dword v166, v[96:97], off
	global_load_dword v165, v[98:99], off
	global_load_dword v103, v[100:101], off
	global_load_dword v197, v[104:105], off
	v_lshl_add_u64 v[106:107], v[106:107], 1, s[8:9]
	global_load_dword v198, v[104:105], off offset:128
	global_load_dword v205, v[84:85], off offset:128
	global_load_dword v206, v[78:79], off offset:128
	global_load_dword v207, v[72:73], off offset:128
	global_load_dword v208, v[74:75], off offset:128
	global_load_dword v209, v[80:81], off offset:128
	global_load_dword v210, v[76:77], off offset:128
	global_load_dword v211, v[86:87], off offset:128
	global_load_dword v212, v[82:83], off offset:128
	global_load_dword v213, v[90:91], off offset:128
	global_load_dword v214, v[92:93], off offset:128
	global_load_dword v215, v[94:95], off offset:128
	global_load_dword v216, v[96:97], off offset:128
	global_load_dword v217, v[98:99], off offset:128
	global_load_dword v218, v[100:101], off offset:128
	global_load_dword v219, v[88:89], off offset:128
	global_load_dword v220, v[88:89], off offset:256
	global_load_dword v224, v[90:91], off offset:256
	global_load_dword v225, v[92:93], off offset:256
	global_load_dword v226, v[94:95], off offset:256
	global_load_dword v227, v[104:105], off offset:256
	global_load_dword v229, v[84:85], off offset:256
	global_load_dword v230, v[86:87], off offset:256
	global_load_dword v231, v[82:83], off offset:256
	global_load_dword v232, v[78:79], off offset:256
	global_load_dword v233, v[72:73], off offset:256
	global_load_dword v234, v[74:75], off offset:256
	global_load_dword v235, v[80:81], off offset:256
	global_load_dword v236, v[76:77], off offset:256
	global_load_dword v237, v[96:97], off offset:256
	global_load_dword v238, v[98:99], off offset:256
	global_load_dword v239, v[100:101], off offset:256
	s_waitcnt vmcnt(0)
	v_add_f32_e32 v196, 1.0, v196
	v_mul_f32_e32 v195, v195, v196
	v_fmac_f32_e32 v178, v49, v194
	v_fmac_f32_e32 v177, v50, v194
	v_fmac_f32_e32 v176, v51, v194
	v_fmac_f32_e32 v175, v52, v194
	v_fmac_f32_e32 v174, v53, v194
	v_fmac_f32_e32 v173, v54, v194
	v_fmac_f32_e32 v172, v55, v194
	v_fmac_f32_e32 v171, v56, v194
	v_fmac_f32_e32 v170, v57, v194
	v_fmac_f32_e32 v168, v58, v194
	v_fmac_f32_e32 v169, v59, v194
	v_fmac_f32_e32 v167, v60, v194
	v_fmac_f32_e32 v166, v61, v194
	v_fmac_f32_e32 v165, v62, v194
	v_fmac_f32_e32 v103, v63, v194
	v_fmac_f32_e32 v197, v48, v194
	v_mul_f32_e32 v48, v195, v197
	v_cvt_pk_bf16_f32 v58, v48, s0
	v_or_b32_e32 v48, 32, v102
	v_ashrrev_i32_e32 v49, 31, v48
	v_lshlrev_b64 v[52:53], 2, v[48:49]
	global_store_dword v[88:89], v178, off sc1
	global_store_dword v[84:85], v177, off sc1
	global_store_dword v[82:83], v176, off sc1
	global_store_dword v[78:79], v175, off sc1
	global_store_dword v[72:73], v174, off sc1
	global_store_dword v[74:75], v173, off sc1
	global_store_dword v[76:77], v172, off sc1
	global_store_dword v[80:81], v171, off sc1
	global_store_dword v[86:87], v170, off sc1
	global_store_dword v[90:91], v168, off sc1
	global_store_dword v[92:93], v169, off sc1
	global_store_dword v[94:95], v167, off sc1
	global_store_dword v[96:97], v166, off sc1
	global_store_dword v[98:99], v165, off sc1
	global_store_dword v[100:101], v103, off sc1
	global_store_dword v[104:105], v197, off sc1
	v_lshl_add_u64 v[50:51], v[132:133], 1, s[8:9]
	v_lshl_add_u64 v[56:57], s[64:65], 0, v[52:53]
	v_mov_b32_e32 v196, v198
	v_lshl_add_u64 v[54:55], s[60:61], 0, v[52:53]
	v_mov_b32_e32 v132, v202
	v_mov_b32_e32 v133, v203
	v_mul_f32_e32 v49, v195, v178
	global_store_short v[50:51], v58, off sc1
	v_lshl_add_u64 v[50:51], s[62:63], 0, v[52:53]
	v_mov_b32_e32 v194, v204
	v_cvt_pk_bf16_f32 v49, v49, s0
	v_lshl_add_u64 v[50:51], v[134:135], 1, s[8:9]
	global_store_short v[50:51], v49, off sc1
	v_mul_f32_e32 v49, v195, v177
	v_cvt_pk_bf16_f32 v49, v49, s0
	v_lshl_add_u64 v[50:51], v[136:137], 1, s[8:9]
	global_store_short v[50:51], v49, off sc1
	v_mul_f32_e32 v49, v195, v176
	v_cvt_pk_bf16_f32 v49, v49, s0
	v_lshl_add_u64 v[50:51], v[130:131], 1, s[8:9]
	global_store_short v[50:51], v49, off sc1
	v_mul_f32_e32 v49, v195, v175
	v_cvt_pk_bf16_f32 v49, v49, s0
	v_lshl_add_u64 v[50:51], v[122:123], 1, s[8:9]
	global_store_short v[50:51], v49, off sc1
	v_mul_f32_e32 v49, v195, v174
	v_cvt_pk_bf16_f32 v49, v49, s0
	v_lshl_add_u64 v[50:51], v[114:115], 1, s[8:9]
	global_store_short v[50:51], v49, off sc1
	v_mul_f32_e32 v49, v195, v173
	v_mov_b32_e32 v62, v205
	v_mov_b32_e32 v60, v206
	v_mov_b32_e32 v59, v207
	v_mov_b32_e32 v58, v208
	v_mov_b32_e32 v56, v209
	v_mov_b32_e32 v57, v210
	v_mov_b32_e32 v55, v211
	v_mov_b32_e32 v61, v212
	v_mov_b32_e32 v54, v213
	v_mov_b32_e32 v53, v214
	v_mov_b32_e32 v52, v215
	v_mov_b32_e32 v51, v216
	v_mov_b32_e32 v50, v217
	v_cvt_pk_bf16_f32 v63, v49, s0
	v_mov_b32_e32 v49, v218
	v_fmac_f32_e32 v196, v32, v194
	global_store_short v[106:107], v63, off sc1
	v_mov_b32_e32 v63, v219
	v_mul_f32_e32 v106, v195, v172
	v_cvt_pk_bf16_f32 v114, v106, s0
	v_lshl_add_u64 v[106:107], v[108:109], 1, s[8:9]
	global_store_short v[106:107], v114, off sc1
	v_mul_f32_e32 v106, v195, v171
	v_cvt_pk_bf16_f32 v108, v106, s0
	v_lshl_add_u64 v[106:107], v[110:111], 1, s[8:9]
	global_store_short v[106:107], v108, off sc1
	v_mul_f32_e32 v106, v195, v170
	v_cvt_pk_bf16_f32 v108, v106, s0
	v_lshl_add_u64 v[106:107], v[112:113], 1, s[8:9]
	global_store_short v[106:107], v108, off sc1
	v_mul_f32_e32 v106, v195, v168
	v_cvt_pk_bf16_f32 v108, v106, s0
	v_lshl_add_u64 v[106:107], v[116:117], 1, s[8:9]
	global_store_short v[106:107], v108, off sc1
	v_mul_f32_e32 v106, v195, v169
	v_cvt_pk_bf16_f32 v108, v106, s0
	v_lshl_add_u64 v[106:107], v[118:119], 1, s[8:9]
	global_store_short v[106:107], v108, off sc1
	v_mul_f32_e32 v106, v195, v167
	v_cvt_pk_bf16_f32 v108, v106, s0
	v_lshl_add_u64 v[106:107], v[120:121], 1, s[8:9]
	global_store_short v[106:107], v108, off sc1
	v_mul_f32_e32 v106, v195, v166
	v_cvt_pk_bf16_f32 v108, v106, s0
	v_lshl_add_u64 v[106:107], v[124:125], 1, s[8:9]
	global_store_short v[106:107], v108, off sc1
	v_mul_f32_e32 v106, v195, v165
	v_cvt_pk_bf16_f32 v108, v106, s0
	v_lshl_add_u64 v[106:107], v[126:127], 1, s[8:9]
	global_store_short v[106:107], v108, off sc1
	v_mul_f32_e32 v106, v195, v103
	v_cvt_pk_bf16_f32 v108, v106, s0
	v_lshl_add_u64 v[106:107], v[128:129], 1, s[8:9]
	global_store_short v[106:107], v108, off sc1
	v_add_f32_e32 v106, 1.0, v132
	v_mul_f32_e32 v110, v133, v106
	v_add_u32_e32 v106, v188, v48
	v_fmac_f32_e32 v62, v34, v194
	v_fmac_f32_e32 v61, v35, v194
	v_fmac_f32_e32 v60, v36, v194
	v_fmac_f32_e32 v59, v37, v194
	v_fmac_f32_e32 v58, v38, v194
	v_fmac_f32_e32 v57, v39, v194
	v_fmac_f32_e32 v56, v40, v194
	v_fmac_f32_e32 v55, v41, v194
	v_fmac_f32_e32 v54, v42, v194
	v_fmac_f32_e32 v53, v43, v194
	v_fmac_f32_e32 v52, v44, v194
	v_fmac_f32_e32 v51, v45, v194
	v_fmac_f32_e32 v50, v46, v194
	v_fmac_f32_e32 v49, v47, v194
	v_ashrrev_i32_e32 v107, 31, v106
	global_store_dword v[104:105], v196, off offset:128 sc1
	v_mul_f32_e32 v32, v110, v196
	global_store_dword v[84:85], v62, off offset:128 sc1
	global_store_dword v[82:83], v61, off offset:128 sc1
	global_store_dword v[78:79], v60, off offset:128 sc1
	global_store_dword v[72:73], v59, off offset:128 sc1
	global_store_dword v[74:75], v58, off offset:128 sc1
	global_store_dword v[76:77], v57, off offset:128 sc1
	global_store_dword v[80:81], v56, off offset:128 sc1
	global_store_dword v[86:87], v55, off offset:128 sc1
	global_store_dword v[90:91], v54, off offset:128 sc1
	global_store_dword v[92:93], v53, off offset:128 sc1
	global_store_dword v[94:95], v52, off offset:128 sc1
	global_store_dword v[96:97], v51, off offset:128 sc1
	global_store_dword v[98:99], v50, off offset:128 sc1
	global_store_dword v[100:101], v49, off offset:128 sc1
	v_cvt_pk_bf16_f32 v32, v32, s0
	v_lshl_add_u64 v[106:107], v[106:107], 1, s[8:9]
	v_add_u32_e32 v108, v186, v48
	v_mov_b32_e32 v45, v220
	v_ashrrev_i32_e32 v109, 31, v108
	global_store_short v[106:107], v32, off sc1
	v_mul_f32_e32 v113, v110, v56
	v_cvt_pk_bf16_f32 v113, v113, s0
	v_mul_f32_e32 v106, v196, v196
	v_fmac_f32_e32 v63, v33, v194
	v_mul_f32_e32 v32, v110, v63
	v_cvt_pk_bf16_f32 v34, v32, s0
	v_lshl_add_u64 v[32:33], v[108:109], 1, s[8:9]
	global_store_short v[32:33], v34, off sc1
	v_add_u32_e32 v32, v184, v48
	v_ashrrev_i32_e32 v33, 31, v32
	v_mul_f32_e32 v34, v110, v62
	v_cvt_pk_bf16_f32 v34, v34, s0
	v_lshl_add_u64 v[32:33], v[32:33], 1, s[8:9]
	global_store_short v[32:33], v34, off sc1
	v_add_u32_e32 v32, v183, v48
	v_ashrrev_i32_e32 v33, 31, v32
	v_mul_f32_e32 v34, v110, v61
	v_cvt_pk_bf16_f32 v34, v34, s0
	v_lshl_add_u64 v[32:33], v[32:33], 1, s[8:9]
	global_store_short v[32:33], v34, off sc1
	v_add_u32_e32 v32, v181, v48
	v_ashrrev_i32_e32 v33, 31, v32
	v_mul_f32_e32 v34, v110, v60
	v_cvt_pk_bf16_f32 v34, v34, s0
	v_lshl_add_u64 v[32:33], v[32:33], 1, s[8:9]
	global_store_short v[32:33], v34, off sc1
	v_add_u32_e32 v32, v179, v48
	v_ashrrev_i32_e32 v33, 31, v32
	v_mul_f32_e32 v34, v110, v59
	v_cvt_pk_bf16_f32 v42, v34, s0
	v_lshl_add_u64 v[34:35], v[32:33], 1, s[8:9]
	v_or_b32_e32 v32, 64, v102
	v_ashrrev_i32_e32 v33, 31, v32
	v_lshlrev_b64 v[36:37], 2, v[32:33]
	global_store_dword v[88:89], v63, off offset:128 sc1
	v_lshl_add_u64 v[40:41], s[64:65], 0, v[36:37]
	v_lshl_add_u64 v[38:39], s[60:61], 0, v[36:37]
	v_mov_b32_e32 v107, v221
	v_mov_b32_e32 v111, v222
	v_mul_f32_e32 v33, v110, v58
	global_store_short v[34:35], v42, off sc1
	v_lshl_add_u64 v[34:35], s[62:63], 0, v[36:37]
	v_mov_b32_e32 v112, v223
	v_add_u32_e32 v34, v71, v48
	v_ashrrev_i32_e32 v35, 31, v34
	v_cvt_pk_bf16_f32 v33, v33, s0
	v_lshl_add_u64 v[34:35], v[34:35], 1, s[8:9]
	global_store_short v[34:35], v33, off sc1
	v_add_u32_e32 v34, v180, v48
	v_ashrrev_i32_e32 v35, 31, v34
	v_mul_f32_e32 v33, v110, v57
	v_cvt_pk_bf16_f32 v33, v33, s0
	v_lshl_add_u64 v[34:35], v[34:35], 1, s[8:9]
	v_mov_b32_e32 v38, v224
	v_mov_b32_e32 v37, v225
	v_mov_b32_e32 v36, v226
	v_mov_b32_e32 v114, v227
	v_mov_b32_e32 v47, v229
	v_mov_b32_e32 v39, v230
	v_mov_b32_e32 v46, v231
	v_mov_b32_e32 v44, v232
	v_mov_b32_e32 v43, v233
	v_mov_b32_e32 v42, v234
	v_mov_b32_e32 v40, v235
	v_mov_b32_e32 v41, v236
	v_add_u32_e32 v108, v182, v48
	global_store_short v[34:35], v33, off sc1
	v_mov_b32_e32 v35, v237
	v_ashrrev_i32_e32 v109, 31, v108
	v_mov_b32_e32 v34, v238
	v_mov_b32_e32 v33, v239
	v_lshl_add_u64 v[108:109], v[108:109], 1, s[8:9]
	global_store_short v[108:109], v113, off sc1
	v_add_u32_e32 v108, v185, v48
	v_ashrrev_i32_e32 v109, 31, v108
	v_mul_f32_e32 v113, v110, v55
	v_cvt_pk_bf16_f32 v113, v113, s0
	v_lshl_add_u64 v[108:109], v[108:109], 1, s[8:9]
	global_store_short v[108:109], v113, off sc1
	v_add_u32_e32 v108, v187, v48
	v_ashrrev_i32_e32 v109, 31, v108
	v_mul_f32_e32 v113, v110, v54
	v_cvt_pk_bf16_f32 v113, v113, s0
	v_lshl_add_u64 v[108:109], v[108:109], 1, s[8:9]
	global_store_short v[108:109], v113, off sc1
	v_add_u32_e32 v108, v189, v48
	v_ashrrev_i32_e32 v109, 31, v108
	v_mul_f32_e32 v113, v110, v53
	v_cvt_pk_bf16_f32 v113, v113, s0
	v_lshl_add_u64 v[108:109], v[108:109], 1, s[8:9]
	global_store_short v[108:109], v113, off sc1
	v_add_u32_e32 v108, v190, v48
	v_ashrrev_i32_e32 v109, 31, v108
	v_mul_f32_e32 v113, v110, v52
	v_cvt_pk_bf16_f32 v113, v113, s0
	v_lshl_add_u64 v[108:109], v[108:109], 1, s[8:9]
	global_store_short v[108:109], v113, off sc1
	v_add_u32_e32 v108, v191, v48
	v_ashrrev_i32_e32 v109, 31, v108
	v_mul_f32_e32 v113, v110, v51
	v_cvt_pk_bf16_f32 v113, v113, s0
	v_lshl_add_u64 v[108:109], v[108:109], 1, s[8:9]
	global_store_short v[108:109], v113, off sc1
	v_add_u32_e32 v108, v192, v48
	v_ashrrev_i32_e32 v109, 31, v108
	v_mul_f32_e32 v113, v110, v50
	v_cvt_pk_bf16_f32 v113, v113, s0
	v_lshl_add_u64 v[108:109], v[108:109], 1, s[8:9]
	global_store_short v[108:109], v113, off sc1
	v_add_u32_e32 v108, v193, v48
	v_ashrrev_i32_e32 v109, 31, v108
	v_mul_f32_e32 v48, v110, v49
	v_cvt_pk_bf16_f32 v48, v48, s0
	v_lshl_add_u64 v[108:109], v[108:109], 1, s[8:9]
	global_store_short v[108:109], v48, off sc1
	v_add_u32_e32 v108, v188, v32
	v_ashrrev_i32_e32 v109, 31, v108
	v_add_f32_e32 v48, 1.0, v107
	v_mul_f32_e32 v48, v111, v48
	v_fmac_f32_e32 v106, v197, v197
	v_fmac_f32_e32 v45, v17, v112
	global_store_dword v[88:89], v45, off offset:256 sc1
	v_fmac_f32_e32 v38, v26, v112
	v_fmac_f32_e32 v37, v27, v112
	v_fmac_f32_e32 v36, v28, v112
	v_fmac_f32_e32 v114, v16, v112
	v_mul_f32_e32 v16, v48, v114
	v_fmac_f32_e32 v47, v18, v112
	v_cvt_pk_bf16_f32 v18, v16, s0
	v_lshl_add_u64 v[16:17], v[108:109], 1, s[8:9]
	global_store_short v[16:17], v18, off sc1
	v_add_u32_e32 v16, v186, v32
	v_ashrrev_i32_e32 v17, 31, v16
	v_mul_f32_e32 v18, v48, v45
	v_cvt_pk_bf16_f32 v18, v18, s0
	v_lshl_add_u64 v[16:17], v[16:17], 1, s[8:9]
	global_store_short v[16:17], v18, off sc1
	v_add_u32_e32 v16, v184, v32
	v_ashrrev_i32_e32 v17, 31, v16
	v_mul_f32_e32 v18, v48, v47
	v_cvt_pk_bf16_f32 v18, v18, s0
	v_lshl_add_u64 v[16:17], v[16:17], 1, s[8:9]
	v_fmac_f32_e32 v46, v19, v112
	global_store_short v[16:17], v18, off sc1
	v_add_u32_e32 v16, v183, v32
	v_ashrrev_i32_e32 v17, 31, v16
	v_mul_f32_e32 v18, v48, v46
	v_fmac_f32_e32 v44, v20, v112
	v_cvt_pk_bf16_f32 v18, v18, s0
	v_lshl_add_u64 v[16:17], v[16:17], 1, s[8:9]
	global_store_short v[16:17], v18, off sc1
	v_mul_f32_e32 v16, v48, v44
	v_cvt_pk_bf16_f32 v26, v16, s0
	v_or_b32_e32 v16, 0x60, v102
	v_add_u32_e32 v18, v181, v32
	v_ashrrev_i32_e32 v17, 31, v16
	v_fmac_f32_e32 v43, v21, v112
	v_fmac_f32_e32 v42, v22, v112
	v_fmac_f32_e32 v41, v23, v112
	v_fmac_f32_e32 v40, v24, v112
	v_fmac_f32_e32 v39, v25, v112
	v_fmac_f32_e32 v35, v29, v112
	v_fmac_f32_e32 v34, v30, v112
	v_fmac_f32_e32 v33, v31, v112
	v_ashrrev_i32_e32 v19, 31, v18
	v_lshlrev_b64 v[20:21], 2, v[16:17]
	global_store_dword v[84:85], v47, off offset:256 sc1
	global_store_dword v[82:83], v46, off offset:256 sc1
	global_store_dword v[78:79], v44, off offset:256 sc1
	global_store_dword v[72:73], v43, off offset:256 sc1
	global_store_dword v[74:75], v42, off offset:256 sc1
	global_store_dword v[76:77], v41, off offset:256 sc1
	global_store_dword v[80:81], v40, off offset:256 sc1
	global_store_dword v[86:87], v39, off offset:256 sc1
	global_store_dword v[90:91], v38, off offset:256 sc1
	global_store_dword v[92:93], v37, off offset:256 sc1
	global_store_dword v[94:95], v36, off offset:256 sc1
	global_store_dword v[96:97], v35, off offset:256 sc1
	global_store_dword v[98:99], v34, off offset:256 sc1
	global_store_dword v[100:101], v33, off offset:256 sc1
	global_store_dword v[104:105], v114, off offset:256 sc1
	v_lshl_add_u64 v[24:25], s[64:65], 0, v[20:21]
	v_lshl_add_u64 v[18:19], v[18:19], 1, s[8:9]
	global_load_dword v29, v[104:105], off offset:384
	v_lshl_add_u64 v[22:23], s[60:61], 0, v[20:21]
	global_load_dword v17, v[24:25], off
	global_load_dword v30, v[22:23], off
	global_load_dword v28, v[88:89], off offset:384
	global_load_dword v27, v[84:85], off offset:384
	v_fmac_f32_e32 v106, v114, v114
	global_store_short v[18:19], v26, off sc1
	v_lshl_add_u64 v[18:19], s[62:63], 0, v[20:21]
	global_load_dword v102, v[18:19], off
	v_add_u32_e32 v18, v179, v32
	v_ashrrev_i32_e32 v19, 31, v18
	v_mul_f32_e32 v20, v48, v43
	v_cvt_pk_bf16_f32 v20, v20, s0
	v_lshl_add_u64 v[18:19], v[18:19], 1, s[8:9]
	global_store_short v[18:19], v20, off sc1
	v_add_u32_e32 v18, v71, v32
	v_ashrrev_i32_e32 v19, 31, v18
	v_mul_f32_e32 v20, v48, v42
	v_cvt_pk_bf16_f32 v20, v20, s0
	v_lshl_add_u64 v[18:19], v[18:19], 1, s[8:9]
	global_store_short v[18:19], v20, off sc1
	v_add_u32_e32 v18, v180, v32
	v_ashrrev_i32_e32 v19, 31, v18
	v_mul_f32_e32 v20, v48, v41
	v_cvt_pk_bf16_f32 v20, v20, s0
	v_lshl_add_u64 v[18:19], v[18:19], 1, s[8:9]
	global_store_short v[18:19], v20, off sc1
	v_add_u32_e32 v18, v182, v32
	v_ashrrev_i32_e32 v19, 31, v18
	v_mul_f32_e32 v20, v48, v40
	v_cvt_pk_bf16_f32 v20, v20, s0
	v_lshl_add_u64 v[18:19], v[18:19], 1, s[8:9]
	global_store_short v[18:19], v20, off sc1
	v_add_u32_e32 v18, v185, v32
	v_ashrrev_i32_e32 v19, 31, v18
	v_mul_f32_e32 v20, v48, v39
	v_cvt_pk_bf16_f32 v20, v20, s0
	v_lshl_add_u64 v[18:19], v[18:19], 1, s[8:9]
	global_store_short v[18:19], v20, off sc1
	v_add_u32_e32 v18, v187, v32
	v_ashrrev_i32_e32 v19, 31, v18
	v_mul_f32_e32 v20, v48, v38
	v_cvt_pk_bf16_f32 v20, v20, s0
	v_lshl_add_u64 v[18:19], v[18:19], 1, s[8:9]
	global_store_short v[18:19], v20, off sc1
	v_add_u32_e32 v18, v189, v32
	v_ashrrev_i32_e32 v19, 31, v18
	v_mul_f32_e32 v20, v48, v37
	v_cvt_pk_bf16_f32 v20, v20, s0
	v_lshl_add_u64 v[18:19], v[18:19], 1, s[8:9]
	global_store_short v[18:19], v20, off sc1
	v_add_u32_e32 v18, v190, v32
	v_ashrrev_i32_e32 v19, 31, v18
	v_mul_f32_e32 v20, v48, v36
	v_cvt_pk_bf16_f32 v20, v20, s0
	v_lshl_add_u64 v[18:19], v[18:19], 1, s[8:9]
	global_store_short v[18:19], v20, off sc1
	v_add_u32_e32 v18, v191, v32
	v_ashrrev_i32_e32 v19, 31, v18
	v_mul_f32_e32 v20, v48, v35
	v_cvt_pk_bf16_f32 v20, v20, s0
	v_lshl_add_u64 v[18:19], v[18:19], 1, s[8:9]
	global_store_short v[18:19], v20, off sc1
	v_add_u32_e32 v18, v192, v32
	v_ashrrev_i32_e32 v19, 31, v18
	v_mul_f32_e32 v20, v48, v34
	v_cvt_pk_bf16_f32 v20, v20, s0
	v_lshl_add_u64 v[18:19], v[18:19], 1, s[8:9]
	global_store_short v[18:19], v20, off sc1
	v_add_u32_e32 v18, v193, v32
	v_ashrrev_i32_e32 v19, 31, v18
	v_mul_f32_e32 v20, v48, v33
	v_cvt_pk_bf16_f32 v20, v20, s0
	v_lshl_add_u64 v[18:19], v[18:19], 1, s[8:9]
	global_store_short v[18:19], v20, off sc1
	global_load_dword v20, v[86:87], off offset:384
	v_add_u32_e32 v18, v188, v16
	global_load_dword v26, v[82:83], off offset:384
	global_load_dword v25, v[78:79], off offset:384
	global_load_dword v24, v[72:73], off offset:384
	global_load_dword v23, v[74:75], off offset:384
	global_load_dword v21, v[80:81], off offset:384
	global_load_dword v22, v[76:77], off offset:384
	s_waitcnt vmcnt(23)
	v_add_f32_e32 v17, 1.0, v17
	s_waitcnt vmcnt(22)
	v_mul_f32_e32 v32, v30, v17
	v_ashrrev_i32_e32 v19, 31, v18
	v_lshl_add_u64 v[18:19], v[18:19], 1, s[8:9]
	v_add_u32_e32 v30, v186, v16
	s_waitcnt vmcnt(18)
	v_fmac_f32_e32 v29, v0, v102
	v_mul_f32_e32 v0, v32, v29
	v_cvt_pk_bf16_f32 v0, v0, s0
	global_store_short v[18:19], v0, off sc1
	global_load_dword v19, v[90:91], off offset:384
	v_ashrrev_i32_e32 v31, 31, v30
	global_load_dword v18, v[92:93], off offset:384
	v_fmac_f32_e32 v28, v1, v102
	v_mul_f32_e32 v0, v32, v28
	v_cvt_pk_bf16_f32 v17, v0, s0
	v_lshl_add_u64 v[0:1], v[30:31], 1, s[8:9]
	global_store_short v[0:1], v17, off sc1
	v_add_u32_e32 v0, v184, v16
	v_fmac_f32_e32 v27, v2, v102
	global_load_dword v17, v[94:95], off offset:384
	v_ashrrev_i32_e32 v1, 31, v0
	v_mul_f32_e32 v2, v32, v27
	v_cvt_pk_bf16_f32 v2, v2, s0
	v_lshl_add_u64 v[0:1], v[0:1], 1, s[8:9]
	global_store_short v[0:1], v2, off sc1
	v_add_u32_e32 v0, v183, v16
	global_load_dword v2, v[96:97], off offset:384
	v_ashrrev_i32_e32 v1, 31, v0
	v_lshl_add_u64 v[0:1], v[0:1], 1, s[8:9]
	v_add_u32_e32 v30, v181, v16
	v_ashrrev_i32_e32 v31, 31, v30
	v_lshl_add_u64 v[30:31], v[30:31], 1, s[8:9]
	v_fmac_f32_e32 v106, v29, v29
	global_store_dword v[104:105], v29, off offset:384 sc1
	global_store_dword v[88:89], v28, off offset:384 sc1
	global_store_dword v[84:85], v27, off offset:384 sc1
	s_waitcnt vmcnt(16)
	v_fmac_f32_e32 v20, v9, v102
	global_store_dword v[86:87], v20, off offset:384 sc1
	s_waitcnt vmcnt(16)
	v_fmac_f32_e32 v26, v3, v102
	v_mul_f32_e32 v3, v32, v26
	v_cvt_pk_bf16_f32 v3, v3, s0
	global_store_short v[0:1], v3, off sc1
	global_load_dword v1, v[98:99], off offset:384
	s_waitcnt vmcnt(17)
	v_fmac_f32_e32 v25, v4, v102
	v_mul_f32_e32 v0, v32, v25
	v_cvt_pk_bf16_f32 v0, v0, s0
	global_store_short v[30:31], v0, off sc1
	global_load_dword v0, v[100:101], off offset:384
	v_add_u32_e32 v30, v179, v16
	s_waitcnt vmcnt(18)
	v_fmac_f32_e32 v24, v5, v102
	v_ashrrev_i32_e32 v31, 31, v30
	v_mul_f32_e32 v3, v32, v24
	v_cvt_pk_bf16_f32 v3, v3, s0
	v_lshl_add_u64 v[4:5], v[30:31], 1, s[8:9]
	global_store_short v[4:5], v3, off sc1
	v_add_u32_e32 v4, v71, v16
	s_waitcnt vmcnt(18)
	v_fmac_f32_e32 v23, v6, v102
	v_ashrrev_i32_e32 v5, 31, v4
	v_mul_f32_e32 v3, v32, v23
	v_cvt_pk_bf16_f32 v3, v3, s0
	v_lshl_add_u64 v[4:5], v[4:5], 1, s[8:9]
	global_store_short v[4:5], v3, off sc1
	v_add_u32_e32 v4, v180, v16
	s_waitcnt vmcnt(17)
	v_fmac_f32_e32 v22, v7, v102
	v_ashrrev_i32_e32 v5, 31, v4
	v_mul_f32_e32 v3, v32, v22
	v_cvt_pk_bf16_f32 v3, v3, s0
	v_lshl_add_u64 v[4:5], v[4:5], 1, s[8:9]
	global_store_short v[4:5], v3, off sc1
	v_add_u32_e32 v4, v182, v16
	v_fmac_f32_e32 v21, v8, v102
	v_ashrrev_i32_e32 v5, 31, v4
	v_mul_f32_e32 v3, v32, v21
	v_cvt_pk_bf16_f32 v3, v3, s0
	v_lshl_add_u64 v[4:5], v[4:5], 1, s[8:9]
	global_store_short v[4:5], v3, off sc1
	v_add_u32_e32 v4, v185, v16
	v_ashrrev_i32_e32 v5, 31, v4
	v_mul_f32_e32 v3, v32, v20
	v_cvt_pk_bf16_f32 v3, v3, s0
	v_lshl_add_u64 v[4:5], v[4:5], 1, s[8:9]
	global_store_short v[4:5], v3, off sc1
	v_add_u32_e32 v4, v187, v16
	s_waitcnt vmcnt(18)
	v_fmac_f32_e32 v19, v10, v102
	v_ashrrev_i32_e32 v5, 31, v4
	v_mul_f32_e32 v3, v32, v19
	v_cvt_pk_bf16_f32 v3, v3, s0
	v_lshl_add_u64 v[4:5], v[4:5], 1, s[8:9]
	global_store_short v[4:5], v3, off sc1
	v_add_u32_e32 v4, v189, v16
	s_waitcnt vmcnt(18)
	v_fmac_f32_e32 v18, v11, v102
	v_ashrrev_i32_e32 v5, 31, v4
	v_mul_f32_e32 v3, v32, v18
	v_cvt_pk_bf16_f32 v3, v3, s0
	v_lshl_add_u64 v[4:5], v[4:5], 1, s[8:9]
	global_store_short v[4:5], v3, off sc1
	v_add_u32_e32 v4, v190, v16
	s_waitcnt vmcnt(17)
	v_fmac_f32_e32 v17, v12, v102
	v_ashrrev_i32_e32 v5, 31, v4
	v_mul_f32_e32 v3, v32, v17
	v_cvt_pk_bf16_f32 v3, v3, s0
	v_lshl_add_u64 v[4:5], v[4:5], 1, s[8:9]
	global_store_short v[4:5], v3, off sc1
	v_add_u32_e32 v4, v191, v16
	s_waitcnt vmcnt(16)
	v_fmac_f32_e32 v2, v13, v102
	v_ashrrev_i32_e32 v5, 31, v4
	v_mul_f32_e32 v3, v32, v2
	v_cvt_pk_bf16_f32 v3, v3, s0
	v_lshl_add_u64 v[4:5], v[4:5], 1, s[8:9]
	global_store_short v[4:5], v3, off sc1
	v_add_u32_e32 v4, v192, v16
	v_ashrrev_i32_e32 v5, 31, v4
	v_lshl_add_u64 v[4:5], v[4:5], 1, s[8:9]
	v_xor_b32_e32 v13, 16, v164
	v_add_u32_e32 v10, v193, v16
	v_ashrrev_i32_e32 v11, 31, v10
	v_lshl_add_u64 v[10:11], v[10:11], 1, s[8:9]
	v_ashrrev_i32_e32 v71, 31, v70
	global_store_dword v[82:83], v26, off offset:384 sc1
	global_store_dword v[78:79], v25, off offset:384 sc1
	global_store_dword v[72:73], v24, off offset:384 sc1
	global_store_dword v[74:75], v23, off offset:384 sc1
	s_waitcnt vmcnt(15)
	v_fmac_f32_e32 v1, v14, v102
	v_mul_f32_e32 v3, v32, v1
	v_cvt_pk_bf16_f32 v3, v3, s0
	global_store_short v[4:5], v3, off sc1
	v_and_b32_e32 v4, 64, v164
	v_xor_b32_e32 v3, 1, v164
	v_add_u32_e32 v7, 64, v4
	v_cmp_lt_i32_e32 vcc, v3, v7
	v_xor_b32_e32 v4, 2, v164
	s_waitcnt vmcnt(14)
	v_fmac_f32_e32 v0, v15, v102
	v_cndmask_b32_e32 v3, v164, v3, vcc
	v_lshlrev_b32_e32 v3, 2, v3
	ds_bpermute_b32 v5, v3, v106
	v_cmp_lt_i32_e32 vcc, v4, v7
	v_mul_f32_e32 v12, v32, v0
	v_cvt_pk_bf16_f32 v12, v12, s0
	v_cndmask_b32_e32 v4, v164, v4, vcc
	v_lshlrev_b32_e32 v4, 2, v4
	s_waitcnt lgkmcnt(0)
	v_add_f32_e32 v6, v106, v5
	ds_bpermute_b32 v8, v4, v6
	v_xor_b32_e32 v5, 4, v164
	v_cmp_lt_i32_e32 vcc, v5, v7
	global_store_dword v[76:77], v22, off offset:384 sc1
	global_store_dword v[80:81], v21, off offset:384 sc1
	v_cndmask_b32_e32 v5, v164, v5, vcc
	v_lshlrev_b32_e32 v5, 2, v5
	s_waitcnt lgkmcnt(0)
	v_add_f32_e32 v8, v6, v8
	ds_bpermute_b32 v9, v5, v8
	v_xor_b32_e32 v6, 8, v164
	v_cmp_lt_i32_e32 vcc, v6, v7
	global_store_dword v[90:91], v19, off offset:384 sc1
	global_store_dword v[92:93], v18, off offset:384 sc1
	v_cndmask_b32_e32 v6, v164, v6, vcc
	v_lshlrev_b32_e32 v6, 2, v6
	s_waitcnt lgkmcnt(0)
	v_add_f32_e32 v8, v8, v9
	ds_bpermute_b32 v9, v6, v8
	v_cmp_lt_i32_e32 vcc, v13, v7
	global_store_dword v[94:95], v17, off offset:384 sc1
	global_store_dword v[96:97], v2, off offset:384 sc1
	v_cndmask_b32_e32 v7, v164, v13, vcc
	v_lshlrev_b32_e32 v7, 2, v7
	s_waitcnt lgkmcnt(0)
	v_add_f32_e32 v8, v8, v9
	ds_bpermute_b32 v9, v7, v8
	global_store_dword v[98:99], v1, off offset:384 sc1
	global_store_dword v[100:101], v0, off offset:384 sc1
	global_store_short v[10:11], v12, off sc1
	s_and_saveexec_b64 s[60:61], s[0:1]
	s_cbranch_execz .LBB0_1571
	s_waitcnt lgkmcnt(0)
	v_add_f32_e32 v10, v8, v9
	v_lshl_add_u64 v[8:9], v[70:71], 2, s[58:59]
	global_store_dword v[8:9], v10, off sc1
